# strategy 4: static s_setprio 1 for waves 4-7 in GEMM phases, all per-block priority flips deleted
# baseline (speedup 1.0000x reference)
.LBB0_231:
	s_add_u32 s26, s90, 0x88f0000
	s_addc_u32 s27, s91, 0
	s_add_u32 s20, s90, 0xb8f0000
	s_addc_u32 s21, s91, 0
	s_add_u32 s24, s90, 0x118f0000
	s_addc_u32 s25, s91, 0
	s_andn2_b64 vcc, exec, s[0:1]
	s_cbranch_vccnz .LBB0_379
	v_ashrrev_i32_e32 v1, 31, v8
	v_lshrrev_b32_e32 v1, 26, v1
	v_add_u32_e32 v1, v8, v1
	v_ashrrev_i32_e32 v9, 6, v1
	v_bfe_i32 v1, v8, 27, 1
	v_lshlrev_b32_e32 v0, 4, v8
	v_lshrrev_b32_e32 v1, 22, v1
	v_add_u32_e32 v1, v0, v1
	v_and_b32_e32 v1, 0xfffffc00, v1
	v_sub_u32_e32 v1, v0, v1
	v_lshrrev_b32_e32 v2, 4, v1
	v_bitop3_b32 v1, v2, v1, 32 bitop3:0x6c
	v_ashrrev_i32_e32 v3, 31, v1
	v_lshrrev_b32_e32 v3, 26, v3
	v_add_u32_e32 v3, v1, v3
	v_lshlrev_b32_e32 v2, 3, v9
	v_ashrrev_i32_e32 v10, 6, v3
	v_and_b32_e32 v3, 0xc0, v3
	v_and_b32_e32 v2, -16, v2
	v_sub_u32_e32 v1, v1, v3
	v_mov_b32_e32 v3, 1
	v_add_u32_e32 v2, v10, v2
	v_ashrrev_i16_sdwa v1, v3, sext(v1) dst_sel:DWORD dst_unused:UNUSED_PAD src0_sel:DWORD src1_sel:BYTE_0
	v_lshlrev_b32_e32 v4, 5, v9
	v_bfe_i32 v11, v1, 0, 16
	v_lshlrev_b32_e32 v1, 1, v2
	v_lshrrev_b32_e32 v5, 2, v2
	v_and_b32_e32 v6, 3, v10
	s_mov_b32 s1, 0x1fffe0
	v_and_b32_e32 v4, 32, v4
	v_and_b32_e32 v1, 24, v1
	v_and_b32_e32 v5, 4, v5
	v_and_or_b32 v6, v2, s1, v6
	v_or3_b32 v1, v6, v5, v1
	v_add_lshl_u32 v4, v4, v11, 1
	v_add_u32_e32 v0, 0x2000, v0
	v_lshl_add_u32 v130, v1, 11, v4
	v_ashrrev_i32_e32 v1, 31, v0
	v_lshrrev_b32_e32 v1, 22, v1
	v_add_u32_e32 v1, v0, v1
	v_ashrrev_i32_e32 v12, 10, v1
	v_mul_i32_i24_e32 v1, 0x400, v12
	v_sub_u32_e32 v0, v0, v1
	v_lshrrev_b32_e32 v1, 4, v0
	v_bitop3_b32 v0, v1, v0, 32 bitop3:0x6c
	v_lshl_add_u32 v128, v2, 11, v4
	v_ashrrev_i32_e32 v2, 31, v0
	v_lshrrev_b32_e32 v2, 26, v2
	v_add_u32_e32 v2, v0, v2
	v_lshlrev_b32_e32 v1, 3, v12
	v_ashrrev_i32_e32 v13, 6, v2
	v_and_b32_e32 v2, 0xc0, v2
	v_and_b32_e32 v1, -16, v1
	v_sub_u32_e32 v0, v0, v2
	v_add_u32_e32 v1, v13, v1
	v_ashrrev_i16_sdwa v0, v3, sext(v0) dst_sel:DWORD dst_unused:UNUSED_PAD src0_sel:DWORD src1_sel:BYTE_0
	v_and_b32_e32 v3, 3, v13
	v_and_or_b32 v3, v1, s1, v3
	s_ashr_i32 s1, s2, 6
	s_lshl_b32 s50, s1, 10
	v_lshlrev_b32_e32 v4, 5, v12
	v_bfe_i32 v14, v0, 0, 16
	v_lshlrev_b32_e32 v0, 1, v1
	v_lshrrev_b32_e32 v2, 2, v1
	s_add_i32 s51, s50, 0
	v_and_b32_e32 v4, 32, v4
	v_and_b32_e32 v0, 24, v0
	v_and_b32_e32 v2, 4, v2
	s_add_i32 m0, s51, 0x10000
	s_ashr_i32 s0, s2, 8
	v_or3_b32 v0, v3, v2, v0
	v_add_lshl_u32 v2, v4, v14, 1
	global_load_lds_dwordx4 v130, s[42:43]
	s_add_i32 m0, s51, 0x12000
	v_lshl_add_u32 v134, v0, 11, v2
	s_add_u32 s10, s42, 0x40000
	global_load_lds_dwordx4 v134, s[42:43]
	s_addc_u32 s11, s43, 0
	s_add_i32 m0, s51, 0x14000
	s_add_i32 s58, s51, 0x2000
	global_load_lds_dwordx4 v130, s[10:11]
	s_add_i32 m0, s51, 0x16000
	v_lshl_add_u32 v132, v1, 11, v2
	global_load_lds_dwordx4 v134, s[10:11]
	s_mov_b32 m0, s51
	s_add_u32 s10, s40, 0x40000
	global_load_lds_dwordx4 v128, s[40:41]
	s_mov_b32 m0, s58
	s_addc_u32 s11, s41, 0
	s_add_i32 s59, s51, 0x4000
	global_load_lds_dwordx4 v132, s[40:41]
	s_mov_b32 m0, s59
	s_add_i32 s60, s51, 0x6000
	global_load_lds_dwordx4 v128, s[10:11]
	s_mov_b32 m0, s60
	v_mov_b32_e32 v137, 0
	global_load_lds_dwordx4 v132, s[10:11]
	v_mov_b32_e32 v131, v137
	v_mov_b32_e32 v135, v137
	v_mov_b32_e32 v129, v137
	v_mov_b32_e32 v133, v137
	s_cmp_eq_u32 s0, 1
	s_mov_b32 s61, 0
	s_mov_b32 s62, 0x10000
	v_lshl_add_u64 v[6:7], s[42:43], 0, v[130:131]
	v_lshl_add_u64 v[4:5], s[42:43], 0, v[134:135]
	v_lshl_add_u64 v[0:1], s[40:41], 0, v[128:129]
	s_cselect_b64 s[10:11], -1, 0
	s_cmp_lg_u32 s0, 1
	v_lshl_add_u64 v[2:3], s[40:41], 0, v[132:133]
	s_cbranch_scc1 .LBB0_234
	s_setprio 1
	s_barrier

.LBB0_244:
	ds_read_b128 v[146:149], v161
	ds_read_b128 v[150:153], v161 offset:1024
	ds_read_b128 v[154:157], v161 offset:2048
	ds_read_b128 v[164:167], v161 offset:3072
	ds_read_b128 v[168:171], v162
	ds_read_b128 v[172:175], v162 offset:1024
	ds_read_b128 v[176:179], v162 offset:2048
	ds_read_b128 v[180:183], v162 offset:3072
	s_add_u32 s7, s40, 0xfffc0080
	s_addc_u32 s9, s41, -1
	s_cmp_eq_u32 s5, 12
	s_cselect_b32 s45, s29, s9
	s_cselect_b32 s44, s28, s7
	s_cselect_b32 s43, s39, s3
	s_cselect_b32 s42, s38, s2
	v_lshl_add_u64 v[218:219], s[40:41], 0, v[138:139]
	s_add_i32 m0, s51, 0xc000
	ds_read_b128 v[184:187], v163
	ds_read_b128 v[188:191], v163 offset:1024
	ds_read_b128 v[194:197], v163 offset:2048
	ds_read_b128 v[198:201], v163 offset:3072
	ds_read_b128 v[202:205], v163 offset:4096
	ds_read_b128 v[206:209], v163 offset:5120
	ds_read_b128 v[210:213], v163 offset:6144
	ds_read_b128 v[214:217], v163 offset:7168
	global_load_lds_dwordx4 v[218:219], off
	v_lshl_add_u64 v[218:219], s[40:41], 0, v[140:141]
	s_add_i32 m0, s51, 0xe000
	s_nop 0
	global_load_lds_dwordx4 v[218:219], off
	s_waitcnt vmcnt(8)
	s_waitcnt lgkmcnt(0)
	s_barrier
	s_waitcnt lgkmcnt(0)
	v_mfma_f32_16x16x32_bf16 v[124:127], v[146:149], v[184:187], v[124:127]
	v_mfma_f32_16x16x32_bf16 v[120:123], v[154:157], v[184:187], v[120:123]
	v_mfma_f32_16x16x32_bf16 v[108:111], v[146:149], v[194:197], v[108:111]
	v_mfma_f32_16x16x32_bf16 v[104:107], v[154:157], v[194:197], v[104:107]
	v_mfma_f32_16x16x32_bf16 v[92:95], v[146:149], v[202:205], v[92:95]
	v_mfma_f32_16x16x32_bf16 v[88:91], v[154:157], v[202:205], v[88:91]
	v_mfma_f32_16x16x32_bf16 v[76:79], v[146:149], v[210:213], v[76:79]
	v_mfma_f32_16x16x32_bf16 v[72:75], v[154:157], v[210:213], v[72:75]
	v_mfma_f32_16x16x32_bf16 v[124:127], v[150:153], v[188:191], v[124:127]
	v_mfma_f32_16x16x32_bf16 v[120:123], v[164:167], v[188:191], v[120:123]
	v_mfma_f32_16x16x32_bf16 v[108:111], v[150:153], v[198:201], v[108:111]
	v_mfma_f32_16x16x32_bf16 v[104:107], v[164:167], v[198:201], v[104:107]
	v_mfma_f32_16x16x32_bf16 v[92:95], v[150:153], v[206:209], v[92:95]
	v_mfma_f32_16x16x32_bf16 v[88:91], v[164:167], v[206:209], v[88:91]
	v_mfma_f32_16x16x32_bf16 v[76:79], v[150:153], v[214:217], v[76:79]
	v_mfma_f32_16x16x32_bf16 v[72:75], v[164:167], v[214:217], v[72:75]
	v_mfma_f32_16x16x32_bf16 v[116:119], v[168:171], v[184:187], v[116:119]
	v_mfma_f32_16x16x32_bf16 v[112:115], v[176:179], v[184:187], v[112:115]
	v_mfma_f32_16x16x32_bf16 v[100:103], v[168:171], v[194:197], v[100:103]
	v_mfma_f32_16x16x32_bf16 v[96:99], v[176:179], v[194:197], v[96:99]
	v_mfma_f32_16x16x32_bf16 v[84:87], v[168:171], v[202:205], v[84:87]
	v_mfma_f32_16x16x32_bf16 v[80:83], v[176:179], v[202:205], v[80:83]
	v_mfma_f32_16x16x32_bf16 v[68:71], v[168:171], v[210:213], v[68:71]
	v_mfma_f32_16x16x32_bf16 v[64:67], v[176:179], v[210:213], v[64:67]
	v_mfma_f32_16x16x32_bf16 v[116:119], v[172:175], v[188:191], v[116:119]
	v_mfma_f32_16x16x32_bf16 v[112:115], v[180:183], v[188:191], v[112:115]
	v_mfma_f32_16x16x32_bf16 v[100:103], v[172:175], v[198:201], v[100:103]
	v_mfma_f32_16x16x32_bf16 v[96:99], v[180:183], v[198:201], v[96:99]
	v_mfma_f32_16x16x32_bf16 v[84:87], v[172:175], v[206:209], v[84:87]
	v_mfma_f32_16x16x32_bf16 v[80:83], v[180:183], v[206:209], v[80:83]
	v_mfma_f32_16x16x32_bf16 v[68:71], v[172:175], v[214:217], v[68:71]
	v_mfma_f32_16x16x32_bf16 v[64:67], v[180:183], v[214:217], v[64:67]
	s_barrier
	s_add_i32 s7, s68, s50
	v_lshl_add_u64 v[218:219], s[42:43], 0, v[130:131]
	s_mov_b32 m0, s7
	ds_read_b128 v[184:187], v163 offset:16384
	ds_read_b128 v[188:191], v163 offset:17408
	ds_read_b128 v[194:197], v163 offset:18432
	ds_read_b128 v[198:201], v163 offset:19456
	ds_read_b128 v[202:205], v163 offset:20480
	ds_read_b128 v[206:209], v163 offset:21504
	ds_read_b128 v[210:213], v163 offset:22528
	ds_read_b128 v[214:217], v163 offset:23552
	global_load_lds_dwordx4 v[218:219], off
	s_add_i32 m0, s7, 0x2000
	s_add_u32 s34, s42, 0x40000
	v_lshl_add_u64 v[220:221], s[42:43], 0, v[134:135]
	s_addc_u32 s35, s43, 0
	s_add_i32 s7, s69, s50
	global_load_lds_dwordx4 v[220:221], off
	v_lshl_add_u64 v[222:223], s[34:35], 0, v[130:131]
	s_mov_b32 m0, s7
	v_lshl_add_u64 v[224:225], s[44:45], 0, v[132:133]
	global_load_lds_dwordx4 v[222:223], off
	v_lshl_add_u64 v[222:223], s[34:35], 0, v[134:135]
	s_add_i32 m0, s7, 0x2000
	s_nop 0
	global_load_lds_dwordx4 v[222:223], off
	v_lshl_add_u64 v[222:223], s[44:45], 0, v[128:129]
	s_mov_b32 m0, s51
	s_nop 0
	global_load_lds_dwordx4 v[222:223], off
	s_mov_b32 m0, s58
	s_nop 0
	global_load_lds_dwordx4 v[224:225], off
	s_waitcnt vmcnt(8)
	s_waitcnt lgkmcnt(0)
	s_barrier
	s_waitcnt lgkmcnt(0)
	v_mfma_f32_16x16x32_bf16 v[60:63], v[146:149], v[184:187], v[60:63]
	v_mfma_f32_16x16x32_bf16 v[56:59], v[154:157], v[184:187], v[56:59]
	v_mfma_f32_16x16x32_bf16 v[44:47], v[146:149], v[194:197], v[44:47]
	v_mfma_f32_16x16x32_bf16 v[40:43], v[154:157], v[194:197], v[40:43]
	v_mfma_f32_16x16x32_bf16 v[28:31], v[146:149], v[202:205], v[28:31]
	v_mfma_f32_16x16x32_bf16 v[24:27], v[154:157], v[202:205], v[24:27]
	v_mfma_f32_16x16x32_bf16 v[12:15], v[146:149], v[210:213], v[12:15]
	v_mfma_f32_16x16x32_bf16 v[8:11], v[154:157], v[210:213], v[8:11]
	v_mfma_f32_16x16x32_bf16 v[60:63], v[150:153], v[188:191], v[60:63]
	v_mfma_f32_16x16x32_bf16 v[56:59], v[164:167], v[188:191], v[56:59]
	v_mfma_f32_16x16x32_bf16 v[44:47], v[150:153], v[198:201], v[44:47]
	v_mfma_f32_16x16x32_bf16 v[40:43], v[164:167], v[198:201], v[40:43]
	v_mfma_f32_16x16x32_bf16 v[28:31], v[150:153], v[206:209], v[28:31]
	v_mfma_f32_16x16x32_bf16 v[24:27], v[164:167], v[206:209], v[24:27]
	v_mfma_f32_16x16x32_bf16 v[12:15], v[150:153], v[214:217], v[12:15]
	v_mfma_f32_16x16x32_bf16 v[8:11], v[164:167], v[214:217], v[8:11]
	v_mfma_f32_16x16x32_bf16 v[52:55], v[168:171], v[184:187], v[52:55]
	v_mfma_f32_16x16x32_bf16 v[48:51], v[176:179], v[184:187], v[48:51]
	v_mfma_f32_16x16x32_bf16 v[36:39], v[168:171], v[194:197], v[36:39]
	v_mfma_f32_16x16x32_bf16 v[32:35], v[176:179], v[194:197], v[32:35]
	v_mfma_f32_16x16x32_bf16 v[20:23], v[168:171], v[202:205], v[20:23]
	v_mfma_f32_16x16x32_bf16 v[16:19], v[176:179], v[202:205], v[16:19]
	v_mfma_f32_16x16x32_bf16 v[4:7], v[168:171], v[210:213], v[4:7]
	v_mfma_f32_16x16x32_bf16 v[0:3], v[176:179], v[210:213], v[0:3]
	v_mfma_f32_16x16x32_bf16 v[52:55], v[172:175], v[188:191], v[52:55]
	v_mfma_f32_16x16x32_bf16 v[48:51], v[180:183], v[188:191], v[48:51]
	v_mfma_f32_16x16x32_bf16 v[36:39], v[172:175], v[198:201], v[36:39]
	v_mfma_f32_16x16x32_bf16 v[32:35], v[180:183], v[198:201], v[32:35]
	v_mfma_f32_16x16x32_bf16 v[20:23], v[172:175], v[206:209], v[20:23]
	v_mfma_f32_16x16x32_bf16 v[16:19], v[180:183], v[206:209], v[16:19]
	v_mfma_f32_16x16x32_bf16 v[4:7], v[172:175], v[214:217], v[4:7]
	v_mfma_f32_16x16x32_bf16 v[0:3], v[180:183], v[214:217], v[0:3]
	s_barrier
	s_add_i32 s7, 0, 0x18000
	v_add_u32_e32 v136, s7, v159
	s_add_i32 s9, 0, 0x1c000
	ds_read_b128 v[146:149], v136
	ds_read_b128 v[150:153], v136 offset:1024
	ds_read_b128 v[154:157], v136 offset:2048
	ds_read_b128 v[164:167], v136 offset:3072
	v_add_u32_e32 v136, s9, v159
	ds_read_b128 v[168:171], v136
	ds_read_b128 v[172:175], v136 offset:1024
	ds_read_b128 v[176:179], v136 offset:2048
	ds_read_b128 v[180:183], v136 offset:3072
	s_add_u32 s34, s44, 0x40000
	s_addc_u32 s35, s45, 0
	s_mov_b32 m0, s59
	v_lshl_add_u64 v[228:229], s[34:35], 0, v[128:129]
	ds_read_b128 v[184:187], v163 offset:32768
	ds_read_b128 v[188:191], v163 offset:33792
	ds_read_b128 v[194:197], v163 offset:34816
	ds_read_b128 v[198:201], v163 offset:35840
	ds_read_b128 v[202:205], v163 offset:36864
	ds_read_b128 v[206:209], v163 offset:37888
	ds_read_b128 v[210:213], v163 offset:38912
	ds_read_b128 v[214:217], v163 offset:39936
	global_load_lds_dwordx4 v[228:229], off
	v_lshl_add_u64 v[228:229], s[34:35], 0, v[132:133]
	s_mov_b32 m0, s60
	s_nop 0
	global_load_lds_dwordx4 v[228:229], off
	s_waitcnt vmcnt(8)
	s_waitcnt lgkmcnt(0)
	s_barrier
	s_waitcnt lgkmcnt(0)
	v_mfma_f32_16x16x32_bf16 v[124:127], v[146:149], v[184:187], v[124:127]
	v_mfma_f32_16x16x32_bf16 v[120:123], v[154:157], v[184:187], v[120:123]
	v_mfma_f32_16x16x32_bf16 v[108:111], v[146:149], v[194:197], v[108:111]
	v_mfma_f32_16x16x32_bf16 v[104:107], v[154:157], v[194:197], v[104:107]
	v_mfma_f32_16x16x32_bf16 v[92:95], v[146:149], v[202:205], v[92:95]
	v_mfma_f32_16x16x32_bf16 v[88:91], v[154:157], v[202:205], v[88:91]
	v_mfma_f32_16x16x32_bf16 v[76:79], v[146:149], v[210:213], v[76:79]
	v_mfma_f32_16x16x32_bf16 v[72:75], v[154:157], v[210:213], v[72:75]
	v_mfma_f32_16x16x32_bf16 v[124:127], v[150:153], v[188:191], v[124:127]
	v_mfma_f32_16x16x32_bf16 v[120:123], v[164:167], v[188:191], v[120:123]
	v_mfma_f32_16x16x32_bf16 v[108:111], v[150:153], v[198:201], v[108:111]
	v_mfma_f32_16x16x32_bf16 v[104:107], v[164:167], v[198:201], v[104:107]
	v_mfma_f32_16x16x32_bf16 v[92:95], v[150:153], v[206:209], v[92:95]
	v_mfma_f32_16x16x32_bf16 v[88:91], v[164:167], v[206:209], v[88:91]
	v_mfma_f32_16x16x32_bf16 v[76:79], v[150:153], v[214:217], v[76:79]
	v_mfma_f32_16x16x32_bf16 v[72:75], v[164:167], v[214:217], v[72:75]
	v_mfma_f32_16x16x32_bf16 v[116:119], v[168:171], v[184:187], v[116:119]
	v_mfma_f32_16x16x32_bf16 v[112:115], v[176:179], v[184:187], v[112:115]
	v_mfma_f32_16x16x32_bf16 v[100:103], v[168:171], v[194:197], v[100:103]
	v_mfma_f32_16x16x32_bf16 v[96:99], v[176:179], v[194:197], v[96:99]
	v_mfma_f32_16x16x32_bf16 v[84:87], v[168:171], v[202:205], v[84:87]
	v_mfma_f32_16x16x32_bf16 v[80:83], v[176:179], v[202:205], v[80:83]
	v_mfma_f32_16x16x32_bf16 v[68:71], v[168:171], v[210:213], v[68:71]
	v_mfma_f32_16x16x32_bf16 v[64:67], v[176:179], v[210:213], v[64:67]
	v_mfma_f32_16x16x32_bf16 v[116:119], v[172:175], v[188:191], v[116:119]
	v_mfma_f32_16x16x32_bf16 v[112:115], v[180:183], v[188:191], v[112:115]
	v_mfma_f32_16x16x32_bf16 v[100:103], v[172:175], v[198:201], v[100:103]
	v_mfma_f32_16x16x32_bf16 v[96:99], v[180:183], v[198:201], v[96:99]
	v_mfma_f32_16x16x32_bf16 v[84:87], v[172:175], v[206:209], v[84:87]
	v_mfma_f32_16x16x32_bf16 v[80:83], v[180:183], v[206:209], v[80:83]
	v_mfma_f32_16x16x32_bf16 v[68:71], v[172:175], v[214:217], v[68:71]
	v_mfma_f32_16x16x32_bf16 v[64:67], v[180:183], v[214:217], v[64:67]
	s_barrier
	s_add_i32 s7, s7, s50
	v_lshl_add_u64 v[218:219], v[218:219], 0, s[12:13]
	s_mov_b32 m0, s7
	ds_read_b128 v[184:187], v163 offset:49152
	ds_read_b128 v[188:191], v163 offset:50176
	ds_read_b128 v[194:197], v163 offset:51200
	ds_read_b128 v[198:201], v163 offset:52224
	ds_read_b128 v[202:205], v163 offset:53248
	ds_read_b128 v[206:209], v163 offset:54272
	ds_read_b128 v[210:213], v163 offset:55296
	ds_read_b128 v[214:217], v163 offset:56320
	global_load_lds_dwordx4 v[218:219], off
	s_add_i32 m0, s7, 0x2000
	s_add_u32 s34, s42, 0x40080
	v_lshl_add_u64 v[218:219], v[220:221], 0, s[12:13]
	s_addc_u32 s35, s43, 0
	s_add_i32 s7, s9, s50
	global_load_lds_dwordx4 v[218:219], off
	v_lshl_add_u64 v[218:219], s[34:35], 0, v[130:131]
	s_mov_b32 m0, s7
	s_nop 0
	global_load_lds_dwordx4 v[218:219], off
	v_lshl_add_u64 v[218:219], s[34:35], 0, v[134:135]
	s_add_i32 m0, s7, 0x2000
	s_nop 0
	global_load_lds_dwordx4 v[218:219], off
	v_lshl_add_u64 v[218:219], v[222:223], 0, s[12:13]
	s_mov_b32 m0, s63
	s_nop 0
	global_load_lds_dwordx4 v[218:219], off
	v_lshl_add_u64 v[218:219], v[224:225], 0, s[12:13]
	s_mov_b32 m0, s64
	s_nop 0
	global_load_lds_dwordx4 v[218:219], off
	s_waitcnt vmcnt(8)
	s_waitcnt lgkmcnt(0)
	s_barrier
	s_waitcnt lgkmcnt(0)
	v_mfma_f32_16x16x32_bf16 v[60:63], v[146:149], v[184:187], v[60:63]
	v_mfma_f32_16x16x32_bf16 v[56:59], v[154:157], v[184:187], v[56:59]
	v_mfma_f32_16x16x32_bf16 v[44:47], v[146:149], v[194:197], v[44:47]
	v_mfma_f32_16x16x32_bf16 v[40:43], v[154:157], v[194:197], v[40:43]
	v_mfma_f32_16x16x32_bf16 v[28:31], v[146:149], v[202:205], v[28:31]
	v_mfma_f32_16x16x32_bf16 v[24:27], v[154:157], v[202:205], v[24:27]
	v_mfma_f32_16x16x32_bf16 v[12:15], v[146:149], v[210:213], v[12:15]
	v_mfma_f32_16x16x32_bf16 v[8:11], v[154:157], v[210:213], v[8:11]
	v_mfma_f32_16x16x32_bf16 v[60:63], v[150:153], v[188:191], v[60:63]
	v_mfma_f32_16x16x32_bf16 v[56:59], v[164:167], v[188:191], v[56:59]
	v_mfma_f32_16x16x32_bf16 v[44:47], v[150:153], v[198:201], v[44:47]
	v_mfma_f32_16x16x32_bf16 v[40:43], v[164:167], v[198:201], v[40:43]
	v_mfma_f32_16x16x32_bf16 v[28:31], v[150:153], v[206:209], v[28:31]
	v_mfma_f32_16x16x32_bf16 v[24:27], v[164:167], v[206:209], v[24:27]
	v_mfma_f32_16x16x32_bf16 v[12:15], v[150:153], v[214:217], v[12:15]
	v_mfma_f32_16x16x32_bf16 v[8:11], v[164:167], v[214:217], v[8:11]
	v_mfma_f32_16x16x32_bf16 v[52:55], v[168:171], v[184:187], v[52:55]
	v_mfma_f32_16x16x32_bf16 v[48:51], v[176:179], v[184:187], v[48:51]
	v_mfma_f32_16x16x32_bf16 v[36:39], v[168:171], v[194:197], v[36:39]
	v_mfma_f32_16x16x32_bf16 v[32:35], v[176:179], v[194:197], v[32:35]
	v_mfma_f32_16x16x32_bf16 v[20:23], v[168:171], v[202:205], v[20:23]
	v_mfma_f32_16x16x32_bf16 v[16:19], v[176:179], v[202:205], v[16:19]
	v_mfma_f32_16x16x32_bf16 v[4:7], v[168:171], v[210:213], v[4:7]
	v_mfma_f32_16x16x32_bf16 v[0:3], v[176:179], v[210:213], v[0:3]
	v_mfma_f32_16x16x32_bf16 v[52:55], v[172:175], v[188:191], v[52:55]
	v_mfma_f32_16x16x32_bf16 v[48:51], v[180:183], v[188:191], v[48:51]
	v_mfma_f32_16x16x32_bf16 v[36:39], v[172:175], v[198:201], v[36:39]
	v_mfma_f32_16x16x32_bf16 v[32:35], v[180:183], v[198:201], v[32:35]
	v_mfma_f32_16x16x32_bf16 v[20:23], v[172:175], v[206:209], v[20:23]
	v_mfma_f32_16x16x32_bf16 v[16:19], v[180:183], v[206:209], v[16:19]
	v_mfma_f32_16x16x32_bf16 v[4:7], v[172:175], v[214:217], v[4:7]
	v_mfma_f32_16x16x32_bf16 v[0:3], v[180:183], v[214:217], v[0:3]
	s_barrier
	s_add_i32 s5, s5, 2
	s_add_u32 s40, s40, 0x100
	s_addc_u32 s41, s41, 0
	s_add_u32 s2, s2, 0x100
	s_addc_u32 s3, s3, 0
	s_cmp_gt_u32 s5, 13
	s_cbranch_scc0 .LBB0_244
	s_and_b64 vcc, exec, s[14:15]
	s_cbranch_vccz .LBB0_247
	s_barrier

.LBB0_379:
	s_setprio 0
	s_waitcnt vmcnt(0)
	s_waitcnt vmcnt(0)
	s_barrier
	s_mov_b64 s[0:1], exec
	v_readlane_b32 s2, v248, 3
	v_readlane_b32 s3, v248, 4
	s_and_b64 s[2:3], s[0:1], s[2:3]
	s_mov_b64 exec, s[2:3]
	s_cbranch_execz .LBB0_431
	v_readlane_b32 s98, v248, 1
	v_readlane_b32 s99, v248, 2
	v_mov_b32_e32 v0, 0x20ff0
	ds_read2_b32 v[2:3], v0 offset1:1
	v_mov_b32_e32 v1, 1
	v_mov_b32_e32 v4, s97
	v_lshlrev_b32_e32 v4, 8, v4
	s_add_u32 s98, s98, 0x1000
	s_addc_u32 s99, s99, 0
	s_nop 2
	global_atomic_add v5, v4, v1, s[98:99] offset:1024 sc0
	s_waitcnt vmcnt(0) lgkmcnt(0)
	v_mul_u32_u24_e32 v2, 3, v2
	v_mul_u32_u24_e32 v3, 3, v3
	v_add_u32_e32 v5, 1, v5
	v_cmp_ne_u32_e32 vcc, v5, v2
	v_mov_b32_e32 v6, 0x2400
	s_cbranch_vccnz .Lxb2_poll
	buffer_wbl2 sc1
	s_waitcnt vmcnt(0)
	global_atomic_add v6, v1, s[98:99]

.Lgrp_p3_noremap:
	s_add_u32 s22, s90, 0x198f0000
	s_addc_u32 s23, s91, 0
	v_mov_b32_e32 v9, v193
	s_waitcnt lgkmcnt(0)
	s_barrier
	s_cmpk_gt_i32 s6, 0x7f
	v_readfirstlane_b32 s10, v9
	s_cbranch_scc1 .LBB0_447
	v_lshlrev_b32_e32 v0, 4, v9
	v_add_u32_e32 v1, 0x2000, v0
	v_ashrrev_i32_e32 v2, 31, v1
	v_lshrrev_b32_e32 v2, 22, v2
	v_add_u32_e32 v2, v1, v2
	v_ashrrev_i32_e32 v8, 10, v2
	v_mul_i32_i24_e32 v2, 0x400, v8
	v_sub_u32_e32 v1, v1, v2
	v_lshrrev_b32_e32 v2, 4, v1
	v_bitop3_b32 v1, v2, v1, 32 bitop3:0x6c
	v_ashrrev_i32_e32 v2, 31, v1
	v_lshrrev_b32_e32 v2, 26, v2
	v_add_u32_e32 v2, v1, v2
	v_lshlrev_b32_e32 v3, 3, v8
	v_ashrrev_i32_e32 v10, 6, v2
	v_and_b32_e32 v3, -16, v3
	v_add_u32_e32 v3, v10, v3
	v_and_b32_e32 v4, 3, v10
	s_mov_b32 s0, 0x3fffe0
	v_lshrrev_b32_e32 v5, 2, v3
	v_lshlrev_b32_e32 v6, 1, v3
	v_and_b32_e32 v2, 0xc0, v2
	v_and_or_b32 v4, v3, s0, v4
	v_and_b32_e32 v5, 4, v5
	v_and_b32_e32 v6, 24, v6
	v_sub_u32_e32 v1, v1, v2
	v_mov_b32_e32 v2, 1
	v_or3_b32 v4, v4, v5, v6
	v_lshlrev_b32_e32 v5, 5, v8
	v_ashrrev_i16_sdwa v1, v2, sext(v1) dst_sel:DWORD dst_unused:UNUSED_PAD src0_sel:DWORD src1_sel:BYTE_0
	v_and_b32_e32 v11, 32, v5
	v_bfe_i32 v12, v1, 0, 16
	s_movk_i32 s13, 0x300
	v_add_u32_e32 v1, v11, v12
	v_mul_lo_u32 v3, v3, s13
	v_lshlrev_b32_e32 v5, 1, v1
	v_add_lshl_u32 v130, v1, v3, 1
	v_bfe_i32 v1, v9, 27, 1
	v_lshrrev_b32_e32 v1, 22, v1
	v_add_u32_e32 v1, v0, v1
	v_and_b32_e32 v1, 0xfffffc00, v1
	v_sub_u32_e32 v0, v0, v1
	v_lshrrev_b32_e32 v1, 4, v0
	v_ashrrev_i32_e32 v3, 31, v9
	v_bitop3_b32 v0, v1, v0, 32 bitop3:0x6c
	v_lshrrev_b32_e32 v3, 26, v3
	v_ashrrev_i32_e32 v1, 31, v0
	v_add_u32_e32 v3, v9, v3
	v_lshrrev_b32_e32 v1, 26, v1
	v_ashrrev_i32_e32 v14, 6, v3
	v_add_u32_e32 v1, v0, v1
	v_lshlrev_b32_e32 v3, 3, v14
	v_ashrrev_i32_e32 v13, 6, v1
	v_and_b32_e32 v3, -16, v3
	s_add_u32 s2, s90, 0x3760000
	v_lshl_add_u32 v128, v4, 10, v5
	v_add_u32_e32 v3, v13, v3
	v_and_b32_e32 v4, 3, v13
	s_addc_u32 s3, s91, 0
	v_and_or_b32 v4, v3, s0, v4
	s_ashr_i32 s0, s6, 31
	s_lshr_b32 s0, s0, 30
	s_add_i32 s0, s6, s0
	s_ashr_i32 s8, s0, 2
	s_lshl_b32 s0, s6, 8
	s_and_b32 s51, s0, 0x300
	s_ashr_i32 s9, s8, 31
	s_lshl_b64 s[0:1], s[8:9], 11
	s_lshl_b32 s5, s51, 1
	s_or_b32 s0, s0, s5
	s_ashr_i32 s4, s10, 6
	v_lshrrev_b32_e32 v5, 2, v3
	v_lshlrev_b32_e32 v6, 1, v3
	v_and_b32_e32 v1, 0xc0, v1
	s_mulk_i32 s1, 0x300
	s_mul_hi_u32 s5, s0, 0x300
	s_ashr_i32 s11, s10, 8
	s_lshl_b32 s12, s4, 10
	v_and_b32_e32 v5, 4, v5
	v_and_b32_e32 v6, 24, v6
	v_sub_u32_e32 v0, v0, v1
	s_add_i32 s5, s5, s1
	s_mulk_i32 s0, 0x300
	v_or3_b32 v4, v4, v5, v6
	v_lshlrev_b32_e32 v5, 5, v14
	v_ashrrev_i16_sdwa v0, v2, sext(v0) dst_sel:DWORD dst_unused:UNUSED_PAD src0_sel:DWORD src1_sel:BYTE_0
	s_add_u32 s38, s26, s0
	v_and_b32_e32 v15, 32, v5
	v_bfe_i32 v16, v0, 0, 16
	s_addc_u32 s39, s27, s5
	s_lshl_b64 s[0:1], s[8:9], 18
	v_add_u32_e32 v0, v15, v16
	s_add_u32 s40, s2, s0
	v_lshlrev_b32_e32 v1, 1, v0
	s_addc_u32 s41, s3, s1
	s_add_i32 s7, s12, 0
	v_lshl_add_u32 v132, v4, 10, v1
	s_add_i32 m0, s7, 0x10000
	v_mul_lo_u32 v1, v3, s13
	global_load_lds_dwordx4 v132, s[40:41]
	s_add_i32 m0, s7, 0x12000
	s_add_u32 s0, s40, 0x20000
	global_load_lds_dwordx4 v128, s[40:41]
	s_addc_u32 s1, s41, 0
	s_add_i32 m0, s7, 0x14000
	s_add_i32 s33, s7, 0x2000
	global_load_lds_dwordx4 v132, s[0:1]
	s_add_i32 m0, s7, 0x16000
	v_add_lshl_u32 v134, v0, v1, 1
	global_load_lds_dwordx4 v128, s[0:1]
	s_mov_b32 m0, s7
	s_add_u32 s0, s38, 0x30000
	global_load_lds_dwordx4 v134, s[38:39]
	s_mov_b32 m0, s33
	s_addc_u32 s1, s39, 0
	s_add_i32 s34, s7, 0x4000
	global_load_lds_dwordx4 v130, s[38:39]
	s_mov_b32 m0, s34
	s_add_i32 s35, s7, 0x6000
	global_load_lds_dwordx4 v134, s[0:1]
	s_mov_b32 m0, s35
	v_mov_b32_e32 v137, 0
	global_load_lds_dwordx4 v130, s[0:1]
	v_mov_b32_e32 v133, v137
	v_mov_b32_e32 v129, v137
	v_mov_b32_e32 v135, v137
	v_mov_b32_e32 v131, v137
	s_cmp_eq_u32 s11, 1
	s_mov_b32 s48, 0
	v_lshl_add_u64 v[6:7], s[40:41], 0, v[132:133]
	v_lshl_add_u64 v[4:5], s[40:41], 0, v[128:129]
	v_lshl_add_u64 v[0:1], s[38:39], 0, v[134:135]
	s_cselect_b64 s[0:1], -1, 0
	s_cmp_lg_u32 s11, 1
	v_lshl_add_u64 v[2:3], s[38:39], 0, v[130:131]
	s_cbranch_scc1 .LBB0_434
	s_setprio 1
	s_barrier

.LBB0_440:
	ds_read_b128 v[148:151], v143
	ds_read_b128 v[152:155], v143 offset:1024
	ds_read_b128 v[156:159], v143 offset:2048
	ds_read_b128 v[160:163], v143 offset:3072
	ds_read_b128 v[164:167], v144
	ds_read_b128 v[168:171], v144 offset:1024
	ds_read_b128 v[172:175], v144 offset:2048
	ds_read_b128 v[176:179], v144 offset:3072
	s_add_u32 s40, s38, 0x100
	s_addc_u32 s41, s39, 0
	s_cmp_eq_u32 s68, 4
	s_cselect_b32 s45, s15, s41
	s_cselect_b32 s44, s14, s40
	s_cselect_b32 s43, s17, s13
	s_cselect_b32 s42, s16, s9
	s_mov_b32 m0, s58
	v_lshl_add_u64 v[214:215], s[38:39], 0, v[138:139]
	ds_read_b128 v[180:183], v145
	ds_read_b128 v[184:187], v145 offset:1024
	ds_read_b128 v[188:191], v145 offset:2048
	ds_read_b128 v[194:197], v145 offset:3072
	ds_read_b128 v[198:201], v145 offset:4096
	ds_read_b128 v[202:205], v145 offset:5120
	ds_read_b128 v[206:209], v145 offset:6144
	ds_read_b128 v[210:213], v145 offset:7168
	global_load_lds_dwordx4 v[214:215], off
	v_lshl_add_u64 v[214:215], s[38:39], 0, v[140:141]
	s_mov_b32 m0, s59
	s_nop 0
	global_load_lds_dwordx4 v[214:215], off
	s_waitcnt vmcnt(8)
	s_waitcnt lgkmcnt(0)
	s_barrier
	s_waitcnt lgkmcnt(0)
	v_mfma_f32_16x16x32_bf16 v[124:127], v[148:151], v[180:183], v[124:127]
	v_mfma_f32_16x16x32_bf16 v[120:123], v[156:159], v[180:183], v[120:123]
	v_mfma_f32_16x16x32_bf16 v[116:119], v[148:151], v[188:191], v[116:119]
	v_mfma_f32_16x16x32_bf16 v[112:115], v[156:159], v[188:191], v[112:115]
	v_mfma_f32_16x16x32_bf16 v[104:107], v[148:151], v[198:201], v[104:107]
	v_mfma_f32_16x16x32_bf16 v[96:99], v[156:159], v[198:201], v[96:99]
	v_mfma_f32_16x16x32_bf16 v[88:91], v[148:151], v[206:209], v[88:91]
	v_mfma_f32_16x16x32_bf16 v[80:83], v[156:159], v[206:209], v[80:83]
	v_mfma_f32_16x16x32_bf16 v[124:127], v[152:155], v[184:187], v[124:127]
	v_mfma_f32_16x16x32_bf16 v[120:123], v[160:163], v[184:187], v[120:123]
	v_mfma_f32_16x16x32_bf16 v[116:119], v[152:155], v[194:197], v[116:119]
	v_mfma_f32_16x16x32_bf16 v[112:115], v[160:163], v[194:197], v[112:115]
	v_mfma_f32_16x16x32_bf16 v[104:107], v[152:155], v[202:205], v[104:107]
	v_mfma_f32_16x16x32_bf16 v[96:99], v[160:163], v[202:205], v[96:99]
	v_mfma_f32_16x16x32_bf16 v[88:91], v[152:155], v[210:213], v[88:91]
	v_mfma_f32_16x16x32_bf16 v[80:83], v[160:163], v[210:213], v[80:83]
	v_mfma_f32_16x16x32_bf16 v[108:111], v[164:167], v[180:183], v[108:111]
	v_mfma_f32_16x16x32_bf16 v[100:103], v[172:175], v[180:183], v[100:103]
	v_mfma_f32_16x16x32_bf16 v[92:95], v[164:167], v[188:191], v[92:95]
	v_mfma_f32_16x16x32_bf16 v[84:87], v[172:175], v[188:191], v[84:87]
	v_mfma_f32_16x16x32_bf16 v[76:79], v[164:167], v[198:201], v[76:79]
	v_mfma_f32_16x16x32_bf16 v[72:75], v[172:175], v[198:201], v[72:75]
	v_mfma_f32_16x16x32_bf16 v[68:71], v[164:167], v[206:209], v[68:71]
	v_mfma_f32_16x16x32_bf16 v[64:67], v[172:175], v[206:209], v[64:67]
	v_mfma_f32_16x16x32_bf16 v[108:111], v[168:171], v[184:187], v[108:111]
	v_mfma_f32_16x16x32_bf16 v[100:103], v[176:179], v[184:187], v[100:103]
	v_mfma_f32_16x16x32_bf16 v[92:95], v[168:171], v[194:197], v[92:95]
	v_mfma_f32_16x16x32_bf16 v[84:87], v[176:179], v[194:197], v[84:87]
	v_mfma_f32_16x16x32_bf16 v[76:79], v[168:171], v[202:205], v[76:79]
	v_mfma_f32_16x16x32_bf16 v[72:75], v[176:179], v[202:205], v[72:75]
	v_mfma_f32_16x16x32_bf16 v[68:71], v[168:171], v[210:213], v[68:71]
	v_mfma_f32_16x16x32_bf16 v[64:67], v[176:179], v[210:213], v[64:67]
	s_barrier
	s_mov_b32 m0, s60
	v_lshl_add_u64 v[214:215], s[42:43], 0, v[132:133]
	s_add_u32 s38, s42, 0x20000
	ds_read_b128 v[180:183], v145 offset:16384
	ds_read_b128 v[184:187], v145 offset:17408
	ds_read_b128 v[188:191], v145 offset:18432
	ds_read_b128 v[194:197], v145 offset:19456
	ds_read_b128 v[198:201], v145 offset:20480
	ds_read_b128 v[202:205], v145 offset:21504
	ds_read_b128 v[206:209], v145 offset:22528
	ds_read_b128 v[210:213], v145 offset:23552
	global_load_lds_dwordx4 v[214:215], off
	v_lshl_add_u64 v[216:217], s[42:43], 0, v[128:129]
	s_mov_b32 m0, s61
	s_addc_u32 s39, s43, 0
	global_load_lds_dwordx4 v[216:217], off
	v_lshl_add_u64 v[218:219], s[38:39], 0, v[132:133]
	s_mov_b32 m0, s62
	v_lshl_add_u64 v[220:221], s[44:45], 0, v[130:131]
	global_load_lds_dwordx4 v[218:219], off
	v_lshl_add_u64 v[218:219], s[38:39], 0, v[128:129]
	s_mov_b32 m0, s63
	s_nop 0
	global_load_lds_dwordx4 v[218:219], off
	v_lshl_add_u64 v[218:219], s[44:45], 0, v[134:135]
	s_mov_b32 m0, s7
	s_nop 0
	global_load_lds_dwordx4 v[218:219], off
	s_mov_b32 m0, s33
	s_nop 0
	global_load_lds_dwordx4 v[220:221], off
	s_waitcnt vmcnt(8)
	s_waitcnt lgkmcnt(0)
	s_barrier
	s_waitcnt lgkmcnt(0)
	v_mfma_f32_16x16x32_bf16 v[60:63], v[148:151], v[180:183], v[60:63]
	v_mfma_f32_16x16x32_bf16 v[56:59], v[156:159], v[180:183], v[56:59]
	v_mfma_f32_16x16x32_bf16 v[52:55], v[148:151], v[188:191], v[52:55]
	v_mfma_f32_16x16x32_bf16 v[48:51], v[156:159], v[188:191], v[48:51]
	v_mfma_f32_16x16x32_bf16 v[40:43], v[148:151], v[198:201], v[40:43]
	v_mfma_f32_16x16x32_bf16 v[32:35], v[156:159], v[198:201], v[32:35]
	v_mfma_f32_16x16x32_bf16 v[24:27], v[148:151], v[206:209], v[24:27]
	v_mfma_f32_16x16x32_bf16 v[16:19], v[156:159], v[206:209], v[16:19]
	v_mfma_f32_16x16x32_bf16 v[60:63], v[152:155], v[184:187], v[60:63]
	v_mfma_f32_16x16x32_bf16 v[56:59], v[160:163], v[184:187], v[56:59]
	v_mfma_f32_16x16x32_bf16 v[52:55], v[152:155], v[194:197], v[52:55]
	v_mfma_f32_16x16x32_bf16 v[48:51], v[160:163], v[194:197], v[48:51]
	v_mfma_f32_16x16x32_bf16 v[40:43], v[152:155], v[202:205], v[40:43]
	v_mfma_f32_16x16x32_bf16 v[32:35], v[160:163], v[202:205], v[32:35]
	v_mfma_f32_16x16x32_bf16 v[24:27], v[152:155], v[210:213], v[24:27]
	v_mfma_f32_16x16x32_bf16 v[16:19], v[160:163], v[210:213], v[16:19]
	v_mfma_f32_16x16x32_bf16 v[44:47], v[164:167], v[180:183], v[44:47]
	v_mfma_f32_16x16x32_bf16 v[36:39], v[172:175], v[180:183], v[36:39]
	v_mfma_f32_16x16x32_bf16 v[28:31], v[164:167], v[188:191], v[28:31]
	v_mfma_f32_16x16x32_bf16 v[20:23], v[172:175], v[188:191], v[20:23]
	v_mfma_f32_16x16x32_bf16 v[12:15], v[164:167], v[198:201], v[12:15]
	v_mfma_f32_16x16x32_bf16 v[8:11], v[172:175], v[198:201], v[8:11]
	v_mfma_f32_16x16x32_bf16 v[4:7], v[164:167], v[206:209], v[4:7]
	v_mfma_f32_16x16x32_bf16 v[0:3], v[172:175], v[206:209], v[0:3]
	v_mfma_f32_16x16x32_bf16 v[44:47], v[168:171], v[184:187], v[44:47]
	v_mfma_f32_16x16x32_bf16 v[36:39], v[176:179], v[184:187], v[36:39]
	v_mfma_f32_16x16x32_bf16 v[28:31], v[168:171], v[194:197], v[28:31]
	v_mfma_f32_16x16x32_bf16 v[20:23], v[176:179], v[194:197], v[20:23]
	v_mfma_f32_16x16x32_bf16 v[12:15], v[168:171], v[202:205], v[12:15]
	v_mfma_f32_16x16x32_bf16 v[8:11], v[176:179], v[202:205], v[8:11]
	v_mfma_f32_16x16x32_bf16 v[4:7], v[168:171], v[210:213], v[4:7]
	v_mfma_f32_16x16x32_bf16 v[0:3], v[176:179], v[210:213], v[0:3]
	s_barrier
	ds_read_b128 v[148:151], v146
	ds_read_b128 v[152:155], v146 offset:1024
	ds_read_b128 v[156:159], v146 offset:2048
	ds_read_b128 v[160:163], v146 offset:3072
	ds_read_b128 v[164:167], v147
	ds_read_b128 v[168:171], v147 offset:1024
	ds_read_b128 v[172:175], v147 offset:2048
	ds_read_b128 v[176:179], v147 offset:3072
	s_add_u32 s38, s44, 0x30000
	s_addc_u32 s39, s45, 0
	s_mov_b32 m0, s34
	v_lshl_add_u64 v[222:223], s[38:39], 0, v[134:135]
	ds_read_b128 v[180:183], v145 offset:32768
	ds_read_b128 v[184:187], v145 offset:33792
	ds_read_b128 v[188:191], v145 offset:34816
	ds_read_b128 v[194:197], v145 offset:35840
	ds_read_b128 v[198:201], v145 offset:36864
	ds_read_b128 v[202:205], v145 offset:37888
	ds_read_b128 v[206:209], v145 offset:38912
	ds_read_b128 v[210:213], v145 offset:39936
	global_load_lds_dwordx4 v[222:223], off
	v_lshl_add_u64 v[222:223], s[38:39], 0, v[130:131]
	s_mov_b32 m0, s35
	s_nop 0
	global_load_lds_dwordx4 v[222:223], off
	s_waitcnt vmcnt(8)
	s_waitcnt lgkmcnt(0)
	s_barrier
	s_waitcnt lgkmcnt(0)
	v_mfma_f32_16x16x32_bf16 v[124:127], v[148:151], v[180:183], v[124:127]
	v_mfma_f32_16x16x32_bf16 v[120:123], v[156:159], v[180:183], v[120:123]
	v_mfma_f32_16x16x32_bf16 v[116:119], v[148:151], v[188:191], v[116:119]
	v_mfma_f32_16x16x32_bf16 v[112:115], v[156:159], v[188:191], v[112:115]
	v_mfma_f32_16x16x32_bf16 v[104:107], v[148:151], v[198:201], v[104:107]
	v_mfma_f32_16x16x32_bf16 v[96:99], v[156:159], v[198:201], v[96:99]
	v_mfma_f32_16x16x32_bf16 v[88:91], v[148:151], v[206:209], v[88:91]
	v_mfma_f32_16x16x32_bf16 v[80:83], v[156:159], v[206:209], v[80:83]
	v_mfma_f32_16x16x32_bf16 v[124:127], v[152:155], v[184:187], v[124:127]
	v_mfma_f32_16x16x32_bf16 v[120:123], v[160:163], v[184:187], v[120:123]
	v_mfma_f32_16x16x32_bf16 v[116:119], v[152:155], v[194:197], v[116:119]
	v_mfma_f32_16x16x32_bf16 v[112:115], v[160:163], v[194:197], v[112:115]
	v_mfma_f32_16x16x32_bf16 v[104:107], v[152:155], v[202:205], v[104:107]
	v_mfma_f32_16x16x32_bf16 v[96:99], v[160:163], v[202:205], v[96:99]
	v_mfma_f32_16x16x32_bf16 v[88:91], v[152:155], v[210:213], v[88:91]
	v_mfma_f32_16x16x32_bf16 v[80:83], v[160:163], v[210:213], v[80:83]
	v_mfma_f32_16x16x32_bf16 v[108:111], v[164:167], v[180:183], v[108:111]
	v_mfma_f32_16x16x32_bf16 v[100:103], v[172:175], v[180:183], v[100:103]
	v_mfma_f32_16x16x32_bf16 v[92:95], v[164:167], v[188:191], v[92:95]
	v_mfma_f32_16x16x32_bf16 v[84:87], v[172:175], v[188:191], v[84:87]
	v_mfma_f32_16x16x32_bf16 v[76:79], v[164:167], v[198:201], v[76:79]
	v_mfma_f32_16x16x32_bf16 v[72:75], v[172:175], v[198:201], v[72:75]
	v_mfma_f32_16x16x32_bf16 v[68:71], v[164:167], v[206:209], v[68:71]
	v_mfma_f32_16x16x32_bf16 v[64:67], v[172:175], v[206:209], v[64:67]
	v_mfma_f32_16x16x32_bf16 v[108:111], v[168:171], v[184:187], v[108:111]
	v_mfma_f32_16x16x32_bf16 v[100:103], v[176:179], v[184:187], v[100:103]
	v_mfma_f32_16x16x32_bf16 v[92:95], v[168:171], v[194:197], v[92:95]
	v_mfma_f32_16x16x32_bf16 v[84:87], v[176:179], v[194:197], v[84:87]
	v_mfma_f32_16x16x32_bf16 v[76:79], v[168:171], v[202:205], v[76:79]
	v_mfma_f32_16x16x32_bf16 v[72:75], v[176:179], v[202:205], v[72:75]
	v_mfma_f32_16x16x32_bf16 v[68:71], v[168:171], v[210:213], v[68:71]
	v_mfma_f32_16x16x32_bf16 v[64:67], v[176:179], v[210:213], v[64:67]
	s_barrier
	s_mov_b32 m0, s64
	v_lshl_add_u64 v[214:215], v[214:215], 0, s[4:5]
	s_add_u32 s38, s42, 0x20080
	ds_read_b128 v[180:183], v145 offset:49152
	ds_read_b128 v[184:187], v145 offset:50176
	ds_read_b128 v[188:191], v145 offset:51200
	ds_read_b128 v[194:197], v145 offset:52224
	ds_read_b128 v[198:201], v145 offset:53248
	ds_read_b128 v[202:205], v145 offset:54272
	ds_read_b128 v[206:209], v145 offset:55296
	ds_read_b128 v[210:213], v145 offset:56320
	global_load_lds_dwordx4 v[214:215], off
	v_lshl_add_u64 v[214:215], v[216:217], 0, s[4:5]
	s_mov_b32 m0, s65
	s_addc_u32 s39, s43, 0
	global_load_lds_dwordx4 v[214:215], off
	v_lshl_add_u64 v[214:215], s[38:39], 0, v[132:133]
	s_mov_b32 m0, s66
	s_nop 0
	global_load_lds_dwordx4 v[214:215], off
	v_lshl_add_u64 v[214:215], s[38:39], 0, v[128:129]
	s_add_i32 m0, s66, 0x2000
	s_nop 0
	global_load_lds_dwordx4 v[214:215], off
	v_lshl_add_u64 v[214:215], v[218:219], 0, s[4:5]
	s_mov_b32 m0, s49
	s_nop 0
	global_load_lds_dwordx4 v[214:215], off
	v_lshl_add_u64 v[214:215], v[220:221], 0, s[4:5]
	s_mov_b32 m0, s50
	s_nop 0
	global_load_lds_dwordx4 v[214:215], off
	s_waitcnt vmcnt(8)
	s_waitcnt lgkmcnt(0)
	s_barrier
	s_waitcnt lgkmcnt(0)
	v_mfma_f32_16x16x32_bf16 v[60:63], v[148:151], v[180:183], v[60:63]
	v_mfma_f32_16x16x32_bf16 v[56:59], v[156:159], v[180:183], v[56:59]
	v_mfma_f32_16x16x32_bf16 v[52:55], v[148:151], v[188:191], v[52:55]
	v_mfma_f32_16x16x32_bf16 v[48:51], v[156:159], v[188:191], v[48:51]
	v_mfma_f32_16x16x32_bf16 v[40:43], v[148:151], v[198:201], v[40:43]
	v_mfma_f32_16x16x32_bf16 v[32:35], v[156:159], v[198:201], v[32:35]
	v_mfma_f32_16x16x32_bf16 v[24:27], v[148:151], v[206:209], v[24:27]
	v_mfma_f32_16x16x32_bf16 v[16:19], v[156:159], v[206:209], v[16:19]
	v_mfma_f32_16x16x32_bf16 v[60:63], v[152:155], v[184:187], v[60:63]
	v_mfma_f32_16x16x32_bf16 v[56:59], v[160:163], v[184:187], v[56:59]
	v_mfma_f32_16x16x32_bf16 v[52:55], v[152:155], v[194:197], v[52:55]
	v_mfma_f32_16x16x32_bf16 v[48:51], v[160:163], v[194:197], v[48:51]
	v_mfma_f32_16x16x32_bf16 v[40:43], v[152:155], v[202:205], v[40:43]
	v_mfma_f32_16x16x32_bf16 v[32:35], v[160:163], v[202:205], v[32:35]
	v_mfma_f32_16x16x32_bf16 v[24:27], v[152:155], v[210:213], v[24:27]
	v_mfma_f32_16x16x32_bf16 v[16:19], v[160:163], v[210:213], v[16:19]
	v_mfma_f32_16x16x32_bf16 v[44:47], v[164:167], v[180:183], v[44:47]
	v_mfma_f32_16x16x32_bf16 v[36:39], v[172:175], v[180:183], v[36:39]
	v_mfma_f32_16x16x32_bf16 v[28:31], v[164:167], v[188:191], v[28:31]
	v_mfma_f32_16x16x32_bf16 v[20:23], v[172:175], v[188:191], v[20:23]
	v_mfma_f32_16x16x32_bf16 v[12:15], v[164:167], v[198:201], v[12:15]
	v_mfma_f32_16x16x32_bf16 v[8:11], v[172:175], v[198:201], v[8:11]
	v_mfma_f32_16x16x32_bf16 v[4:7], v[164:167], v[206:209], v[4:7]
	v_mfma_f32_16x16x32_bf16 v[0:3], v[172:175], v[206:209], v[0:3]
	v_mfma_f32_16x16x32_bf16 v[44:47], v[168:171], v[184:187], v[44:47]
	v_mfma_f32_16x16x32_bf16 v[36:39], v[176:179], v[184:187], v[36:39]
	v_mfma_f32_16x16x32_bf16 v[28:31], v[168:171], v[194:197], v[28:31]
	v_mfma_f32_16x16x32_bf16 v[20:23], v[176:179], v[194:197], v[20:23]
	v_mfma_f32_16x16x32_bf16 v[12:15], v[168:171], v[202:205], v[12:15]
	v_mfma_f32_16x16x32_bf16 v[8:11], v[176:179], v[202:205], v[8:11]
	v_mfma_f32_16x16x32_bf16 v[4:7], v[168:171], v[210:213], v[4:7]
	v_mfma_f32_16x16x32_bf16 v[0:3], v[176:179], v[210:213], v[0:3]
	s_barrier
	s_add_i32 s68, s68, 2
	s_add_u32 s9, s9, 0x100
	s_addc_u32 s13, s13, 0
	s_cmp_gt_u32 s68, 5
	s_mov_b64 s[38:39], s[40:41]
	s_cbranch_scc0 .LBB0_440
	s_and_b64 vcc, exec, s[10:11]
	s_cbranch_vccz .LBB0_443
	s_barrier

.LBB0_447:
	s_setprio 0
	s_mov_b32 s6, s101
	v_mov_b32_e32 v150, v193
	s_cmpk_lt_i32 s6, 0x200
	s_cselect_b64 s[28:29], -1, 0
	v_readfirstlane_b32 s0, v150
	s_cmpk_gt_i32 s6, 0x1ff
	s_movk_i32 s2, 0x1ff
	s_cbranch_scc1 .LBB0_492
	v_lshlrev_b32_e32 v0, 3, v150
	v_ashrrev_i32_e32 v1, 31, v0
	v_and_b32_e32 v4, 15, v150
	v_lshl_add_u64 v[2:3], v[0:1], 1, s[90:91]
	v_lshlrev_b32_e32 v1, 2, v150
	v_and_b32_e32 v0, 0xff8, v0
	s_add_i32 s7, 0, 0x10100
	s_ashr_i32 s3, s0, 6
	s_mov_b64 s[0:1], 0x40f0000
	s_movk_i32 s4, 0x7fc
	v_and_b32_e32 v1, 0x7fc, v1
	v_add_u32_e32 v151, s7, v0
	v_add_u32_e32 v0, 7, v4
	v_lshl_add_u64 v[138:139], v[2:3], 0, s[0:1]
	v_lshlrev_b32_e32 v140, 1, v1
	v_cmp_ne_u32_e64 s[0:1], 0, v1
	v_cmp_ne_u32_e64 s[16:17], s4, v1
	v_and_b32_e32 v1, 24, v0
	v_lshlrev_b32_e32 v0, 1, v0
	v_and_b32_e32 v6, 63, v150
	v_and_b32_e32 v0, 48, v0
	v_sub_u32_e32 v0, v6, v0
	v_sub_u32_e32 v1, v1, v4
	v_and_b32_e32 v0, -16, v0
	s_movk_i32 s8, 0x2020
	v_bfe_u32 v7, v150, 4, 2
	s_movk_i32 s64, 0x1010
	v_mad_i32_i24 v10, v1, s8, v0
	v_mov_b32_e32 v0, s7
	v_mad_u32_u24 v153, v4, s64, v0
	v_lshlrev_b32_e32 v0, 2, v7
	v_mov_b32_e32 v141, 0
	v_lshl_or_b32 v0, s3, 8, v0
	v_lshl_add_u64 v[142:143], s[20:21], 0, v[140:141]
	v_lshlrev_b32_e32 v140, 12, v4
	v_ashrrev_i32_e32 v1, 31, v0
	v_cmp_gt_u32_e64 s[4:5], s2, v193
	s_lshl_b32 s2, s3, 9
	v_mul_u32_u24_e32 v9, 0x1010, v4
	v_lshl_add_u64 v[2:3], s[20:21], 0, v[140:141]
	v_lshlrev_b64 v[4:5], 1, v[0:1]
	v_cmp_lt_i32_e32 vcc, 0, v0
	s_movk_i32 s3, 0x70c
	v_add_u32_e32 v1, 48, v150
	v_lshl_add_u64 v[144:145], v[2:3], 0, v[4:5]
	v_cndmask_b32_e64 v146, 0, -1, vcc
	v_cmp_gt_i32_e32 vcc, s3, v0
	v_and_b32_e32 v3, 63, v1
	v_add_u32_e32 v1, 16, v150
	s_movk_i32 s3, 0x70b
	v_cmp_eq_u32_e64 s[8:9], 0, v0
	v_cmp_eq_u32_e64 s[10:11], 3, v7
	v_cmp_gt_u32_e64 s[12:13], 16, v6
	v_and_b32_e32 v6, 63, v1
	v_cmp_lt_i32_e64 s[14:15], s3, v0
	v_lshlrev_b32_e32 v7, 1, v0
	v_lshl_add_u64 v[0:1], s[18:19], 0, v[140:141]
	v_lshl_add_u64 v[148:149], v[0:1], 0, v[4:5]
	v_subrev_u32_e32 v0, s2, v10
	v_add_u32_e32 v0, 0, v0
	v_add_u32_e32 v154, 0x1020, v0
	v_mbcnt_hi_u32_b32 v0, -1, v226
	v_and_b32_e32 v0, 64, v0
	v_lshlrev_b32_e32 v8, 4, v193
	v_and_b32_e32 v152, 48, v150
	v_add_u32_e32 v11, 0, v10
	s_sub_i32 s33, 0, s2
	v_cndmask_b32_e64 v2, 3, 4, vcc
	v_or_b32_e32 v1, v0, v3
	v_or_b32_e32 v0, v0, v6
	v_mov_b32_e32 v147, v146
	v_add3_u32 v155, v9, v152, 0
	v_mov_b32_e32 v156, 0x1000
	v_mov_b32_e32 v157, 0x3000
	s_mov_b32 s65, 0x1000706
	v_mov_b32_e32 v158, 0x2000
	v_lshlrev_b32_e32 v140, 1, v2
	v_mov_b32_e32 v159, 0x4000
	s_mov_b64 s[38:39], 0x4000000
	v_add_u32_e32 v160, 0, v8
	v_add_u32_e32 v161, s33, v11
	v_lshlrev_b32_e32 v162, 2, v1
	v_lshlrev_b32_e32 v163, 2, v0
	v_add_u32_e32 v164, v153, v7
	s_mov_b32 s40, s6

.LBB0_641:
	s_or_b64 exec, exec, s[0:1]
	s_mov_b32 s101, s6
	s_and_b32 s98, s6, 7
	s_lshl_b32 s98, s98, 5
	s_lshr_b32 s6, s6, 3
	s_add_i32 s6, s6, s98
	v_mov_b32_e32 v9, v193
	s_cmpk_lt_i32 s6, 0x100
	s_waitcnt lgkmcnt(0)
	s_barrier
	s_cselect_b64 s[0:1], -1, 0
	s_cmpk_gt_i32 s6, 0xff
	v_readfirstlane_b32 s3, v9
	s_cbranch_scc1 .LBB0_657
	v_lshlrev_b32_e32 v0, 4, v9
	v_add_u32_e32 v1, 0x2000, v0
	v_ashrrev_i32_e32 v2, 31, v1
	v_lshrrev_b32_e32 v2, 22, v2
	v_add_u32_e32 v2, v1, v2
	v_ashrrev_i32_e32 v8, 10, v2
	v_mul_i32_i24_e32 v2, 0x400, v8
	v_sub_u32_e32 v1, v1, v2
	v_lshrrev_b32_e32 v2, 4, v1
	v_bitop3_b32 v1, v2, v1, 32 bitop3:0x6c
	v_ashrrev_i32_e32 v2, 31, v1
	v_lshrrev_b32_e32 v2, 26, v2
	v_add_u32_e32 v2, v1, v2
	v_lshlrev_b32_e32 v3, 3, v8
	v_ashrrev_i32_e32 v10, 6, v2
	v_and_b32_e32 v3, -16, v3
	v_add_u32_e32 v3, v10, v3
	v_and_b32_e32 v4, 3, v10
	s_mov_b32 s2, 0xffffe0
	v_lshrrev_b32_e32 v5, 2, v3
	v_lshlrev_b32_e32 v6, 1, v3
	v_and_b32_e32 v2, 0xc0, v2
	v_and_or_b32 v4, v3, s2, v4
	v_and_b32_e32 v5, 4, v5
	v_and_b32_e32 v6, 24, v6
	v_sub_u32_e32 v1, v1, v2
	v_mov_b32_e32 v2, 1
	v_or3_b32 v4, v4, v5, v6
	v_lshlrev_b32_e32 v5, 5, v8
	v_ashrrev_i16_sdwa v1, v2, sext(v1) dst_sel:DWORD dst_unused:UNUSED_PAD src0_sel:DWORD src1_sel:BYTE_0
	s_movk_i32 s33, 0x300
	v_and_b32_e32 v11, 32, v5
	v_bfe_i32 v12, v1, 0, 16
	v_mul_u32_u24_e32 v4, 0x300, v4
	v_add_u32_e32 v1, v11, v12
	v_mul_lo_u32 v3, v3, s33
	v_add_lshl_u32 v128, v4, v1, 1
	v_add_lshl_u32 v130, v1, v3, 1
	v_bfe_i32 v1, v9, 27, 1
	v_lshrrev_b32_e32 v1, 22, v1
	v_add_u32_e32 v1, v0, v1
	v_and_b32_e32 v1, 0xfffffc00, v1
	v_sub_u32_e32 v0, v0, v1
	v_lshrrev_b32_e32 v1, 4, v0
	v_ashrrev_i32_e32 v3, 31, v9
	v_bitop3_b32 v0, v1, v0, 32 bitop3:0x6c
	v_lshrrev_b32_e32 v3, 26, v3
	v_ashrrev_i32_e32 v1, 31, v0
	v_add_u32_e32 v3, v9, v3
	v_lshrrev_b32_e32 v1, 26, v1
	v_ashrrev_i32_e32 v14, 6, v3
	v_add_u32_e32 v1, v0, v1
	v_lshlrev_b32_e32 v3, 3, v14
	s_add_u32 s66, s90, 0x1f60000
	v_ashrrev_i32_e32 v13, 6, v1
	v_and_b32_e32 v3, -16, v3
	s_addc_u32 s67, s91, 0
	v_add_u32_e32 v3, v13, v3
	v_and_b32_e32 v4, 3, v13
	s_ashr_i32 s9, s6, 31
	v_and_or_b32 v4, v3, s2, v4
	s_lshr_b32 s2, s6, 31
	s_lshr_b32 s9, s9, 29
	s_add_i32 s2, s6, s2
	s_add_i32 s9, s6, s9
	s_and_b32 s8, s2, 0xfffffe
	s_ashr_i32 s54, s9, 3
	s_lshl_b32 s2, s2, 7
	s_sub_i32 s8, s6, s8
	s_and_b32 s2, s2, 0x300
	s_ashr_i32 s55, s54, 31
	s_lshl_b32 s56, s8, 8
	s_lshl_b64 s[8:9], s[54:55], 11
	s_lshl_b32 s11, s2, 1
	s_or_b32 s8, s8, s11
	s_ashr_i32 s10, s3, 6
	s_mulk_i32 s9, 0x300
	s_mul_hi_u32 s11, s8, 0x300
	s_ashr_i32 s7, s3, 8
	s_lshl_b32 s68, s10, 10
	s_add_i32 s11, s11, s9
	s_mulk_i32 s8, 0x300
	s_add_u32 s58, s26, s8
	s_addc_u32 s59, s27, s11
	s_ashr_i32 s57, s56, 31
	s_lshl_b64 s[8:9], s[54:55], 10
	s_lshl_b64 s[30:31], s[56:57], 1
	s_add_u32 s8, s30, s8
	v_lshrrev_b32_e32 v5, 2, v3
	v_lshlrev_b32_e32 v6, 1, v3
	v_and_b32_e32 v1, 0xc0, v1
	s_addc_u32 s9, s31, s9
	v_and_b32_e32 v5, 4, v5
	v_and_b32_e32 v6, 24, v6
	v_sub_u32_e32 v0, v0, v1
	s_mulk_i32 s9, 0x300
	s_mul_hi_u32 s11, s8, 0x300
	v_or3_b32 v4, v4, v5, v6
	v_lshlrev_b32_e32 v5, 5, v14
	v_ashrrev_i16_sdwa v0, v2, sext(v0) dst_sel:DWORD dst_unused:UNUSED_PAD src0_sel:DWORD src1_sel:BYTE_0
	s_add_i32 s11, s11, s9
	s_mulk_i32 s8, 0x300
	v_and_b32_e32 v15, 32, v5
	v_bfe_i32 v16, v0, 0, 16
	s_add_u32 s60, s66, s8
	v_mul_u32_u24_e32 v4, 0x300, v4
	v_add_u32_e32 v0, v15, v16
	s_addc_u32 s61, s67, s11
	s_add_i32 s57, s68, 0
	v_add_lshl_u32 v132, v4, v0, 1
	s_add_i32 m0, s57, 0x10000
	v_mul_lo_u32 v1, v3, s33
	global_load_lds_dwordx4 v132, s[60:61]
	s_add_i32 m0, s57, 0x12000
	s_add_u32 s8, s60, 0x30000
	global_load_lds_dwordx4 v128, s[60:61]
	s_addc_u32 s9, s61, 0
	s_add_i32 m0, s57, 0x14000
	s_add_i32 s69, s57, 0x2000
	global_load_lds_dwordx4 v132, s[8:9]
	s_add_i32 m0, s57, 0x16000
	v_add_lshl_u32 v134, v0, v1, 1
	global_load_lds_dwordx4 v128, s[8:9]
	s_mov_b32 m0, s57
	s_add_u32 s8, s58, 0x30000
	global_load_lds_dwordx4 v134, s[58:59]
	s_mov_b32 m0, s69
	s_addc_u32 s9, s59, 0
	s_add_i32 s70, s57, 0x4000
	global_load_lds_dwordx4 v130, s[58:59]
	s_mov_b32 m0, s70
	s_add_i32 s71, s57, 0x6000
	global_load_lds_dwordx4 v134, s[8:9]
	s_mov_b32 m0, s71
	v_mov_b32_e32 v137, 0
	global_load_lds_dwordx4 v130, s[8:9]
	v_mov_b32_e32 v133, v137
	v_mov_b32_e32 v129, v137
	v_mov_b32_e32 v135, v137
	v_mov_b32_e32 v131, v137
	s_cmp_eq_u32 s7, 1
	s_mov_b32 s72, 0
	v_lshl_add_u64 v[6:7], s[60:61], 0, v[132:133]
	v_lshl_add_u64 v[4:5], s[60:61], 0, v[128:129]
	v_lshl_add_u64 v[0:1], s[58:59], 0, v[134:135]
	s_cselect_b64 s[8:9], -1, 0
	s_cmp_lg_u32 s7, 1
	v_lshl_add_u64 v[2:3], s[58:59], 0, v[130:131]
	s_cbranch_scc1 .LBB0_644
	s_setprio 1
	s_barrier

.LBB0_650:
	ds_read_b128 v[148:151], v145
	ds_read_b128 v[152:155], v145 offset:1024
	ds_read_b128 v[156:159], v145 offset:2048
	ds_read_b128 v[160:163], v145 offset:3072
	ds_read_b128 v[164:167], v146
	ds_read_b128 v[168:171], v146 offset:1024
	ds_read_b128 v[172:175], v146 offset:2048
	ds_read_b128 v[176:179], v146 offset:3072
	s_add_u32 s60, s58, 0x100
	s_addc_u32 s61, s59, 0
	s_cmp_eq_u32 s33, 8
	s_cselect_b32 s65, s45, s61
	s_cselect_b32 s64, s44, s60
	s_cselect_b32 s63, s49, s7
	s_cselect_b32 s62, s48, s3
	s_mov_b32 m0, s77
	v_lshl_add_u64 v[214:215], s[58:59], 0, v[138:139]
	ds_read_b128 v[180:183], v147
	ds_read_b128 v[184:187], v147 offset:1024
	ds_read_b128 v[188:191], v147 offset:2048
	ds_read_b128 v[194:197], v147 offset:3072
	ds_read_b128 v[198:201], v147 offset:4096
	ds_read_b128 v[202:205], v147 offset:5120
	ds_read_b128 v[206:209], v147 offset:6144
	ds_read_b128 v[210:213], v147 offset:7168
	global_load_lds_dwordx4 v[214:215], off
	v_lshl_add_u64 v[214:215], s[58:59], 0, v[140:141]
	s_mov_b32 m0, s78
	s_nop 0
	global_load_lds_dwordx4 v[214:215], off
	s_waitcnt vmcnt(8)
	s_waitcnt lgkmcnt(0)
	s_barrier
	s_waitcnt lgkmcnt(0)
	v_mfma_f32_16x16x32_bf16 v[124:127], v[148:151], v[180:183], v[124:127]
	v_mfma_f32_16x16x32_bf16 v[120:123], v[156:159], v[180:183], v[120:123]
	v_mfma_f32_16x16x32_bf16 v[108:111], v[148:151], v[188:191], v[108:111]
	v_mfma_f32_16x16x32_bf16 v[104:107], v[156:159], v[188:191], v[104:107]
	v_mfma_f32_16x16x32_bf16 v[92:95], v[148:151], v[198:201], v[92:95]
	v_mfma_f32_16x16x32_bf16 v[88:91], v[156:159], v[198:201], v[88:91]
	v_mfma_f32_16x16x32_bf16 v[76:79], v[148:151], v[206:209], v[76:79]
	v_mfma_f32_16x16x32_bf16 v[72:75], v[156:159], v[206:209], v[72:75]
	v_mfma_f32_16x16x32_bf16 v[124:127], v[152:155], v[184:187], v[124:127]
	v_mfma_f32_16x16x32_bf16 v[120:123], v[160:163], v[184:187], v[120:123]
	v_mfma_f32_16x16x32_bf16 v[108:111], v[152:155], v[194:197], v[108:111]
	v_mfma_f32_16x16x32_bf16 v[104:107], v[160:163], v[194:197], v[104:107]
	v_mfma_f32_16x16x32_bf16 v[92:95], v[152:155], v[202:205], v[92:95]
	v_mfma_f32_16x16x32_bf16 v[88:91], v[160:163], v[202:205], v[88:91]
	v_mfma_f32_16x16x32_bf16 v[76:79], v[152:155], v[210:213], v[76:79]
	v_mfma_f32_16x16x32_bf16 v[72:75], v[160:163], v[210:213], v[72:75]
	v_mfma_f32_16x16x32_bf16 v[116:119], v[164:167], v[180:183], v[116:119]
	v_mfma_f32_16x16x32_bf16 v[112:115], v[172:175], v[180:183], v[112:115]
	v_mfma_f32_16x16x32_bf16 v[100:103], v[164:167], v[188:191], v[100:103]
	v_mfma_f32_16x16x32_bf16 v[96:99], v[172:175], v[188:191], v[96:99]
	v_mfma_f32_16x16x32_bf16 v[84:87], v[164:167], v[198:201], v[84:87]
	v_mfma_f32_16x16x32_bf16 v[80:83], v[172:175], v[198:201], v[80:83]
	v_mfma_f32_16x16x32_bf16 v[68:71], v[164:167], v[206:209], v[68:71]
	v_mfma_f32_16x16x32_bf16 v[64:67], v[172:175], v[206:209], v[64:67]
	v_mfma_f32_16x16x32_bf16 v[116:119], v[168:171], v[184:187], v[116:119]
	v_mfma_f32_16x16x32_bf16 v[112:115], v[176:179], v[184:187], v[112:115]
	v_mfma_f32_16x16x32_bf16 v[100:103], v[168:171], v[194:197], v[100:103]
	v_mfma_f32_16x16x32_bf16 v[96:99], v[176:179], v[194:197], v[96:99]
	v_mfma_f32_16x16x32_bf16 v[84:87], v[168:171], v[202:205], v[84:87]
	v_mfma_f32_16x16x32_bf16 v[80:83], v[176:179], v[202:205], v[80:83]
	v_mfma_f32_16x16x32_bf16 v[68:71], v[168:171], v[210:213], v[68:71]
	v_mfma_f32_16x16x32_bf16 v[64:67], v[176:179], v[210:213], v[64:67]
	s_barrier
	s_mov_b32 m0, s79
	v_lshl_add_u64 v[214:215], s[62:63], 0, v[132:133]
	s_add_u32 s34, s62, 0x30000
	ds_read_b128 v[180:183], v147 offset:16384
	ds_read_b128 v[184:187], v147 offset:17408
	ds_read_b128 v[188:191], v147 offset:18432
	ds_read_b128 v[194:197], v147 offset:19456
	ds_read_b128 v[198:201], v147 offset:20480
	ds_read_b128 v[202:205], v147 offset:21504
	ds_read_b128 v[206:209], v147 offset:22528
	ds_read_b128 v[210:213], v147 offset:23552
	global_load_lds_dwordx4 v[214:215], off
	v_lshl_add_u64 v[216:217], s[62:63], 0, v[128:129]
	s_mov_b32 m0, s80
	s_addc_u32 s35, s63, 0
	s_add_i32 s43, s75, s68
	global_load_lds_dwordx4 v[216:217], off
	v_lshl_add_u64 v[218:219], s[34:35], 0, v[132:133]
	s_mov_b32 m0, s43
	v_lshl_add_u64 v[220:221], s[64:65], 0, v[130:131]
	global_load_lds_dwordx4 v[218:219], off
	v_lshl_add_u64 v[218:219], s[34:35], 0, v[128:129]
	s_add_i32 m0, s43, 0x2000
	s_nop 0
	global_load_lds_dwordx4 v[218:219], off
	v_lshl_add_u64 v[218:219], s[64:65], 0, v[134:135]
	s_mov_b32 m0, s57
	s_nop 0
	global_load_lds_dwordx4 v[218:219], off
	s_mov_b32 m0, s69
	s_nop 0
	global_load_lds_dwordx4 v[220:221], off
	s_waitcnt vmcnt(8)
	s_waitcnt lgkmcnt(0)
	s_barrier
	s_waitcnt lgkmcnt(0)
	v_mfma_f32_16x16x32_bf16 v[60:63], v[148:151], v[180:183], v[60:63]
	v_mfma_f32_16x16x32_bf16 v[56:59], v[156:159], v[180:183], v[56:59]
	v_mfma_f32_16x16x32_bf16 v[44:47], v[148:151], v[188:191], v[44:47]
	v_mfma_f32_16x16x32_bf16 v[40:43], v[156:159], v[188:191], v[40:43]
	v_mfma_f32_16x16x32_bf16 v[28:31], v[148:151], v[198:201], v[28:31]
	v_mfma_f32_16x16x32_bf16 v[24:27], v[156:159], v[198:201], v[24:27]
	v_mfma_f32_16x16x32_bf16 v[12:15], v[148:151], v[206:209], v[12:15]
	v_mfma_f32_16x16x32_bf16 v[8:11], v[156:159], v[206:209], v[8:11]
	v_mfma_f32_16x16x32_bf16 v[60:63], v[152:155], v[184:187], v[60:63]
	v_mfma_f32_16x16x32_bf16 v[56:59], v[160:163], v[184:187], v[56:59]
	v_mfma_f32_16x16x32_bf16 v[44:47], v[152:155], v[194:197], v[44:47]
	v_mfma_f32_16x16x32_bf16 v[40:43], v[160:163], v[194:197], v[40:43]
	v_mfma_f32_16x16x32_bf16 v[28:31], v[152:155], v[202:205], v[28:31]
	v_mfma_f32_16x16x32_bf16 v[24:27], v[160:163], v[202:205], v[24:27]
	v_mfma_f32_16x16x32_bf16 v[12:15], v[152:155], v[210:213], v[12:15]
	v_mfma_f32_16x16x32_bf16 v[8:11], v[160:163], v[210:213], v[8:11]
	v_mfma_f32_16x16x32_bf16 v[52:55], v[164:167], v[180:183], v[52:55]
	v_mfma_f32_16x16x32_bf16 v[48:51], v[172:175], v[180:183], v[48:51]
	v_mfma_f32_16x16x32_bf16 v[36:39], v[164:167], v[188:191], v[36:39]
	v_mfma_f32_16x16x32_bf16 v[32:35], v[172:175], v[188:191], v[32:35]
	v_mfma_f32_16x16x32_bf16 v[20:23], v[164:167], v[198:201], v[20:23]
	v_mfma_f32_16x16x32_bf16 v[16:19], v[172:175], v[198:201], v[16:19]
	v_mfma_f32_16x16x32_bf16 v[4:7], v[164:167], v[206:209], v[4:7]
	v_mfma_f32_16x16x32_bf16 v[0:3], v[172:175], v[206:209], v[0:3]
	v_mfma_f32_16x16x32_bf16 v[52:55], v[168:171], v[184:187], v[52:55]
	v_mfma_f32_16x16x32_bf16 v[48:51], v[176:179], v[184:187], v[48:51]
	v_mfma_f32_16x16x32_bf16 v[36:39], v[168:171], v[194:197], v[36:39]
	v_mfma_f32_16x16x32_bf16 v[32:35], v[176:179], v[194:197], v[32:35]
	v_mfma_f32_16x16x32_bf16 v[20:23], v[168:171], v[202:205], v[20:23]
	v_mfma_f32_16x16x32_bf16 v[16:19], v[176:179], v[202:205], v[16:19]
	v_mfma_f32_16x16x32_bf16 v[4:7], v[168:171], v[210:213], v[4:7]
	v_mfma_f32_16x16x32_bf16 v[0:3], v[176:179], v[210:213], v[0:3]
	s_barrier
	s_add_i32 s43, 0, 0x18000
	v_add_u32_e32 v136, s43, v143
	s_add_i32 s55, 0, 0x1c000
	ds_read_b128 v[148:151], v136
	ds_read_b128 v[152:155], v136 offset:1024
	ds_read_b128 v[156:159], v136 offset:2048
	ds_read_b128 v[160:163], v136 offset:3072
	v_add_u32_e32 v136, s55, v143
	ds_read_b128 v[164:167], v136
	ds_read_b128 v[168:171], v136 offset:1024
	ds_read_b128 v[172:175], v136 offset:2048
	ds_read_b128 v[176:179], v136 offset:3072
	s_add_u32 s34, s64, 0x30000
	s_addc_u32 s35, s65, 0
	s_mov_b32 m0, s70
	v_lshl_add_u64 v[222:223], s[34:35], 0, v[134:135]
	ds_read_b128 v[180:183], v147 offset:32768
	ds_read_b128 v[184:187], v147 offset:33792
	ds_read_b128 v[188:191], v147 offset:34816
	ds_read_b128 v[194:197], v147 offset:35840
	ds_read_b128 v[198:201], v147 offset:36864
	ds_read_b128 v[202:205], v147 offset:37888
	ds_read_b128 v[206:209], v147 offset:38912
	ds_read_b128 v[210:213], v147 offset:39936
	global_load_lds_dwordx4 v[222:223], off
	v_lshl_add_u64 v[222:223], s[34:35], 0, v[130:131]
	s_mov_b32 m0, s71
	s_nop 0
	global_load_lds_dwordx4 v[222:223], off
	s_waitcnt vmcnt(8)
	s_waitcnt lgkmcnt(0)
	s_barrier
	s_waitcnt lgkmcnt(0)
	v_mfma_f32_16x16x32_bf16 v[124:127], v[148:151], v[180:183], v[124:127]
	v_mfma_f32_16x16x32_bf16 v[120:123], v[156:159], v[180:183], v[120:123]
	v_mfma_f32_16x16x32_bf16 v[108:111], v[148:151], v[188:191], v[108:111]
	v_mfma_f32_16x16x32_bf16 v[104:107], v[156:159], v[188:191], v[104:107]
	v_mfma_f32_16x16x32_bf16 v[92:95], v[148:151], v[198:201], v[92:95]
	v_mfma_f32_16x16x32_bf16 v[88:91], v[156:159], v[198:201], v[88:91]
	v_mfma_f32_16x16x32_bf16 v[76:79], v[148:151], v[206:209], v[76:79]
	v_mfma_f32_16x16x32_bf16 v[72:75], v[156:159], v[206:209], v[72:75]
	v_mfma_f32_16x16x32_bf16 v[124:127], v[152:155], v[184:187], v[124:127]
	v_mfma_f32_16x16x32_bf16 v[120:123], v[160:163], v[184:187], v[120:123]
	v_mfma_f32_16x16x32_bf16 v[108:111], v[152:155], v[194:197], v[108:111]
	v_mfma_f32_16x16x32_bf16 v[104:107], v[160:163], v[194:197], v[104:107]
	v_mfma_f32_16x16x32_bf16 v[92:95], v[152:155], v[202:205], v[92:95]
	v_mfma_f32_16x16x32_bf16 v[88:91], v[160:163], v[202:205], v[88:91]
	v_mfma_f32_16x16x32_bf16 v[76:79], v[152:155], v[210:213], v[76:79]
	v_mfma_f32_16x16x32_bf16 v[72:75], v[160:163], v[210:213], v[72:75]
	v_mfma_f32_16x16x32_bf16 v[116:119], v[164:167], v[180:183], v[116:119]
	v_mfma_f32_16x16x32_bf16 v[112:115], v[172:175], v[180:183], v[112:115]
	v_mfma_f32_16x16x32_bf16 v[100:103], v[164:167], v[188:191], v[100:103]
	v_mfma_f32_16x16x32_bf16 v[96:99], v[172:175], v[188:191], v[96:99]
	v_mfma_f32_16x16x32_bf16 v[84:87], v[164:167], v[198:201], v[84:87]
	v_mfma_f32_16x16x32_bf16 v[80:83], v[172:175], v[198:201], v[80:83]
	v_mfma_f32_16x16x32_bf16 v[68:71], v[164:167], v[206:209], v[68:71]
	v_mfma_f32_16x16x32_bf16 v[64:67], v[172:175], v[206:209], v[64:67]
	v_mfma_f32_16x16x32_bf16 v[116:119], v[168:171], v[184:187], v[116:119]
	v_mfma_f32_16x16x32_bf16 v[112:115], v[176:179], v[184:187], v[112:115]
	v_mfma_f32_16x16x32_bf16 v[100:103], v[168:171], v[194:197], v[100:103]
	v_mfma_f32_16x16x32_bf16 v[96:99], v[176:179], v[194:197], v[96:99]
	v_mfma_f32_16x16x32_bf16 v[84:87], v[168:171], v[202:205], v[84:87]
	v_mfma_f32_16x16x32_bf16 v[80:83], v[176:179], v[202:205], v[80:83]
	v_mfma_f32_16x16x32_bf16 v[68:71], v[168:171], v[210:213], v[68:71]
	v_mfma_f32_16x16x32_bf16 v[64:67], v[176:179], v[210:213], v[64:67]
	s_barrier
	s_add_i32 s34, s43, s68
	v_lshl_add_u64 v[214:215], v[214:215], 0, s[10:11]
	s_mov_b32 m0, s34
	ds_read_b128 v[180:183], v147 offset:49152
	ds_read_b128 v[184:187], v147 offset:50176
	ds_read_b128 v[188:191], v147 offset:51200
	ds_read_b128 v[194:197], v147 offset:52224
	ds_read_b128 v[198:201], v147 offset:53248
	ds_read_b128 v[202:205], v147 offset:54272
	ds_read_b128 v[206:209], v147 offset:55296
	ds_read_b128 v[210:213], v147 offset:56320
	global_load_lds_dwordx4 v[214:215], off
	s_add_i32 m0, s34, 0x2000
	s_add_u32 s34, s62, 0x30080
	v_lshl_add_u64 v[214:215], v[216:217], 0, s[10:11]
	s_addc_u32 s35, s63, 0
	s_add_i32 s43, s55, s68
	global_load_lds_dwordx4 v[214:215], off
	v_lshl_add_u64 v[214:215], s[34:35], 0, v[132:133]
	s_mov_b32 m0, s43
	s_nop 0
	global_load_lds_dwordx4 v[214:215], off
	v_lshl_add_u64 v[214:215], s[34:35], 0, v[128:129]
	s_add_i32 m0, s43, 0x2000
	s_nop 0
	global_load_lds_dwordx4 v[214:215], off
	v_lshl_add_u64 v[214:215], v[218:219], 0, s[10:11]
	s_mov_b32 m0, s73
	s_nop 0
	global_load_lds_dwordx4 v[214:215], off
	v_lshl_add_u64 v[214:215], v[220:221], 0, s[10:11]
	s_mov_b32 m0, s74
	s_nop 0
	global_load_lds_dwordx4 v[214:215], off
	s_waitcnt vmcnt(8)
	s_waitcnt lgkmcnt(0)
	s_barrier
	s_waitcnt lgkmcnt(0)
	v_mfma_f32_16x16x32_bf16 v[60:63], v[148:151], v[180:183], v[60:63]
	v_mfma_f32_16x16x32_bf16 v[56:59], v[156:159], v[180:183], v[56:59]
	v_mfma_f32_16x16x32_bf16 v[44:47], v[148:151], v[188:191], v[44:47]
	v_mfma_f32_16x16x32_bf16 v[40:43], v[156:159], v[188:191], v[40:43]
	v_mfma_f32_16x16x32_bf16 v[28:31], v[148:151], v[198:201], v[28:31]
	v_mfma_f32_16x16x32_bf16 v[24:27], v[156:159], v[198:201], v[24:27]
	v_mfma_f32_16x16x32_bf16 v[12:15], v[148:151], v[206:209], v[12:15]
	v_mfma_f32_16x16x32_bf16 v[8:11], v[156:159], v[206:209], v[8:11]
	v_mfma_f32_16x16x32_bf16 v[60:63], v[152:155], v[184:187], v[60:63]
	v_mfma_f32_16x16x32_bf16 v[56:59], v[160:163], v[184:187], v[56:59]
	v_mfma_f32_16x16x32_bf16 v[44:47], v[152:155], v[194:197], v[44:47]
	v_mfma_f32_16x16x32_bf16 v[40:43], v[160:163], v[194:197], v[40:43]
	v_mfma_f32_16x16x32_bf16 v[28:31], v[152:155], v[202:205], v[28:31]
	v_mfma_f32_16x16x32_bf16 v[24:27], v[160:163], v[202:205], v[24:27]
	v_mfma_f32_16x16x32_bf16 v[12:15], v[152:155], v[210:213], v[12:15]
	v_mfma_f32_16x16x32_bf16 v[8:11], v[160:163], v[210:213], v[8:11]
	v_mfma_f32_16x16x32_bf16 v[52:55], v[164:167], v[180:183], v[52:55]
	v_mfma_f32_16x16x32_bf16 v[48:51], v[172:175], v[180:183], v[48:51]
	v_mfma_f32_16x16x32_bf16 v[36:39], v[164:167], v[188:191], v[36:39]
	v_mfma_f32_16x16x32_bf16 v[32:35], v[172:175], v[188:191], v[32:35]
	v_mfma_f32_16x16x32_bf16 v[20:23], v[164:167], v[198:201], v[20:23]
	v_mfma_f32_16x16x32_bf16 v[16:19], v[172:175], v[198:201], v[16:19]
	v_mfma_f32_16x16x32_bf16 v[4:7], v[164:167], v[206:209], v[4:7]
	v_mfma_f32_16x16x32_bf16 v[0:3], v[172:175], v[206:209], v[0:3]
	v_mfma_f32_16x16x32_bf16 v[52:55], v[168:171], v[184:187], v[52:55]
	v_mfma_f32_16x16x32_bf16 v[48:51], v[176:179], v[184:187], v[48:51]
	v_mfma_f32_16x16x32_bf16 v[36:39], v[168:171], v[194:197], v[36:39]
	v_mfma_f32_16x16x32_bf16 v[32:35], v[176:179], v[194:197], v[32:35]
	v_mfma_f32_16x16x32_bf16 v[20:23], v[168:171], v[202:205], v[20:23]
	v_mfma_f32_16x16x32_bf16 v[16:19], v[176:179], v[202:205], v[16:19]
	v_mfma_f32_16x16x32_bf16 v[4:7], v[168:171], v[210:213], v[4:7]
	v_mfma_f32_16x16x32_bf16 v[0:3], v[176:179], v[210:213], v[0:3]
	s_barrier
	s_add_i32 s33, s33, 2
	s_add_u32 s3, s3, 0x100
	s_addc_u32 s7, s7, 0
	s_cmp_gt_u32 s33, 9
	s_mov_b64 s[58:59], s[60:61]
	s_cbranch_scc0 .LBB0_650
	s_and_b64 vcc, exec, s[30:31]
	s_cbranch_vccz .LBB0_653
	s_barrier

.LBB0_657:
	s_setprio 0
	s_mov_b32 s6, s101
	s_waitcnt vmcnt(0)
	s_waitcnt vmcnt(0)
	s_barrier
	s_and_saveexec_b64 s[8:9], s[80:81]
	s_cbranch_execz .LBB0_709
	v_readlane_b32 s98, v248, 1
	v_readlane_b32 s99, v248, 2
	v_mov_b32_e32 v0, 0x20ff0
	ds_read2_b32 v[2:3], v0 offset1:1
	v_mov_b32_e32 v1, 1
	v_mov_b32_e32 v4, s97
	v_lshlrev_b32_e32 v4, 8, v4
	s_add_u32 s98, s98, 0x1000
	s_addc_u32 s99, s99, 0
	s_nop 2
	global_atomic_add v5, v4, v1, s[98:99] offset:1024 sc0
	s_waitcnt vmcnt(0) lgkmcnt(0)
	v_mul_u32_u24_e32 v2, 6, v2
	v_mul_u32_u24_e32 v3, 6, v3
	v_add_u32_e32 v5, 1, v5
	v_cmp_ne_u32_e32 vcc, v5, v2
	v_mov_b32_e32 v6, 0x2400
	s_cbranch_vccnz .Lxb5_poll
	buffer_wbl2 sc1
	s_waitcnt vmcnt(0)
	global_atomic_add v6, v1, s[98:99]

.LBB0_714:
	v_ashrrev_i32_e32 v1, 31, v8
	v_lshrrev_b32_e32 v1, 26, v1
	v_add_u32_e32 v1, v8, v1
	v_ashrrev_i32_e32 v9, 6, v1
	v_bfe_i32 v1, v8, 27, 1
	v_lshlrev_b32_e32 v0, 4, v8
	v_lshrrev_b32_e32 v1, 22, v1
	v_add_u32_e32 v1, v0, v1
	v_and_b32_e32 v1, 0xfffffc00, v1
	v_sub_u32_e32 v1, v0, v1
	v_lshrrev_b32_e32 v2, 4, v1
	v_bitop3_b32 v1, v2, v1, 32 bitop3:0x6c
	v_ashrrev_i32_e32 v3, 31, v1
	v_lshrrev_b32_e32 v3, 26, v3
	v_add_u32_e32 v3, v1, v3
	v_lshlrev_b32_e32 v2, 3, v9
	v_ashrrev_i32_e32 v10, 6, v3
	v_and_b32_e32 v3, 0xc0, v3
	v_and_b32_e32 v2, -16, v2
	v_sub_u32_e32 v1, v1, v3
	v_mov_b32_e32 v3, 1
	v_add_u32_e32 v2, v10, v2
	v_ashrrev_i16_sdwa v1, v3, sext(v1) dst_sel:DWORD dst_unused:UNUSED_PAD src0_sel:DWORD src1_sel:BYTE_0
	v_lshlrev_b32_e32 v4, 5, v9
	v_bfe_i32 v11, v1, 0, 16
	v_lshlrev_b32_e32 v1, 1, v2
	v_lshrrev_b32_e32 v5, 2, v2
	v_and_b32_e32 v6, 3, v10
	s_mov_b32 s1, 0x3fffe0
	v_and_b32_e32 v4, 32, v4
	v_and_b32_e32 v1, 24, v1
	v_and_b32_e32 v5, 4, v5
	v_and_or_b32 v6, v2, s1, v6
	s_ashr_i32 s7, s7, 3
	v_or3_b32 v1, v6, v5, v1
	v_add_lshl_u32 v4, v4, v11, 1
	v_add_u32_e32 v0, 0x2000, v0
	v_lshl_add_u32 v166, v1, 10, v4
	v_ashrrev_i32_e32 v1, 31, v0
	s_add_i32 s3, s3, s7
	v_lshrrev_b32_e32 v1, 22, v1
	s_ashr_i32 s7, s3, 31
	v_add_u32_e32 v1, v0, v1
	s_lshr_b32 s7, s7, 28
	v_ashrrev_i32_e32 v12, 10, v1
	s_add_i32 s7, s3, s7
	v_mul_i32_i24_e32 v1, 0x400, v12
	s_and_b32 s8, s7, -16
	v_sub_u32_e32 v0, v0, v1
	s_sub_i32 s3, s3, s8
	v_lshrrev_b32_e32 v1, 4, v0
	s_bfe_i32 s8, s3, 0x80000
	v_bitop3_b32 v0, v1, v0, 32 bitop3:0x6c
	s_bfe_u32 s8, s8, 0x3000c
	v_lshl_add_u32 v164, v2, 10, v4
	v_ashrrev_i32_e32 v2, 31, v0
	s_add_i32 s8, s3, s8
	v_lshrrev_b32_e32 v2, 26, v2
	s_bfe_i32 s9, s8, 0x80000
	s_and_b32 s8, s8, 0xf8
	v_add_u32_e32 v2, v0, v2
	s_sub_i32 s3, s3, s8
	v_lshlrev_b32_e32 v1, 3, v12
	v_ashrrev_i32_e32 v13, 6, v2
	v_and_b32_e32 v2, 0xc0, v2
	s_sext_i32_i8 s3, s3
	s_lshl_b32 s7, s7, 7
	v_and_b32_e32 v1, -16, v1
	v_sub_u32_e32 v0, v0, v2
	s_and_b32 s7, s7, 0xfffff800
	s_lshl_b32 s3, s3, 8
	v_add_u32_e32 v1, v13, v1
	v_ashrrev_i16_sdwa v0, v3, sext(v0) dst_sel:DWORD dst_unused:UNUSED_PAD src0_sel:DWORD src1_sel:BYTE_0
	v_and_b32_e32 v3, 3, v13
	s_sext_i32_i16 s9, s9
	s_add_i32 s54, s3, s7
	v_and_or_b32 v3, v1, s1, v3
	s_ashr_i32 s1, s2, 6
	s_lshl_b32 s3, s9, 5
	s_ashr_i32 s55, s54, 31
	s_ashr_i32 s0, s2, 8
	s_lshl_b32 s65, s1, 10
	s_and_b32 s56, s3, 0xffffff00
	s_lshl_b64 s[8:9], s[54:55], 10
	s_add_u32 s58, s18, s8
	s_addc_u32 s59, s19, s9
	s_ashr_i32 s57, s56, 31
	s_lshl_b64 s[8:9], s[56:57], 10
	s_add_u32 s60, s4, s8
	v_lshlrev_b32_e32 v4, 5, v12
	v_bfe_i32 v14, v0, 0, 16
	v_lshlrev_b32_e32 v0, 1, v1
	v_lshrrev_b32_e32 v2, 2, v1
	s_addc_u32 s61, s5, s9
	s_add_i32 s55, s65, 0
	v_and_b32_e32 v4, 32, v4
	v_and_b32_e32 v0, 24, v0
	v_and_b32_e32 v2, 4, v2
	s_add_i32 m0, s55, 0x10000
	v_or3_b32 v0, v3, v2, v0
	v_add_lshl_u32 v2, v4, v14, 1
	global_load_lds_dwordx4 v166, s[60:61]
	s_add_i32 m0, s55, 0x12000
	v_lshl_add_u32 v170, v0, 10, v2
	s_add_u32 s8, s60, 0x20000
	global_load_lds_dwordx4 v170, s[60:61]
	s_addc_u32 s9, s61, 0
	s_add_i32 m0, s55, 0x14000
	s_add_i32 s57, s55, 0x2000
	global_load_lds_dwordx4 v166, s[8:9]
	s_add_i32 m0, s55, 0x16000
	v_lshl_add_u32 v168, v1, 10, v2
	global_load_lds_dwordx4 v170, s[8:9]
	s_mov_b32 m0, s55
	s_add_u32 s8, s58, 0x20000
	global_load_lds_dwordx4 v164, s[58:59]
	s_mov_b32 m0, s57
	s_addc_u32 s9, s59, 0
	s_add_i32 s66, s55, 0x4000
	global_load_lds_dwordx4 v168, s[58:59]
	s_mov_b32 m0, s66
	s_add_i32 s67, s55, 0x6000
	global_load_lds_dwordx4 v164, s[8:9]
	s_mov_b32 m0, s67
	v_mov_b32_e32 v167, 0
	global_load_lds_dwordx4 v168, s[8:9]
	v_mov_b32_e32 v171, v167
	v_mov_b32_e32 v165, v167
	v_mov_b32_e32 v169, v167
	s_cmp_eq_u32 s0, 1
	s_mov_b32 s68, 0
	v_lshl_add_u64 v[6:7], s[60:61], 0, v[166:167]
	v_lshl_add_u64 v[4:5], s[60:61], 0, v[170:171]
	v_lshl_add_u64 v[0:1], s[58:59], 0, v[164:165]
	s_cselect_b64 s[8:9], -1, 0
	s_cmp_lg_u32 s0, 1
	v_lshl_add_u64 v[2:3], s[58:59], 0, v[168:169]
	s_cbranch_scc1 .LBB0_716
	s_setprio 1
	s_barrier

.LBB0_726:
	ds_read_b128 v[64:67], v195
	ds_read_b128 v[72:75], v195 offset:1024
	ds_read_b128 v[80:83], v195 offset:2048
	ds_read_b128 v[84:87], v195 offset:3072
	ds_read_b128 v[144:147], v196
	ds_read_b128 v[148:151], v196 offset:1024
	ds_read_b128 v[152:155], v196 offset:2048
	ds_read_b128 v[156:159], v196 offset:3072
	s_add_u32 s35, s58, 0xfffe0080
	s_addc_u32 s43, s59, -1
	s_cmp_eq_u32 s34, 4
	s_cselect_b32 s63, s49, s43
	s_cselect_b32 s62, s48, s35
	s_cselect_b32 s61, s51, s33
	s_cselect_b32 s60, s50, s7
	v_lshl_add_u64 v[188:189], s[58:59], 0, v[172:173]
	s_add_i32 m0, s55, 0xc000
	ds_read_b128 v[160:163], v197
	ds_read_b128 v[180:183], v197 offset:1024
	ds_read_b128 v[184:187], v197 offset:2048
	ds_read_b128 v[198:201], v197 offset:3072
	ds_read_b128 v[202:205], v197 offset:4096
	ds_read_b128 v[206:209], v197 offset:5120
	ds_read_b128 v[210:213], v197 offset:6144
	ds_read_b128 v[214:217], v197 offset:7168
	global_load_lds_dwordx4 v[188:189], off
	v_lshl_add_u64 v[188:189], s[58:59], 0, v[174:175]
	s_add_i32 m0, s55, 0xe000
	s_nop 0
	global_load_lds_dwordx4 v[188:189], off
	s_waitcnt vmcnt(8)
	s_waitcnt lgkmcnt(0)
	s_barrier
	s_waitcnt lgkmcnt(0)
	v_mfma_f32_16x16x32_bf16 v[140:143], v[64:67], v[160:163], v[140:143]
	v_mfma_f32_16x16x32_bf16 v[136:139], v[80:83], v[160:163], v[136:139]
	v_mfma_f32_16x16x32_bf16 v[124:127], v[64:67], v[184:187], v[124:127]
	v_mfma_f32_16x16x32_bf16 v[120:123], v[80:83], v[184:187], v[120:123]
	v_mfma_f32_16x16x32_bf16 v[108:111], v[64:67], v[202:205], v[108:111]
	v_mfma_f32_16x16x32_bf16 v[104:107], v[80:83], v[202:205], v[104:107]
	v_mfma_f32_16x16x32_bf16 v[92:95], v[64:67], v[210:213], v[92:95]
	v_mfma_f32_16x16x32_bf16 v[88:91], v[80:83], v[210:213], v[88:91]
	v_mfma_f32_16x16x32_bf16 v[140:143], v[72:75], v[180:183], v[140:143]
	v_mfma_f32_16x16x32_bf16 v[136:139], v[84:87], v[180:183], v[136:139]
	v_mfma_f32_16x16x32_bf16 v[124:127], v[72:75], v[198:201], v[124:127]
	v_mfma_f32_16x16x32_bf16 v[120:123], v[84:87], v[198:201], v[120:123]
	v_mfma_f32_16x16x32_bf16 v[108:111], v[72:75], v[206:209], v[108:111]
	v_mfma_f32_16x16x32_bf16 v[104:107], v[84:87], v[206:209], v[104:107]
	v_mfma_f32_16x16x32_bf16 v[92:95], v[72:75], v[214:217], v[92:95]
	v_mfma_f32_16x16x32_bf16 v[88:91], v[84:87], v[214:217], v[88:91]
	v_mfma_f32_16x16x32_bf16 v[132:135], v[144:147], v[160:163], v[132:135]
	v_mfma_f32_16x16x32_bf16 v[128:131], v[152:155], v[160:163], v[128:131]
	v_mfma_f32_16x16x32_bf16 v[116:119], v[144:147], v[184:187], v[116:119]
	v_mfma_f32_16x16x32_bf16 v[112:115], v[152:155], v[184:187], v[112:115]
	v_mfma_f32_16x16x32_bf16 v[100:103], v[144:147], v[202:205], v[100:103]
	v_mfma_f32_16x16x32_bf16 v[96:99], v[152:155], v[202:205], v[96:99]
	v_mfma_f32_16x16x32_bf16 v[76:79], v[144:147], v[210:213], v[76:79]
	v_mfma_f32_16x16x32_bf16 v[68:71], v[152:155], v[210:213], v[68:71]
	v_mfma_f32_16x16x32_bf16 v[132:135], v[148:151], v[180:183], v[132:135]
	v_mfma_f32_16x16x32_bf16 v[128:131], v[156:159], v[180:183], v[128:131]
	v_mfma_f32_16x16x32_bf16 v[116:119], v[148:151], v[198:201], v[116:119]
	v_mfma_f32_16x16x32_bf16 v[112:115], v[156:159], v[198:201], v[112:115]
	v_mfma_f32_16x16x32_bf16 v[100:103], v[148:151], v[206:209], v[100:103]
	v_mfma_f32_16x16x32_bf16 v[96:99], v[156:159], v[206:209], v[96:99]
	v_mfma_f32_16x16x32_bf16 v[76:79], v[148:151], v[214:217], v[76:79]
	v_mfma_f32_16x16x32_bf16 v[68:71], v[156:159], v[214:217], v[68:71]
	s_barrier
	s_add_i32 s35, s2, s65
	v_lshl_add_u64 v[188:189], s[60:61], 0, v[166:167]
	s_mov_b32 m0, s35
	ds_read_b128 v[160:163], v197 offset:16384
	ds_read_b128 v[180:183], v197 offset:17408
	ds_read_b128 v[184:187], v197 offset:18432
	ds_read_b128 v[198:201], v197 offset:19456
	ds_read_b128 v[202:205], v197 offset:20480
	ds_read_b128 v[206:209], v197 offset:21504
	ds_read_b128 v[210:213], v197 offset:22528
	ds_read_b128 v[214:217], v197 offset:23552
	global_load_lds_dwordx4 v[188:189], off
	s_add_i32 m0, s35, 0x2000
	s_add_u32 s74, s60, 0x20000
	v_lshl_add_u64 v[218:219], s[60:61], 0, v[170:171]
	s_addc_u32 s75, s61, 0
	s_add_i32 s35, s3, s65
	global_load_lds_dwordx4 v[218:219], off
	v_lshl_add_u64 v[220:221], s[74:75], 0, v[166:167]
	s_mov_b32 m0, s35
	v_lshl_add_u64 v[222:223], s[62:63], 0, v[168:169]
	global_load_lds_dwordx4 v[220:221], off
	v_lshl_add_u64 v[220:221], s[74:75], 0, v[170:171]
	s_add_i32 m0, s35, 0x2000
	s_nop 0
	global_load_lds_dwordx4 v[220:221], off
	v_lshl_add_u64 v[220:221], s[62:63], 0, v[164:165]
	s_mov_b32 m0, s55
	s_nop 0
	global_load_lds_dwordx4 v[220:221], off
	s_mov_b32 m0, s57
	s_nop 0
	global_load_lds_dwordx4 v[222:223], off
	s_waitcnt vmcnt(8)
	s_waitcnt lgkmcnt(0)
	s_barrier
	s_waitcnt lgkmcnt(0)
	v_mfma_f32_16x16x32_bf16 v[60:63], v[64:67], v[160:163], v[60:63]
	v_mfma_f32_16x16x32_bf16 v[56:59], v[80:83], v[160:163], v[56:59]
	v_mfma_f32_16x16x32_bf16 v[44:47], v[64:67], v[184:187], v[44:47]
	v_mfma_f32_16x16x32_bf16 v[40:43], v[80:83], v[184:187], v[40:43]
	v_mfma_f32_16x16x32_bf16 v[28:31], v[64:67], v[202:205], v[28:31]
	v_mfma_f32_16x16x32_bf16 v[20:23], v[80:83], v[202:205], v[20:23]
	v_mfma_f32_16x16x32_bf16 v[8:11], v[64:67], v[210:213], v[8:11]
	v_mfma_f32_16x16x32_bf16 v[0:3], v[80:83], v[210:213], v[0:3]
	v_mfma_f32_16x16x32_bf16 v[60:63], v[72:75], v[180:183], v[60:63]
	v_mfma_f32_16x16x32_bf16 v[56:59], v[84:87], v[180:183], v[56:59]
	v_mfma_f32_16x16x32_bf16 v[44:47], v[72:75], v[198:201], v[44:47]
	v_mfma_f32_16x16x32_bf16 v[40:43], v[84:87], v[198:201], v[40:43]
	v_mfma_f32_16x16x32_bf16 v[28:31], v[72:75], v[206:209], v[28:31]
	v_mfma_f32_16x16x32_bf16 v[20:23], v[84:87], v[206:209], v[20:23]
	v_mfma_f32_16x16x32_bf16 v[8:11], v[72:75], v[214:217], v[8:11]
	v_mfma_f32_16x16x32_bf16 v[0:3], v[84:87], v[214:217], v[0:3]
	v_mfma_f32_16x16x32_bf16 v[52:55], v[144:147], v[160:163], v[52:55]
	v_mfma_f32_16x16x32_bf16 v[48:51], v[152:155], v[160:163], v[48:51]
	v_mfma_f32_16x16x32_bf16 v[36:39], v[144:147], v[184:187], v[36:39]
	v_mfma_f32_16x16x32_bf16 v[32:35], v[152:155], v[184:187], v[32:35]
	v_mfma_f32_16x16x32_bf16 v[24:27], v[144:147], v[202:205], v[24:27]
	v_mfma_f32_16x16x32_bf16 v[16:19], v[152:155], v[202:205], v[16:19]
	v_mfma_f32_16x16x32_bf16 v[12:15], v[144:147], v[210:213], v[12:15]
	v_mfma_f32_16x16x32_bf16 v[4:7], v[152:155], v[210:213], v[4:7]
	v_mfma_f32_16x16x32_bf16 v[52:55], v[148:151], v[180:183], v[52:55]
	v_mfma_f32_16x16x32_bf16 v[48:51], v[156:159], v[180:183], v[48:51]
	v_mfma_f32_16x16x32_bf16 v[36:39], v[148:151], v[198:201], v[36:39]
	v_mfma_f32_16x16x32_bf16 v[32:35], v[156:159], v[198:201], v[32:35]
	v_mfma_f32_16x16x32_bf16 v[24:27], v[148:151], v[206:209], v[24:27]
	v_mfma_f32_16x16x32_bf16 v[16:19], v[156:159], v[206:209], v[16:19]
	v_mfma_f32_16x16x32_bf16 v[12:15], v[148:151], v[214:217], v[12:15]
	v_mfma_f32_16x16x32_bf16 v[4:7], v[156:159], v[214:217], v[4:7]
	s_barrier
	s_add_i32 s35, 0, 0x18000
	s_add_i32 s43, 0, 0x1c000
	v_add_u32_e32 v84, s35, v191
	v_add_u32_e32 v156, s43, v191
	ds_read_b128 v[64:67], v84
	ds_read_b128 v[72:75], v84 offset:1024
	ds_read_b128 v[80:83], v84 offset:2048
	ds_read_b128 v[84:87], v84 offset:3072
	ds_read_b128 v[144:147], v156
	ds_read_b128 v[148:151], v156 offset:1024
	ds_read_b128 v[152:155], v156 offset:2048
	ds_read_b128 v[156:159], v156 offset:3072
	s_add_u32 s62, s62, 0x20000
	s_addc_u32 s63, s63, 0
	s_mov_b32 m0, s66
	v_lshl_add_u64 v[224:225], s[62:63], 0, v[164:165]
	ds_read_b128 v[160:163], v197 offset:32768
	ds_read_b128 v[180:183], v197 offset:33792
	ds_read_b128 v[184:187], v197 offset:34816
	ds_read_b128 v[198:201], v197 offset:35840
	ds_read_b128 v[202:205], v197 offset:36864
	ds_read_b128 v[206:209], v197 offset:37888
	ds_read_b128 v[210:213], v197 offset:38912
	ds_read_b128 v[214:217], v197 offset:39936
	global_load_lds_dwordx4 v[224:225], off
	v_lshl_add_u64 v[224:225], s[62:63], 0, v[168:169]
	s_mov_b32 m0, s67
	s_nop 0
	global_load_lds_dwordx4 v[224:225], off
	s_waitcnt vmcnt(8)
	s_waitcnt lgkmcnt(0)
	s_barrier
	s_waitcnt lgkmcnt(0)
	v_mfma_f32_16x16x32_bf16 v[140:143], v[64:67], v[160:163], v[140:143]
	v_mfma_f32_16x16x32_bf16 v[136:139], v[80:83], v[160:163], v[136:139]
	v_mfma_f32_16x16x32_bf16 v[124:127], v[64:67], v[184:187], v[124:127]
	v_mfma_f32_16x16x32_bf16 v[120:123], v[80:83], v[184:187], v[120:123]
	v_mfma_f32_16x16x32_bf16 v[108:111], v[64:67], v[202:205], v[108:111]
	v_mfma_f32_16x16x32_bf16 v[104:107], v[80:83], v[202:205], v[104:107]
	v_mfma_f32_16x16x32_bf16 v[92:95], v[64:67], v[210:213], v[92:95]
	v_mfma_f32_16x16x32_bf16 v[88:91], v[80:83], v[210:213], v[88:91]
	v_mfma_f32_16x16x32_bf16 v[140:143], v[72:75], v[180:183], v[140:143]
	v_mfma_f32_16x16x32_bf16 v[136:139], v[84:87], v[180:183], v[136:139]
	v_mfma_f32_16x16x32_bf16 v[124:127], v[72:75], v[198:201], v[124:127]
	v_mfma_f32_16x16x32_bf16 v[120:123], v[84:87], v[198:201], v[120:123]
	v_mfma_f32_16x16x32_bf16 v[108:111], v[72:75], v[206:209], v[108:111]
	v_mfma_f32_16x16x32_bf16 v[104:107], v[84:87], v[206:209], v[104:107]
	v_mfma_f32_16x16x32_bf16 v[92:95], v[72:75], v[214:217], v[92:95]
	v_mfma_f32_16x16x32_bf16 v[88:91], v[84:87], v[214:217], v[88:91]
	v_mfma_f32_16x16x32_bf16 v[132:135], v[144:147], v[160:163], v[132:135]
	v_mfma_f32_16x16x32_bf16 v[128:131], v[152:155], v[160:163], v[128:131]
	v_mfma_f32_16x16x32_bf16 v[116:119], v[144:147], v[184:187], v[116:119]
	v_mfma_f32_16x16x32_bf16 v[112:115], v[152:155], v[184:187], v[112:115]
	v_mfma_f32_16x16x32_bf16 v[100:103], v[144:147], v[202:205], v[100:103]
	v_mfma_f32_16x16x32_bf16 v[96:99], v[152:155], v[202:205], v[96:99]
	v_mfma_f32_16x16x32_bf16 v[76:79], v[144:147], v[210:213], v[76:79]
	v_mfma_f32_16x16x32_bf16 v[68:71], v[152:155], v[210:213], v[68:71]
	v_mfma_f32_16x16x32_bf16 v[132:135], v[148:151], v[180:183], v[132:135]
	v_mfma_f32_16x16x32_bf16 v[128:131], v[156:159], v[180:183], v[128:131]
	v_mfma_f32_16x16x32_bf16 v[116:119], v[148:151], v[198:201], v[116:119]
	v_mfma_f32_16x16x32_bf16 v[112:115], v[156:159], v[198:201], v[112:115]
	v_mfma_f32_16x16x32_bf16 v[100:103], v[148:151], v[206:209], v[100:103]
	v_mfma_f32_16x16x32_bf16 v[96:99], v[156:159], v[206:209], v[96:99]
	v_mfma_f32_16x16x32_bf16 v[76:79], v[148:151], v[214:217], v[76:79]
	v_mfma_f32_16x16x32_bf16 v[68:71], v[156:159], v[214:217], v[68:71]
	s_barrier
	s_add_i32 s35, s35, s65
	v_lshl_add_u64 v[188:189], v[188:189], 0, s[10:11]
	s_mov_b32 m0, s35
	ds_read_b128 v[160:163], v197 offset:49152
	ds_read_b128 v[180:183], v197 offset:50176
	ds_read_b128 v[184:187], v197 offset:51200
	ds_read_b128 v[198:201], v197 offset:52224
	ds_read_b128 v[202:205], v197 offset:53248
	ds_read_b128 v[206:209], v197 offset:54272
	ds_read_b128 v[210:213], v197 offset:55296
	ds_read_b128 v[214:217], v197 offset:56320
	global_load_lds_dwordx4 v[188:189], off
	s_add_i32 m0, s35, 0x2000
	s_add_u32 s60, s60, 0x20080
	v_lshl_add_u64 v[188:189], v[218:219], 0, s[10:11]
	s_addc_u32 s61, s61, 0
	s_add_i32 s35, s43, s65
	global_load_lds_dwordx4 v[188:189], off
	v_lshl_add_u64 v[188:189], s[60:61], 0, v[166:167]
	s_mov_b32 m0, s35
	s_nop 0
	global_load_lds_dwordx4 v[188:189], off
	v_lshl_add_u64 v[188:189], s[60:61], 0, v[170:171]
	s_add_i32 m0, s35, 0x2000
	s_nop 0
	global_load_lds_dwordx4 v[188:189], off
	v_lshl_add_u64 v[188:189], v[220:221], 0, s[10:11]
	s_mov_b32 m0, s69
	s_nop 0
	global_load_lds_dwordx4 v[188:189], off
	v_lshl_add_u64 v[188:189], v[222:223], 0, s[10:11]
	s_mov_b32 m0, s70
	s_nop 0
	global_load_lds_dwordx4 v[188:189], off
	s_waitcnt vmcnt(8)
	s_waitcnt lgkmcnt(0)
	s_barrier
	s_waitcnt lgkmcnt(0)
	v_mfma_f32_16x16x32_bf16 v[60:63], v[64:67], v[160:163], v[60:63]
	v_mfma_f32_16x16x32_bf16 v[56:59], v[80:83], v[160:163], v[56:59]
	v_mfma_f32_16x16x32_bf16 v[44:47], v[64:67], v[184:187], v[44:47]
	v_mfma_f32_16x16x32_bf16 v[40:43], v[80:83], v[184:187], v[40:43]
	v_mfma_f32_16x16x32_bf16 v[28:31], v[64:67], v[202:205], v[28:31]
	v_mfma_f32_16x16x32_bf16 v[20:23], v[80:83], v[202:205], v[20:23]
	v_mfma_f32_16x16x32_bf16 v[8:11], v[64:67], v[210:213], v[8:11]
	v_mfma_f32_16x16x32_bf16 v[0:3], v[80:83], v[210:213], v[0:3]
	v_mfma_f32_16x16x32_bf16 v[60:63], v[72:75], v[180:183], v[60:63]
	v_mfma_f32_16x16x32_bf16 v[56:59], v[84:87], v[180:183], v[56:59]
	v_mfma_f32_16x16x32_bf16 v[44:47], v[72:75], v[198:201], v[44:47]
	v_mfma_f32_16x16x32_bf16 v[40:43], v[84:87], v[198:201], v[40:43]
	v_mfma_f32_16x16x32_bf16 v[28:31], v[72:75], v[206:209], v[28:31]
	v_mfma_f32_16x16x32_bf16 v[20:23], v[84:87], v[206:209], v[20:23]
	v_mfma_f32_16x16x32_bf16 v[8:11], v[72:75], v[214:217], v[8:11]
	v_mfma_f32_16x16x32_bf16 v[0:3], v[84:87], v[214:217], v[0:3]
	v_mfma_f32_16x16x32_bf16 v[52:55], v[144:147], v[160:163], v[52:55]
	v_mfma_f32_16x16x32_bf16 v[48:51], v[152:155], v[160:163], v[48:51]
	v_mfma_f32_16x16x32_bf16 v[36:39], v[144:147], v[184:187], v[36:39]
	v_mfma_f32_16x16x32_bf16 v[32:35], v[152:155], v[184:187], v[32:35]
	v_mfma_f32_16x16x32_bf16 v[24:27], v[144:147], v[202:205], v[24:27]
	v_mfma_f32_16x16x32_bf16 v[16:19], v[152:155], v[202:205], v[16:19]
	v_mfma_f32_16x16x32_bf16 v[12:15], v[144:147], v[210:213], v[12:15]
	v_mfma_f32_16x16x32_bf16 v[4:7], v[152:155], v[210:213], v[4:7]
	v_mfma_f32_16x16x32_bf16 v[52:55], v[148:151], v[180:183], v[52:55]
	v_mfma_f32_16x16x32_bf16 v[48:51], v[156:159], v[180:183], v[48:51]
	v_mfma_f32_16x16x32_bf16 v[36:39], v[148:151], v[198:201], v[36:39]
	v_mfma_f32_16x16x32_bf16 v[32:35], v[156:159], v[198:201], v[32:35]
	v_mfma_f32_16x16x32_bf16 v[24:27], v[148:151], v[206:209], v[24:27]
	v_mfma_f32_16x16x32_bf16 v[16:19], v[156:159], v[206:209], v[16:19]
	v_mfma_f32_16x16x32_bf16 v[12:15], v[148:151], v[214:217], v[12:15]
	v_mfma_f32_16x16x32_bf16 v[4:7], v[156:159], v[214:217], v[4:7]
	s_barrier
	s_add_i32 s34, s34, 2
	s_add_u32 s58, s58, 0x100
	s_addc_u32 s59, s59, 0
	s_add_u32 s7, s7, 0x100
	s_addc_u32 s33, s33, 0
	s_cmp_gt_u32 s34, 5
	s_cbranch_scc0 .LBB0_726
	s_and_b64 vcc, exec, s[30:31]
	s_cbranch_vccz .LBB0_729
	s_barrier

.LBB0_733:
	s_setprio 0
	s_waitcnt vmcnt(0)
	s_barrier
	s_and_saveexec_b64 s[0:1], s[80:81]
	s_cbranch_execz .LBB0_785
	v_readlane_b32 s98, v248, 1
	v_readlane_b32 s99, v248, 2
	v_mov_b32_e32 v0, 0x20ff0
	ds_read2_b32 v[2:3], v0 offset1:1
	v_mov_b32_e32 v1, 1
	v_mov_b32_e32 v4, s97
	v_lshlrev_b32_e32 v4, 8, v4
	s_add_u32 s98, s98, 0x1000
	s_addc_u32 s99, s99, 0
	s_nop 2
	global_atomic_add v5, v4, v1, s[98:99] offset:1024 sc0
	s_waitcnt vmcnt(0) lgkmcnt(0)
	v_mul_u32_u24_e32 v2, 7, v2
	v_mul_u32_u24_e32 v3, 7, v3
	v_add_u32_e32 v5, 1, v5
	v_cmp_ne_u32_e32 vcc, v5, v2
	v_mov_b32_e32 v6, 0x2400
	s_cbranch_vccnz .Lxb6_poll
	buffer_wbl2 sc1
	s_waitcnt vmcnt(0)
	global_atomic_add v6, v1, s[98:99]

.LBB0_792:
	v_ashrrev_i32_e32 v1, 31, v8
	v_lshrrev_b32_e32 v1, 26, v1
	v_add_u32_e32 v1, v8, v1
	v_ashrrev_i32_e32 v9, 6, v1
	v_bfe_i32 v1, v8, 27, 1
	v_lshlrev_b32_e32 v0, 4, v8
	v_lshrrev_b32_e32 v1, 22, v1
	v_add_u32_e32 v1, v0, v1
	v_and_b32_e32 v1, 0xfffffc00, v1
	v_sub_u32_e32 v1, v0, v1
	v_lshrrev_b32_e32 v2, 4, v1
	v_bitop3_b32 v1, v2, v1, 32 bitop3:0x6c
	v_ashrrev_i32_e32 v3, 31, v1
	v_lshrrev_b32_e32 v3, 26, v3
	v_add_u32_e32 v3, v1, v3
	v_lshlrev_b32_e32 v2, 3, v9
	v_ashrrev_i32_e32 v10, 6, v3
	v_and_b32_e32 v3, 0xc0, v3
	v_and_b32_e32 v2, -16, v2
	v_sub_u32_e32 v1, v1, v3
	v_mov_b32_e32 v3, 1
	v_add_u32_e32 v2, v10, v2
	v_ashrrev_i16_sdwa v1, v3, sext(v1) dst_sel:DWORD dst_unused:UNUSED_PAD src0_sel:DWORD src1_sel:BYTE_0
	v_lshlrev_b32_e32 v4, 5, v9
	v_bfe_i32 v11, v1, 0, 16
	v_lshlrev_b32_e32 v1, 1, v2
	v_lshrrev_b32_e32 v5, 2, v2
	v_and_b32_e32 v6, 3, v10
	s_mov_b32 s1, 0x3fffe0
	v_and_b32_e32 v4, 32, v4
	v_and_b32_e32 v1, 24, v1
	v_and_b32_e32 v5, 4, v5
	v_and_or_b32 v6, v2, s1, v6
	v_or3_b32 v1, v6, v5, v1
	v_add_lshl_u32 v4, v4, v11, 1
	v_add_u32_e32 v0, 0x2000, v0
	v_lshl_add_u32 v196, v1, 10, v4
	v_ashrrev_i32_e32 v1, 31, v0
	v_lshrrev_b32_e32 v1, 22, v1
	v_add_u32_e32 v1, v0, v1
	v_ashrrev_i32_e32 v12, 10, v1
	v_mul_i32_i24_e32 v1, 0x400, v12
	v_sub_u32_e32 v0, v0, v1
	v_lshrrev_b32_e32 v1, 4, v0
	v_bitop3_b32 v0, v1, v0, 32 bitop3:0x6c
	v_lshl_add_u32 v194, v2, 10, v4
	v_ashrrev_i32_e32 v2, 31, v0
	v_lshrrev_b32_e32 v2, 26, v2
	v_add_u32_e32 v2, v0, v2
	v_lshlrev_b32_e32 v1, 3, v12
	v_ashrrev_i32_e32 v13, 6, v2
	v_and_b32_e32 v2, 0xc0, v2
	v_and_b32_e32 v1, -16, v1
	v_sub_u32_e32 v0, v0, v2
	v_add_u32_e32 v1, v13, v1
	v_ashrrev_i16_sdwa v0, v3, sext(v0) dst_sel:DWORD dst_unused:UNUSED_PAD src0_sel:DWORD src1_sel:BYTE_0
	v_and_b32_e32 v3, 3, v13
	v_and_or_b32 v3, v1, s1, v3
	s_ashr_i32 s1, s3, 6
	s_lshl_b32 s60, s1, 10
	v_lshlrev_b32_e32 v4, 5, v12
	v_bfe_i32 v14, v0, 0, 16
	v_lshlrev_b32_e32 v0, 1, v1
	v_lshrrev_b32_e32 v2, 2, v1
	s_add_i32 s61, s60, 0
	v_and_b32_e32 v4, 32, v4
	v_and_b32_e32 v0, 24, v0
	v_and_b32_e32 v2, 4, v2
	s_add_i32 m0, s61, 0x10000
	s_ashr_i32 s0, s3, 8
	v_or3_b32 v0, v3, v2, v0
	v_add_lshl_u32 v2, v4, v14, 1
	global_load_lds_dwordx4 v196, s[56:57]
	s_add_i32 m0, s61, 0x12000
	v_lshl_add_u32 v200, v0, 10, v2
	s_add_u32 s28, s56, 0x20000
	global_load_lds_dwordx4 v200, s[56:57]
	s_addc_u32 s29, s57, 0
	s_add_i32 m0, s61, 0x14000
	s_add_i32 s62, s61, 0x2000
	global_load_lds_dwordx4 v196, s[28:29]
	s_add_i32 m0, s61, 0x16000
	v_lshl_add_u32 v198, v1, 10, v2
	global_load_lds_dwordx4 v200, s[28:29]
	s_mov_b32 m0, s61
	s_add_u32 s28, s54, 0x20000
	global_load_lds_dwordx4 v194, s[54:55]
	s_mov_b32 m0, s62
	s_addc_u32 s29, s55, 0
	s_add_i32 s63, s61, 0x4000
	global_load_lds_dwordx4 v198, s[54:55]
	s_mov_b32 m0, s63
	s_add_i32 s64, s61, 0x6000
	global_load_lds_dwordx4 v194, s[28:29]
	s_mov_b32 m0, s64
	v_mov_b32_e32 v197, 0
	global_load_lds_dwordx4 v198, s[28:29]
	v_mov_b32_e32 v201, v197
	v_mov_b32_e32 v195, v197
	v_mov_b32_e32 v199, v197
	s_cmp_eq_u32 s0, 1
	s_mov_b32 s2, 0
	v_lshl_add_u64 v[6:7], s[56:57], 0, v[196:197]
	v_lshl_add_u64 v[4:5], s[56:57], 0, v[200:201]
	v_lshl_add_u64 v[0:1], s[54:55], 0, v[194:195]
	s_cselect_b64 s[28:29], -1, 0
	s_cmp_lg_u32 s0, 1
	v_lshl_add_u64 v[2:3], s[54:55], 0, v[198:199]
	s_cbranch_scc1 .LBB0_794
	s_setprio 1
	s_barrier

.LBB0_804:
	v_add_u32_e32 v140, s70, v228
	v_add_u32_e32 v156, s71, v228
	ds_read_b128 v[128:131], v140
	ds_read_b128 v[132:135], v140 offset:1024
	ds_read_b128 v[136:139], v140 offset:2048
	ds_read_b128 v[140:143], v140 offset:3072
	ds_read_b128 v[144:147], v156
	ds_read_b128 v[148:151], v156 offset:1024
	ds_read_b128 v[152:155], v156 offset:2048
	ds_read_b128 v[156:159], v156 offset:3072
	s_add_u32 s9, s54, 0xfffe0080
	s_addc_u32 s33, s55, -1
	s_cmp_eq_u32 s7, 4
	s_cselect_b32 s59, s51, s33
	s_cselect_b32 s58, s50, s9
	s_cselect_b32 s57, s53, s5
	s_cselect_b32 s56, s52, s3
	v_lshl_add_u64 v[210:211], s[54:55], 0, v[202:203]
	s_add_i32 m0, s61, 0xc000
	ds_read_b128 v[160:163], v230
	ds_read_b128 v[164:167], v230 offset:1024
	ds_read_b128 v[168:171], v230 offset:2048
	ds_read_b128 v[172:175], v230 offset:3072
	ds_read_b128 v[176:179], v230 offset:4096
	ds_read_b128 v[180:183], v230 offset:5120
	ds_read_b128 v[184:187], v230 offset:6144
	ds_read_b128 v[188:191], v230 offset:7168
	global_load_lds_dwordx4 v[210:211], off
	v_lshl_add_u64 v[210:211], s[54:55], 0, v[204:205]
	s_add_i32 m0, s61, 0xe000
	s_nop 0
	global_load_lds_dwordx4 v[210:211], off
	s_waitcnt vmcnt(8)
	s_waitcnt lgkmcnt(0)
	s_barrier
	s_waitcnt lgkmcnt(0)
	v_mfma_f32_16x16x32_bf16 v[124:127], v[128:131], v[160:163], v[124:127]
	v_mfma_f32_16x16x32_bf16 v[120:123], v[136:139], v[160:163], v[120:123]
	v_mfma_f32_16x16x32_bf16 v[116:119], v[128:131], v[168:171], v[116:119]
	v_mfma_f32_16x16x32_bf16 v[112:115], v[136:139], v[168:171], v[112:115]
	v_mfma_f32_16x16x32_bf16 v[108:111], v[128:131], v[176:179], v[108:111]
	v_mfma_f32_16x16x32_bf16 v[104:107], v[136:139], v[176:179], v[104:107]
	v_mfma_f32_16x16x32_bf16 v[100:103], v[128:131], v[184:187], v[100:103]
	v_mfma_f32_16x16x32_bf16 v[96:99], v[136:139], v[184:187], v[96:99]
	v_mfma_f32_16x16x32_bf16 v[124:127], v[132:135], v[164:167], v[124:127]
	v_mfma_f32_16x16x32_bf16 v[120:123], v[140:143], v[164:167], v[120:123]
	v_mfma_f32_16x16x32_bf16 v[116:119], v[132:135], v[172:175], v[116:119]
	v_mfma_f32_16x16x32_bf16 v[112:115], v[140:143], v[172:175], v[112:115]
	v_mfma_f32_16x16x32_bf16 v[108:111], v[132:135], v[180:183], v[108:111]
	v_mfma_f32_16x16x32_bf16 v[104:107], v[140:143], v[180:183], v[104:107]
	v_mfma_f32_16x16x32_bf16 v[100:103], v[132:135], v[188:191], v[100:103]
	v_mfma_f32_16x16x32_bf16 v[96:99], v[140:143], v[188:191], v[96:99]
	v_mfma_f32_16x16x32_bf16 v[92:95], v[144:147], v[160:163], v[92:95]
	v_mfma_f32_16x16x32_bf16 v[88:91], v[152:155], v[160:163], v[88:91]
	v_mfma_f32_16x16x32_bf16 v[84:87], v[144:147], v[168:171], v[84:87]
	v_mfma_f32_16x16x32_bf16 v[80:83], v[152:155], v[168:171], v[80:83]
	v_mfma_f32_16x16x32_bf16 v[76:79], v[144:147], v[176:179], v[76:79]
	v_mfma_f32_16x16x32_bf16 v[72:75], v[152:155], v[176:179], v[72:75]
	v_mfma_f32_16x16x32_bf16 v[68:71], v[144:147], v[184:187], v[68:71]
	v_mfma_f32_16x16x32_bf16 v[64:67], v[152:155], v[184:187], v[64:67]
	v_mfma_f32_16x16x32_bf16 v[92:95], v[148:151], v[164:167], v[92:95]
	v_mfma_f32_16x16x32_bf16 v[88:91], v[156:159], v[164:167], v[88:91]
	v_mfma_f32_16x16x32_bf16 v[84:87], v[148:151], v[172:175], v[84:87]
	v_mfma_f32_16x16x32_bf16 v[80:83], v[156:159], v[172:175], v[80:83]
	v_mfma_f32_16x16x32_bf16 v[76:79], v[148:151], v[180:183], v[76:79]
	v_mfma_f32_16x16x32_bf16 v[72:75], v[156:159], v[180:183], v[72:75]
	v_mfma_f32_16x16x32_bf16 v[68:71], v[148:151], v[188:191], v[68:71]
	v_mfma_f32_16x16x32_bf16 v[64:67], v[156:159], v[188:191], v[64:67]
	s_barrier
	s_add_i32 s9, s70, s60
	v_lshl_add_u64 v[210:211], s[56:57], 0, v[196:197]
	s_mov_b32 m0, s9
	ds_read_b128 v[160:163], v230 offset:16384
	ds_read_b128 v[164:167], v230 offset:17408
	ds_read_b128 v[168:171], v230 offset:18432
	ds_read_b128 v[172:175], v230 offset:19456
	ds_read_b128 v[176:179], v230 offset:20480
	ds_read_b128 v[180:183], v230 offset:21504
	ds_read_b128 v[184:187], v230 offset:22528
	ds_read_b128 v[188:191], v230 offset:23552
	global_load_lds_dwordx4 v[210:211], off
	s_add_i32 m0, s9, 0x2000
	s_add_u32 s34, s56, 0x20000
	v_lshl_add_u64 v[212:213], s[56:57], 0, v[200:201]
	s_addc_u32 s35, s57, 0
	s_add_i32 s9, s71, s60
	global_load_lds_dwordx4 v[212:213], off
	v_lshl_add_u64 v[214:215], s[34:35], 0, v[196:197]
	s_mov_b32 m0, s9
	v_lshl_add_u64 v[216:217], s[58:59], 0, v[198:199]
	global_load_lds_dwordx4 v[214:215], off
	v_lshl_add_u64 v[214:215], s[34:35], 0, v[200:201]
	s_add_i32 m0, s9, 0x2000
	s_nop 0
	global_load_lds_dwordx4 v[214:215], off
	v_lshl_add_u64 v[214:215], s[58:59], 0, v[194:195]
	s_mov_b32 m0, s61
	s_nop 0
	global_load_lds_dwordx4 v[214:215], off
	s_mov_b32 m0, s62
	s_nop 0
	global_load_lds_dwordx4 v[216:217], off
	s_waitcnt vmcnt(8)
	s_waitcnt lgkmcnt(0)
	s_barrier
	s_waitcnt lgkmcnt(0)
	v_mfma_f32_16x16x32_bf16 v[60:63], v[128:131], v[160:163], v[60:63]
	v_mfma_f32_16x16x32_bf16 v[56:59], v[136:139], v[160:163], v[56:59]
	v_mfma_f32_16x16x32_bf16 v[52:55], v[128:131], v[168:171], v[52:55]
	v_mfma_f32_16x16x32_bf16 v[48:51], v[136:139], v[168:171], v[48:51]
	v_mfma_f32_16x16x32_bf16 v[44:47], v[128:131], v[176:179], v[44:47]
	v_mfma_f32_16x16x32_bf16 v[40:43], v[136:139], v[176:179], v[40:43]
	v_mfma_f32_16x16x32_bf16 v[36:39], v[128:131], v[184:187], v[36:39]
	v_mfma_f32_16x16x32_bf16 v[32:35], v[136:139], v[184:187], v[32:35]
	v_mfma_f32_16x16x32_bf16 v[60:63], v[132:135], v[164:167], v[60:63]
	v_mfma_f32_16x16x32_bf16 v[56:59], v[140:143], v[164:167], v[56:59]
	v_mfma_f32_16x16x32_bf16 v[52:55], v[132:135], v[172:175], v[52:55]
	v_mfma_f32_16x16x32_bf16 v[48:51], v[140:143], v[172:175], v[48:51]
	v_mfma_f32_16x16x32_bf16 v[44:47], v[132:135], v[180:183], v[44:47]
	v_mfma_f32_16x16x32_bf16 v[40:43], v[140:143], v[180:183], v[40:43]
	v_mfma_f32_16x16x32_bf16 v[36:39], v[132:135], v[188:191], v[36:39]
	v_mfma_f32_16x16x32_bf16 v[32:35], v[140:143], v[188:191], v[32:35]
	v_mfma_f32_16x16x32_bf16 v[28:31], v[144:147], v[160:163], v[28:31]
	v_mfma_f32_16x16x32_bf16 v[24:27], v[152:155], v[160:163], v[24:27]
	v_mfma_f32_16x16x32_bf16 v[20:23], v[144:147], v[168:171], v[20:23]
	v_mfma_f32_16x16x32_bf16 v[16:19], v[152:155], v[168:171], v[16:19]
	v_mfma_f32_16x16x32_bf16 v[12:15], v[144:147], v[176:179], v[12:15]
	v_mfma_f32_16x16x32_bf16 v[8:11], v[152:155], v[176:179], v[8:11]
	v_mfma_f32_16x16x32_bf16 v[4:7], v[144:147], v[184:187], v[4:7]
	v_mfma_f32_16x16x32_bf16 v[0:3], v[152:155], v[184:187], v[0:3]
	v_mfma_f32_16x16x32_bf16 v[28:31], v[148:151], v[164:167], v[28:31]
	v_mfma_f32_16x16x32_bf16 v[24:27], v[156:159], v[164:167], v[24:27]
	v_mfma_f32_16x16x32_bf16 v[20:23], v[148:151], v[172:175], v[20:23]
	v_mfma_f32_16x16x32_bf16 v[16:19], v[156:159], v[172:175], v[16:19]
	v_mfma_f32_16x16x32_bf16 v[12:15], v[148:151], v[180:183], v[12:15]
	v_mfma_f32_16x16x32_bf16 v[8:11], v[156:159], v[180:183], v[8:11]
	v_mfma_f32_16x16x32_bf16 v[4:7], v[148:151], v[188:191], v[4:7]
	v_mfma_f32_16x16x32_bf16 v[0:3], v[156:159], v[188:191], v[0:3]
	s_barrier
	s_add_i32 s9, 0, 0x18000
	s_add_i32 s33, 0, 0x1c000
	v_add_u32_e32 v140, s9, v228
	v_add_u32_e32 v156, s33, v228
	ds_read_b128 v[128:131], v140
	ds_read_b128 v[132:135], v140 offset:1024
	ds_read_b128 v[136:139], v140 offset:2048
	ds_read_b128 v[140:143], v140 offset:3072
	ds_read_b128 v[144:147], v156
	ds_read_b128 v[148:151], v156 offset:1024
	ds_read_b128 v[152:155], v156 offset:2048
	ds_read_b128 v[156:159], v156 offset:3072
	s_add_u32 s34, s58, 0x20000
	s_addc_u32 s35, s59, 0
	s_mov_b32 m0, s63
	v_lshl_add_u64 v[218:219], s[34:35], 0, v[194:195]
	ds_read_b128 v[160:163], v230 offset:32768
	ds_read_b128 v[164:167], v230 offset:33792
	ds_read_b128 v[168:171], v230 offset:34816
	ds_read_b128 v[172:175], v230 offset:35840
	ds_read_b128 v[176:179], v230 offset:36864
	ds_read_b128 v[180:183], v230 offset:37888
	ds_read_b128 v[184:187], v230 offset:38912
	ds_read_b128 v[188:191], v230 offset:39936
	global_load_lds_dwordx4 v[218:219], off
	v_lshl_add_u64 v[218:219], s[34:35], 0, v[198:199]
	s_mov_b32 m0, s64
	s_nop 0
	global_load_lds_dwordx4 v[218:219], off
	s_waitcnt vmcnt(8)
	s_waitcnt lgkmcnt(0)
	s_barrier
	s_waitcnt lgkmcnt(0)
	v_mfma_f32_16x16x32_bf16 v[124:127], v[128:131], v[160:163], v[124:127]
	v_mfma_f32_16x16x32_bf16 v[120:123], v[136:139], v[160:163], v[120:123]
	v_mfma_f32_16x16x32_bf16 v[116:119], v[128:131], v[168:171], v[116:119]
	v_mfma_f32_16x16x32_bf16 v[112:115], v[136:139], v[168:171], v[112:115]
	v_mfma_f32_16x16x32_bf16 v[108:111], v[128:131], v[176:179], v[108:111]
	v_mfma_f32_16x16x32_bf16 v[104:107], v[136:139], v[176:179], v[104:107]
	v_mfma_f32_16x16x32_bf16 v[100:103], v[128:131], v[184:187], v[100:103]
	v_mfma_f32_16x16x32_bf16 v[96:99], v[136:139], v[184:187], v[96:99]
	v_mfma_f32_16x16x32_bf16 v[124:127], v[132:135], v[164:167], v[124:127]
	v_mfma_f32_16x16x32_bf16 v[120:123], v[140:143], v[164:167], v[120:123]
	v_mfma_f32_16x16x32_bf16 v[116:119], v[132:135], v[172:175], v[116:119]
	v_mfma_f32_16x16x32_bf16 v[112:115], v[140:143], v[172:175], v[112:115]
	v_mfma_f32_16x16x32_bf16 v[108:111], v[132:135], v[180:183], v[108:111]
	v_mfma_f32_16x16x32_bf16 v[104:107], v[140:143], v[180:183], v[104:107]
	v_mfma_f32_16x16x32_bf16 v[100:103], v[132:135], v[188:191], v[100:103]
	v_mfma_f32_16x16x32_bf16 v[96:99], v[140:143], v[188:191], v[96:99]
	v_mfma_f32_16x16x32_bf16 v[92:95], v[144:147], v[160:163], v[92:95]
	v_mfma_f32_16x16x32_bf16 v[88:91], v[152:155], v[160:163], v[88:91]
	v_mfma_f32_16x16x32_bf16 v[84:87], v[144:147], v[168:171], v[84:87]
	v_mfma_f32_16x16x32_bf16 v[80:83], v[152:155], v[168:171], v[80:83]
	v_mfma_f32_16x16x32_bf16 v[76:79], v[144:147], v[176:179], v[76:79]
	v_mfma_f32_16x16x32_bf16 v[72:75], v[152:155], v[176:179], v[72:75]
	v_mfma_f32_16x16x32_bf16 v[68:71], v[144:147], v[184:187], v[68:71]
	v_mfma_f32_16x16x32_bf16 v[64:67], v[152:155], v[184:187], v[64:67]
	v_mfma_f32_16x16x32_bf16 v[92:95], v[148:151], v[164:167], v[92:95]
	v_mfma_f32_16x16x32_bf16 v[88:91], v[156:159], v[164:167], v[88:91]
	v_mfma_f32_16x16x32_bf16 v[84:87], v[148:151], v[172:175], v[84:87]
	v_mfma_f32_16x16x32_bf16 v[80:83], v[156:159], v[172:175], v[80:83]
	v_mfma_f32_16x16x32_bf16 v[76:79], v[148:151], v[180:183], v[76:79]
	v_mfma_f32_16x16x32_bf16 v[72:75], v[156:159], v[180:183], v[72:75]
	v_mfma_f32_16x16x32_bf16 v[68:71], v[148:151], v[188:191], v[68:71]
	v_mfma_f32_16x16x32_bf16 v[64:67], v[156:159], v[188:191], v[64:67]
	s_barrier
	s_add_i32 s9, s9, s60
	v_lshl_add_u64 v[210:211], v[210:211], 0, s[30:31]
	s_mov_b32 m0, s9
	ds_read_b128 v[160:163], v230 offset:49152
	ds_read_b128 v[164:167], v230 offset:50176
	ds_read_b128 v[168:171], v230 offset:51200
	ds_read_b128 v[172:175], v230 offset:52224
	ds_read_b128 v[176:179], v230 offset:53248
	ds_read_b128 v[180:183], v230 offset:54272
	ds_read_b128 v[184:187], v230 offset:55296
	ds_read_b128 v[188:191], v230 offset:56320
	global_load_lds_dwordx4 v[210:211], off
	s_add_i32 m0, s9, 0x2000
	s_add_u32 s34, s56, 0x20080
	v_lshl_add_u64 v[210:211], v[212:213], 0, s[30:31]
	s_addc_u32 s35, s57, 0
	s_add_i32 s9, s33, s60
	global_load_lds_dwordx4 v[210:211], off
	v_lshl_add_u64 v[210:211], s[34:35], 0, v[196:197]
	s_mov_b32 m0, s9
	s_nop 0
	global_load_lds_dwordx4 v[210:211], off
	v_lshl_add_u64 v[210:211], s[34:35], 0, v[200:201]
	s_add_i32 m0, s9, 0x2000
	s_nop 0
	global_load_lds_dwordx4 v[210:211], off
	v_lshl_add_u64 v[210:211], v[214:215], 0, s[30:31]
	s_mov_b32 m0, s67
	s_nop 0
	global_load_lds_dwordx4 v[210:211], off
	v_lshl_add_u64 v[210:211], v[216:217], 0, s[30:31]
	s_mov_b32 m0, s68
	s_nop 0
	global_load_lds_dwordx4 v[210:211], off
	s_waitcnt vmcnt(8)
	s_waitcnt lgkmcnt(0)
	s_barrier
	s_waitcnt lgkmcnt(0)
	v_mfma_f32_16x16x32_bf16 v[60:63], v[128:131], v[160:163], v[60:63]
	v_mfma_f32_16x16x32_bf16 v[56:59], v[136:139], v[160:163], v[56:59]
	v_mfma_f32_16x16x32_bf16 v[52:55], v[128:131], v[168:171], v[52:55]
	v_mfma_f32_16x16x32_bf16 v[48:51], v[136:139], v[168:171], v[48:51]
	v_mfma_f32_16x16x32_bf16 v[44:47], v[128:131], v[176:179], v[44:47]
	v_mfma_f32_16x16x32_bf16 v[40:43], v[136:139], v[176:179], v[40:43]
	v_mfma_f32_16x16x32_bf16 v[36:39], v[128:131], v[184:187], v[36:39]
	v_mfma_f32_16x16x32_bf16 v[32:35], v[136:139], v[184:187], v[32:35]
	v_mfma_f32_16x16x32_bf16 v[60:63], v[132:135], v[164:167], v[60:63]
	v_mfma_f32_16x16x32_bf16 v[56:59], v[140:143], v[164:167], v[56:59]
	v_mfma_f32_16x16x32_bf16 v[52:55], v[132:135], v[172:175], v[52:55]
	v_mfma_f32_16x16x32_bf16 v[48:51], v[140:143], v[172:175], v[48:51]
	v_mfma_f32_16x16x32_bf16 v[44:47], v[132:135], v[180:183], v[44:47]
	v_mfma_f32_16x16x32_bf16 v[40:43], v[140:143], v[180:183], v[40:43]
	v_mfma_f32_16x16x32_bf16 v[36:39], v[132:135], v[188:191], v[36:39]
	v_mfma_f32_16x16x32_bf16 v[32:35], v[140:143], v[188:191], v[32:35]
	v_mfma_f32_16x16x32_bf16 v[28:31], v[144:147], v[160:163], v[28:31]
	v_mfma_f32_16x16x32_bf16 v[24:27], v[152:155], v[160:163], v[24:27]
	v_mfma_f32_16x16x32_bf16 v[20:23], v[144:147], v[168:171], v[20:23]
	v_mfma_f32_16x16x32_bf16 v[16:19], v[152:155], v[168:171], v[16:19]
	v_mfma_f32_16x16x32_bf16 v[12:15], v[144:147], v[176:179], v[12:15]
	v_mfma_f32_16x16x32_bf16 v[8:11], v[152:155], v[176:179], v[8:11]
	v_mfma_f32_16x16x32_bf16 v[4:7], v[144:147], v[184:187], v[4:7]
	v_mfma_f32_16x16x32_bf16 v[0:3], v[152:155], v[184:187], v[0:3]
	v_mfma_f32_16x16x32_bf16 v[28:31], v[148:151], v[164:167], v[28:31]
	v_mfma_f32_16x16x32_bf16 v[24:27], v[156:159], v[164:167], v[24:27]
	v_mfma_f32_16x16x32_bf16 v[20:23], v[148:151], v[172:175], v[20:23]
	v_mfma_f32_16x16x32_bf16 v[16:19], v[156:159], v[172:175], v[16:19]
	v_mfma_f32_16x16x32_bf16 v[12:15], v[148:151], v[180:183], v[12:15]
	v_mfma_f32_16x16x32_bf16 v[8:11], v[156:159], v[180:183], v[8:11]
	v_mfma_f32_16x16x32_bf16 v[4:7], v[148:151], v[188:191], v[4:7]
	v_mfma_f32_16x16x32_bf16 v[0:3], v[156:159], v[188:191], v[0:3]
	s_barrier
	s_add_i32 s7, s7, 2
	s_add_u32 s54, s54, 0x100
	s_addc_u32 s55, s55, 0
	s_add_u32 s3, s3, 0x100
	s_addc_u32 s5, s5, 0
	s_cmp_gt_u32 s7, 5
	s_cbranch_scc0 .LBB0_804
	s_and_b64 vcc, exec, s[42:43]
	s_cbranch_vccz .LBB0_807
	s_barrier

.LBB0_909:
	s_setprio 0
	s_waitcnt vmcnt(0)
	s_barrier
	s_and_saveexec_b64 s[0:1], s[80:81]
	s_cbranch_execz .LBB0_961
	v_readlane_b32 s98, v248, 1
	v_readlane_b32 s99, v248, 2
	v_mov_b32_e32 v0, 0x20ff0
	ds_read2_b32 v[2:3], v0 offset1:1
	v_mov_b32_e32 v1, 1
	v_mov_b32_e32 v4, s97
	v_lshlrev_b32_e32 v4, 8, v4
	s_add_u32 s98, s98, 0x1000
	s_addc_u32 s99, s99, 0
	s_nop 2
	global_atomic_add v5, v4, v1, s[98:99] offset:1024 sc0
	s_waitcnt vmcnt(0) lgkmcnt(0)
	v_mul_u32_u24_e32 v2, 8, v2
	v_mul_u32_u24_e32 v3, 8, v3
	v_add_u32_e32 v5, 1, v5
	v_cmp_ne_u32_e32 vcc, v5, v2
	v_mov_b32_e32 v6, 0x2400
	s_cbranch_vccnz .Lxb7_poll
	buffer_wbl2 sc1
	s_waitcnt vmcnt(0)
	global_atomic_add v6, v1, s[98:99]

.LBB0_966:
	v_ashrrev_i32_e32 v1, 31, v8
	v_lshrrev_b32_e32 v1, 26, v1
	v_add_u32_e32 v1, v8, v1
	v_ashrrev_i32_e32 v9, 6, v1
	v_bfe_i32 v1, v8, 27, 1
	v_lshlrev_b32_e32 v0, 4, v8
	v_lshrrev_b32_e32 v1, 22, v1
	v_add_u32_e32 v1, v0, v1
	v_and_b32_e32 v1, 0xfffffc00, v1
	v_sub_u32_e32 v1, v0, v1
	v_lshrrev_b32_e32 v2, 4, v1
	v_bitop3_b32 v1, v2, v1, 32 bitop3:0x6c
	v_ashrrev_i32_e32 v3, 31, v1
	v_lshrrev_b32_e32 v3, 26, v3
	v_add_u32_e32 v3, v1, v3
	v_lshlrev_b32_e32 v2, 3, v9
	v_ashrrev_i32_e32 v10, 6, v3
	v_and_b32_e32 v3, 0xc0, v3
	v_and_b32_e32 v2, -16, v2
	v_sub_u32_e32 v1, v1, v3
	v_mov_b32_e32 v3, 1
	v_add_u32_e32 v2, v10, v2
	v_ashrrev_i16_sdwa v1, v3, sext(v1) dst_sel:DWORD dst_unused:UNUSED_PAD src0_sel:DWORD src1_sel:BYTE_0
	v_lshlrev_b32_e32 v4, 5, v9
	v_bfe_i32 v11, v1, 0, 16
	v_lshlrev_b32_e32 v1, 1, v2
	v_lshrrev_b32_e32 v5, 2, v2
	v_and_b32_e32 v6, 3, v10
	s_mov_b32 s1, 0x1fffe0
	v_and_b32_e32 v4, 32, v4
	v_and_b32_e32 v1, 24, v1
	v_and_b32_e32 v5, 4, v5
	v_and_or_b32 v6, v2, s1, v6
	s_ashr_i32 s5, s3, 3
	v_or3_b32 v1, v6, v5, v1
	v_add_lshl_u32 v4, v4, v11, 1
	v_add_u32_e32 v0, 0x2000, v0
	v_lshl_add_u32 v146, v1, 11, v4
	v_ashrrev_i32_e32 v1, 31, v0
	s_add_i32 s4, s4, s5
	v_lshrrev_b32_e32 v1, 22, v1
	s_ashr_i32 s5, s4, 31
	v_add_u32_e32 v1, v0, v1
	s_lshr_b32 s5, s5, 27
	v_ashrrev_i32_e32 v12, 10, v1
	s_add_i32 s5, s4, s5
	v_mul_i32_i24_e32 v1, 0x400, v12
	s_and_b32 s7, s5, 0xffffffe0
	v_sub_u32_e32 v0, v0, v1
	s_sub_i32 s4, s4, s7
	v_lshrrev_b32_e32 v1, 4, v0
	s_bfe_i32 s7, s4, 0x80000
	v_bitop3_b32 v0, v1, v0, 32 bitop3:0x6c
	s_bfe_u32 s7, s7, 0x3000c
	v_lshl_add_u32 v144, v2, 11, v4
	v_ashrrev_i32_e32 v2, 31, v0
	s_add_i32 s7, s4, s7
	v_lshrrev_b32_e32 v2, 26, v2
	s_bfe_i32 s8, s7, 0x80000
	s_and_b32 s7, s7, 0xf8
	v_add_u32_e32 v2, v0, v2
	s_sub_i32 s4, s4, s7
	v_lshlrev_b32_e32 v1, 3, v12
	v_ashrrev_i32_e32 v13, 6, v2
	v_and_b32_e32 v2, 0xc0, v2
	s_sext_i32_i8 s4, s4
	s_lshl_b32 s5, s5, 6
	v_and_b32_e32 v1, -16, v1
	v_sub_u32_e32 v0, v0, v2
	s_and_b32 s5, s5, 0xfffff800
	s_lshl_b32 s4, s4, 8
	v_add_u32_e32 v1, v13, v1
	v_ashrrev_i16_sdwa v0, v3, sext(v0) dst_sel:DWORD dst_unused:UNUSED_PAD src0_sel:DWORD src1_sel:BYTE_0
	v_and_b32_e32 v3, 3, v13
	s_sext_i32_i16 s8, s8
	s_add_i32 s40, s4, s5
	v_and_or_b32 v3, v1, s1, v3
	s_ashr_i32 s1, s24, 6
	s_lshl_b32 s4, s8, 5
	s_ashr_i32 s41, s40, 31
	s_ashr_i32 s0, s24, 8
	s_lshl_b32 s3, s1, 10
	s_and_b32 s42, s4, 0xffffff00
	s_lshl_b64 s[4:5], s[40:41], 11
	s_add_u32 s44, s20, s4
	s_addc_u32 s45, s21, s5
	s_ashr_i32 s43, s42, 31
	s_lshl_b64 s[4:5], s[42:43], 11
	s_add_u32 s48, s12, s4
	v_lshlrev_b32_e32 v4, 5, v12
	v_bfe_i32 v14, v0, 0, 16
	v_lshlrev_b32_e32 v0, 1, v1
	v_lshrrev_b32_e32 v2, 2, v1
	s_addc_u32 s49, s13, s5
	s_add_i32 s7, s3, 0
	v_and_b32_e32 v4, 32, v4
	v_and_b32_e32 v0, 24, v0
	v_and_b32_e32 v2, 4, v2
	s_add_i32 m0, s7, 0x10000
	v_or3_b32 v0, v3, v2, v0
	v_add_lshl_u32 v2, v4, v14, 1
	global_load_lds_dwordx4 v146, s[48:49]
	s_add_i32 m0, s7, 0x12000
	v_lshl_add_u32 v150, v0, 11, v2
	s_add_u32 s4, s48, 0x40000
	global_load_lds_dwordx4 v150, s[48:49]
	s_addc_u32 s5, s49, 0
	s_add_i32 m0, s7, 0x14000
	s_add_i32 s33, s7, 0x2000
	global_load_lds_dwordx4 v146, s[4:5]
	s_add_i32 m0, s7, 0x16000
	v_lshl_add_u32 v148, v1, 11, v2
	global_load_lds_dwordx4 v150, s[4:5]
	s_mov_b32 m0, s7
	s_add_u32 s4, s44, 0x40000
	global_load_lds_dwordx4 v144, s[44:45]
	s_mov_b32 m0, s33
	s_addc_u32 s5, s45, 0
	s_add_i32 s34, s7, 0x4000
	global_load_lds_dwordx4 v148, s[44:45]
	s_mov_b32 m0, s34
	s_add_i32 s35, s7, 0x6000
	global_load_lds_dwordx4 v144, s[4:5]
	s_mov_b32 m0, s35
	v_mov_b32_e32 v147, 0
	global_load_lds_dwordx4 v148, s[4:5]
	v_mov_b32_e32 v151, v147
	v_mov_b32_e32 v145, v147
	v_mov_b32_e32 v149, v147
	s_cmp_eq_u32 s0, 1
	s_mov_b32 s41, 0
	v_lshl_add_u64 v[6:7], s[48:49], 0, v[146:147]
	v_lshl_add_u64 v[4:5], s[48:49], 0, v[150:151]
	v_lshl_add_u64 v[0:1], s[44:45], 0, v[144:145]
	s_cselect_b64 s[4:5], -1, 0
	s_cmp_lg_u32 s0, 1
	v_lshl_add_u64 v[2:3], s[44:45], 0, v[148:149]
	s_cbranch_scc1 .LBB0_968
	s_setprio 1
	s_barrier

.LBB0_978:
	ds_read_b128 v[128:131], v169
	ds_read_b128 v[132:135], v169 offset:1024
	ds_read_b128 v[136:139], v169 offset:2048
	ds_read_b128 v[140:143], v169 offset:3072
	ds_read_b128 v[160:163], v170
	ds_read_b128 v[172:175], v170 offset:1024
	ds_read_b128 v[176:179], v170 offset:2048
	ds_read_b128 v[180:183], v170 offset:3072
	s_add_u32 s48, s44, 0xfffc0080
	s_addc_u32 s49, s45, -1
	s_cmp_eq_u32 s59, 12
	s_cselect_b32 s51, s31, s49
	s_cselect_b32 s50, s30, s48
	s_cselect_b32 s49, s39, s29
	s_cselect_b32 s48, s38, s27
	v_lshl_add_u64 v[164:165], s[44:45], 0, v[152:153]
	s_add_i32 m0, s7, 0xc000
	ds_read_b128 v[184:187], v171
	ds_read_b128 v[188:191], v171 offset:1024
	ds_read_b128 v[194:197], v171 offset:2048
	ds_read_b128 v[198:201], v171 offset:3072
	ds_read_b128 v[202:205], v171 offset:4096
	ds_read_b128 v[206:209], v171 offset:5120
	ds_read_b128 v[210:213], v171 offset:6144
	ds_read_b128 v[214:217], v171 offset:7168
	global_load_lds_dwordx4 v[164:165], off
	v_lshl_add_u64 v[164:165], s[44:45], 0, v[154:155]
	s_add_i32 m0, s7, 0xe000
	s_nop 0
	global_load_lds_dwordx4 v[164:165], off
	s_waitcnt vmcnt(8)
	s_waitcnt lgkmcnt(0)
	s_barrier
	s_waitcnt lgkmcnt(0)
	v_mfma_f32_16x16x32_bf16 v[124:127], v[128:131], v[184:187], v[124:127]
	v_mfma_f32_16x16x32_bf16 v[120:123], v[136:139], v[184:187], v[120:123]
	v_mfma_f32_16x16x32_bf16 v[116:119], v[128:131], v[194:197], v[116:119]
	v_mfma_f32_16x16x32_bf16 v[112:115], v[136:139], v[194:197], v[112:115]
	v_mfma_f32_16x16x32_bf16 v[92:95], v[128:131], v[202:205], v[92:95]
	v_mfma_f32_16x16x32_bf16 v[88:91], v[136:139], v[202:205], v[88:91]
	v_mfma_f32_16x16x32_bf16 v[84:87], v[128:131], v[210:213], v[84:87]
	v_mfma_f32_16x16x32_bf16 v[76:79], v[136:139], v[210:213], v[76:79]
	v_mfma_f32_16x16x32_bf16 v[124:127], v[132:135], v[188:191], v[124:127]
	v_mfma_f32_16x16x32_bf16 v[120:123], v[140:143], v[188:191], v[120:123]
	v_mfma_f32_16x16x32_bf16 v[116:119], v[132:135], v[198:201], v[116:119]
	v_mfma_f32_16x16x32_bf16 v[112:115], v[140:143], v[198:201], v[112:115]
	v_mfma_f32_16x16x32_bf16 v[92:95], v[132:135], v[206:209], v[92:95]
	v_mfma_f32_16x16x32_bf16 v[88:91], v[140:143], v[206:209], v[88:91]
	v_mfma_f32_16x16x32_bf16 v[84:87], v[132:135], v[214:217], v[84:87]
	v_mfma_f32_16x16x32_bf16 v[76:79], v[140:143], v[214:217], v[76:79]
	v_mfma_f32_16x16x32_bf16 v[108:111], v[160:163], v[184:187], v[108:111]
	v_mfma_f32_16x16x32_bf16 v[104:107], v[176:179], v[184:187], v[104:107]
	v_mfma_f32_16x16x32_bf16 v[100:103], v[160:163], v[194:197], v[100:103]
	v_mfma_f32_16x16x32_bf16 v[96:99], v[176:179], v[194:197], v[96:99]
	v_mfma_f32_16x16x32_bf16 v[80:83], v[160:163], v[202:205], v[80:83]
	v_mfma_f32_16x16x32_bf16 v[72:75], v[176:179], v[202:205], v[72:75]
	v_mfma_f32_16x16x32_bf16 v[68:71], v[160:163], v[210:213], v[68:71]
	v_mfma_f32_16x16x32_bf16 v[64:67], v[176:179], v[210:213], v[64:67]
	v_mfma_f32_16x16x32_bf16 v[108:111], v[172:175], v[188:191], v[108:111]
	v_mfma_f32_16x16x32_bf16 v[104:107], v[180:183], v[188:191], v[104:107]
	v_mfma_f32_16x16x32_bf16 v[100:103], v[172:175], v[198:201], v[100:103]
	v_mfma_f32_16x16x32_bf16 v[96:99], v[180:183], v[198:201], v[96:99]
	v_mfma_f32_16x16x32_bf16 v[80:83], v[172:175], v[206:209], v[80:83]
	v_mfma_f32_16x16x32_bf16 v[72:75], v[180:183], v[206:209], v[72:75]
	v_mfma_f32_16x16x32_bf16 v[68:71], v[172:175], v[214:217], v[68:71]
	v_mfma_f32_16x16x32_bf16 v[64:67], v[180:183], v[214:217], v[64:67]
	s_barrier
	s_add_i32 s60, s57, s3
	v_lshl_add_u64 v[164:165], s[48:49], 0, v[146:147]
	s_mov_b32 m0, s60
	ds_read_b128 v[184:187], v171 offset:16384
	ds_read_b128 v[188:191], v171 offset:17408
	ds_read_b128 v[194:197], v171 offset:18432
	ds_read_b128 v[198:201], v171 offset:19456
	ds_read_b128 v[202:205], v171 offset:20480
	ds_read_b128 v[206:209], v171 offset:21504
	ds_read_b128 v[210:213], v171 offset:22528
	ds_read_b128 v[214:217], v171 offset:23552
	global_load_lds_dwordx4 v[164:165], off
	s_add_i32 m0, s60, 0x2000
	s_add_u32 s60, s48, 0x40000
	v_lshl_add_u64 v[218:219], s[48:49], 0, v[150:151]
	s_addc_u32 s61, s49, 0
	s_add_i32 s62, s58, s3
	global_load_lds_dwordx4 v[218:219], off
	v_lshl_add_u64 v[220:221], s[60:61], 0, v[146:147]
	s_mov_b32 m0, s62
	v_lshl_add_u64 v[222:223], s[50:51], 0, v[148:149]
	global_load_lds_dwordx4 v[220:221], off
	v_lshl_add_u64 v[220:221], s[60:61], 0, v[150:151]
	s_add_i32 m0, s62, 0x2000
	s_nop 0
	global_load_lds_dwordx4 v[220:221], off
	v_lshl_add_u64 v[220:221], s[50:51], 0, v[144:145]
	s_mov_b32 m0, s7
	s_nop 0
	global_load_lds_dwordx4 v[220:221], off
	s_mov_b32 m0, s33
	s_nop 0
	global_load_lds_dwordx4 v[222:223], off
	s_waitcnt vmcnt(8)
	s_waitcnt lgkmcnt(0)
	s_barrier
	s_waitcnt lgkmcnt(0)
	v_mfma_f32_16x16x32_bf16 v[60:63], v[128:131], v[184:187], v[60:63]
	v_mfma_f32_16x16x32_bf16 v[56:59], v[136:139], v[184:187], v[56:59]
	v_mfma_f32_16x16x32_bf16 v[44:47], v[128:131], v[194:197], v[44:47]
	v_mfma_f32_16x16x32_bf16 v[36:39], v[136:139], v[194:197], v[36:39]
	v_mfma_f32_16x16x32_bf16 v[20:23], v[128:131], v[202:205], v[20:23]
	v_mfma_f32_16x16x32_bf16 v[12:15], v[136:139], v[202:205], v[12:15]
	v_mfma_f32_16x16x32_bf16 v[4:7], v[128:131], v[210:213], v[4:7]
	v_mfma_f32_16x16x32_bf16 v[0:3], v[136:139], v[210:213], v[0:3]
	v_mfma_f32_16x16x32_bf16 v[60:63], v[132:135], v[188:191], v[60:63]
	v_mfma_f32_16x16x32_bf16 v[56:59], v[140:143], v[188:191], v[56:59]
	v_mfma_f32_16x16x32_bf16 v[44:47], v[132:135], v[198:201], v[44:47]
	v_mfma_f32_16x16x32_bf16 v[36:39], v[140:143], v[198:201], v[36:39]
	v_mfma_f32_16x16x32_bf16 v[20:23], v[132:135], v[206:209], v[20:23]
	v_mfma_f32_16x16x32_bf16 v[12:15], v[140:143], v[206:209], v[12:15]
	v_mfma_f32_16x16x32_bf16 v[4:7], v[132:135], v[214:217], v[4:7]
	v_mfma_f32_16x16x32_bf16 v[0:3], v[140:143], v[214:217], v[0:3]
	v_mfma_f32_16x16x32_bf16 v[40:43], v[160:163], v[184:187], v[40:43]
	v_mfma_f32_16x16x32_bf16 v[32:35], v[176:179], v[184:187], v[32:35]
	v_mfma_f32_16x16x32_bf16 v[16:19], v[160:163], v[194:197], v[16:19]
	v_mfma_f32_16x16x32_bf16 v[8:11], v[176:179], v[194:197], v[8:11]
	v_mfma_f32_16x16x32_bf16 v[52:55], v[160:163], v[202:205], v[52:55]
	v_mfma_f32_16x16x32_bf16 v[48:51], v[176:179], v[202:205], v[48:51]
	v_mfma_f32_16x16x32_bf16 v[28:31], v[160:163], v[210:213], v[28:31]
	v_mfma_f32_16x16x32_bf16 v[24:27], v[176:179], v[210:213], v[24:27]
	v_mfma_f32_16x16x32_bf16 v[40:43], v[172:175], v[188:191], v[40:43]
	v_mfma_f32_16x16x32_bf16 v[32:35], v[180:183], v[188:191], v[32:35]
	v_mfma_f32_16x16x32_bf16 v[16:19], v[172:175], v[198:201], v[16:19]
	v_mfma_f32_16x16x32_bf16 v[8:11], v[180:183], v[198:201], v[8:11]
	v_mfma_f32_16x16x32_bf16 v[52:55], v[172:175], v[206:209], v[52:55]
	v_mfma_f32_16x16x32_bf16 v[48:51], v[180:183], v[206:209], v[48:51]
	v_mfma_f32_16x16x32_bf16 v[28:31], v[172:175], v[214:217], v[28:31]
	v_mfma_f32_16x16x32_bf16 v[24:27], v[180:183], v[214:217], v[24:27]
	s_barrier
	s_add_i32 s60, 0, 0x18000
	s_add_i32 s61, 0, 0x1c000
	v_add_u32_e32 v140, s60, v167
	v_add_u32_e32 v180, s61, v167
	ds_read_b128 v[128:131], v140
	ds_read_b128 v[132:135], v140 offset:1024
	ds_read_b128 v[136:139], v140 offset:2048
	ds_read_b128 v[140:143], v140 offset:3072
	ds_read_b128 v[160:163], v180
	ds_read_b128 v[172:175], v180 offset:1024
	ds_read_b128 v[176:179], v180 offset:2048
	ds_read_b128 v[180:183], v180 offset:3072
	s_add_u32 s50, s50, 0x40000
	s_addc_u32 s51, s51, 0
	s_mov_b32 m0, s34
	v_lshl_add_u64 v[224:225], s[50:51], 0, v[144:145]
	ds_read_b128 v[184:187], v171 offset:32768
	ds_read_b128 v[188:191], v171 offset:33792
	ds_read_b128 v[194:197], v171 offset:34816
	ds_read_b128 v[198:201], v171 offset:35840
	ds_read_b128 v[202:205], v171 offset:36864
	ds_read_b128 v[206:209], v171 offset:37888
	ds_read_b128 v[210:213], v171 offset:38912
	ds_read_b128 v[214:217], v171 offset:39936
	global_load_lds_dwordx4 v[224:225], off
	v_lshl_add_u64 v[224:225], s[50:51], 0, v[148:149]
	s_mov_b32 m0, s35
	s_nop 0
	global_load_lds_dwordx4 v[224:225], off
	s_waitcnt vmcnt(8)
	s_waitcnt lgkmcnt(0)
	s_barrier
	s_waitcnt lgkmcnt(0)
	v_mfma_f32_16x16x32_bf16 v[124:127], v[128:131], v[184:187], v[124:127]
	v_mfma_f32_16x16x32_bf16 v[120:123], v[136:139], v[184:187], v[120:123]
	v_mfma_f32_16x16x32_bf16 v[116:119], v[128:131], v[194:197], v[116:119]
	v_mfma_f32_16x16x32_bf16 v[112:115], v[136:139], v[194:197], v[112:115]
	v_mfma_f32_16x16x32_bf16 v[92:95], v[128:131], v[202:205], v[92:95]
	v_mfma_f32_16x16x32_bf16 v[88:91], v[136:139], v[202:205], v[88:91]
	v_mfma_f32_16x16x32_bf16 v[84:87], v[128:131], v[210:213], v[84:87]
	v_mfma_f32_16x16x32_bf16 v[76:79], v[136:139], v[210:213], v[76:79]
	v_mfma_f32_16x16x32_bf16 v[124:127], v[132:135], v[188:191], v[124:127]
	v_mfma_f32_16x16x32_bf16 v[120:123], v[140:143], v[188:191], v[120:123]
	v_mfma_f32_16x16x32_bf16 v[116:119], v[132:135], v[198:201], v[116:119]
	v_mfma_f32_16x16x32_bf16 v[112:115], v[140:143], v[198:201], v[112:115]
	v_mfma_f32_16x16x32_bf16 v[92:95], v[132:135], v[206:209], v[92:95]
	v_mfma_f32_16x16x32_bf16 v[88:91], v[140:143], v[206:209], v[88:91]
	v_mfma_f32_16x16x32_bf16 v[84:87], v[132:135], v[214:217], v[84:87]
	v_mfma_f32_16x16x32_bf16 v[76:79], v[140:143], v[214:217], v[76:79]
	v_mfma_f32_16x16x32_bf16 v[108:111], v[160:163], v[184:187], v[108:111]
	v_mfma_f32_16x16x32_bf16 v[104:107], v[176:179], v[184:187], v[104:107]
	v_mfma_f32_16x16x32_bf16 v[100:103], v[160:163], v[194:197], v[100:103]
	v_mfma_f32_16x16x32_bf16 v[96:99], v[176:179], v[194:197], v[96:99]
	v_mfma_f32_16x16x32_bf16 v[80:83], v[160:163], v[202:205], v[80:83]
	v_mfma_f32_16x16x32_bf16 v[72:75], v[176:179], v[202:205], v[72:75]
	v_mfma_f32_16x16x32_bf16 v[68:71], v[160:163], v[210:213], v[68:71]
	v_mfma_f32_16x16x32_bf16 v[64:67], v[176:179], v[210:213], v[64:67]
	v_mfma_f32_16x16x32_bf16 v[108:111], v[172:175], v[188:191], v[108:111]
	v_mfma_f32_16x16x32_bf16 v[104:107], v[180:183], v[188:191], v[104:107]
	v_mfma_f32_16x16x32_bf16 v[100:103], v[172:175], v[198:201], v[100:103]
	v_mfma_f32_16x16x32_bf16 v[96:99], v[180:183], v[198:201], v[96:99]
	v_mfma_f32_16x16x32_bf16 v[80:83], v[172:175], v[206:209], v[80:83]
	v_mfma_f32_16x16x32_bf16 v[72:75], v[180:183], v[206:209], v[72:75]
	v_mfma_f32_16x16x32_bf16 v[68:71], v[172:175], v[214:217], v[68:71]
	v_mfma_f32_16x16x32_bf16 v[64:67], v[180:183], v[214:217], v[64:67]
	s_barrier
	s_add_i32 s50, s60, s3
	v_lshl_add_u64 v[164:165], v[164:165], 0, s[8:9]
	s_mov_b32 m0, s50
	ds_read_b128 v[184:187], v171 offset:49152
	ds_read_b128 v[188:191], v171 offset:50176
	ds_read_b128 v[194:197], v171 offset:51200
	ds_read_b128 v[198:201], v171 offset:52224
	ds_read_b128 v[202:205], v171 offset:53248
	ds_read_b128 v[206:209], v171 offset:54272
	ds_read_b128 v[210:213], v171 offset:55296
	ds_read_b128 v[214:217], v171 offset:56320
	global_load_lds_dwordx4 v[164:165], off
	s_add_i32 m0, s50, 0x2000
	s_add_u32 s48, s48, 0x40080
	v_lshl_add_u64 v[164:165], v[218:219], 0, s[8:9]
	s_addc_u32 s49, s49, 0
	s_add_i32 s50, s61, s3
	global_load_lds_dwordx4 v[164:165], off
	v_lshl_add_u64 v[164:165], s[48:49], 0, v[146:147]
	s_mov_b32 m0, s50
	s_nop 0
	global_load_lds_dwordx4 v[164:165], off
	v_lshl_add_u64 v[164:165], s[48:49], 0, v[150:151]
	s_add_i32 m0, s50, 0x2000
	s_nop 0
	global_load_lds_dwordx4 v[164:165], off
	v_lshl_add_u64 v[164:165], v[220:221], 0, s[8:9]
	s_mov_b32 m0, s53
	s_nop 0
	global_load_lds_dwordx4 v[164:165], off
	v_lshl_add_u64 v[164:165], v[222:223], 0, s[8:9]
	s_mov_b32 m0, s54
	s_nop 0
	global_load_lds_dwordx4 v[164:165], off
	s_waitcnt vmcnt(8)
	s_waitcnt lgkmcnt(0)
	s_barrier
	s_waitcnt lgkmcnt(0)
	v_mfma_f32_16x16x32_bf16 v[60:63], v[128:131], v[184:187], v[60:63]
	v_mfma_f32_16x16x32_bf16 v[56:59], v[136:139], v[184:187], v[56:59]
	v_mfma_f32_16x16x32_bf16 v[44:47], v[128:131], v[194:197], v[44:47]
	v_mfma_f32_16x16x32_bf16 v[36:39], v[136:139], v[194:197], v[36:39]
	v_mfma_f32_16x16x32_bf16 v[20:23], v[128:131], v[202:205], v[20:23]
	v_mfma_f32_16x16x32_bf16 v[12:15], v[136:139], v[202:205], v[12:15]
	v_mfma_f32_16x16x32_bf16 v[4:7], v[128:131], v[210:213], v[4:7]
	v_mfma_f32_16x16x32_bf16 v[0:3], v[136:139], v[210:213], v[0:3]
	v_mfma_f32_16x16x32_bf16 v[60:63], v[132:135], v[188:191], v[60:63]
	v_mfma_f32_16x16x32_bf16 v[56:59], v[140:143], v[188:191], v[56:59]
	v_mfma_f32_16x16x32_bf16 v[44:47], v[132:135], v[198:201], v[44:47]
	v_mfma_f32_16x16x32_bf16 v[36:39], v[140:143], v[198:201], v[36:39]
	v_mfma_f32_16x16x32_bf16 v[20:23], v[132:135], v[206:209], v[20:23]
	v_mfma_f32_16x16x32_bf16 v[12:15], v[140:143], v[206:209], v[12:15]
	v_mfma_f32_16x16x32_bf16 v[4:7], v[132:135], v[214:217], v[4:7]
	v_mfma_f32_16x16x32_bf16 v[0:3], v[140:143], v[214:217], v[0:3]
	v_mfma_f32_16x16x32_bf16 v[40:43], v[160:163], v[184:187], v[40:43]
	v_mfma_f32_16x16x32_bf16 v[32:35], v[176:179], v[184:187], v[32:35]
	v_mfma_f32_16x16x32_bf16 v[16:19], v[160:163], v[194:197], v[16:19]
	v_mfma_f32_16x16x32_bf16 v[8:11], v[176:179], v[194:197], v[8:11]
	v_mfma_f32_16x16x32_bf16 v[52:55], v[160:163], v[202:205], v[52:55]
	v_mfma_f32_16x16x32_bf16 v[48:51], v[176:179], v[202:205], v[48:51]
	v_mfma_f32_16x16x32_bf16 v[28:31], v[160:163], v[210:213], v[28:31]
	v_mfma_f32_16x16x32_bf16 v[24:27], v[176:179], v[210:213], v[24:27]
	v_mfma_f32_16x16x32_bf16 v[40:43], v[172:175], v[188:191], v[40:43]
	v_mfma_f32_16x16x32_bf16 v[32:35], v[180:183], v[188:191], v[32:35]
	v_mfma_f32_16x16x32_bf16 v[16:19], v[172:175], v[198:201], v[16:19]
	v_mfma_f32_16x16x32_bf16 v[8:11], v[180:183], v[198:201], v[8:11]
	v_mfma_f32_16x16x32_bf16 v[52:55], v[172:175], v[206:209], v[52:55]
	v_mfma_f32_16x16x32_bf16 v[48:51], v[180:183], v[206:209], v[48:51]
	v_mfma_f32_16x16x32_bf16 v[28:31], v[172:175], v[214:217], v[28:31]
	v_mfma_f32_16x16x32_bf16 v[24:27], v[180:183], v[214:217], v[24:27]
	s_barrier
	s_add_i32 s59, s59, 2
	s_add_u32 s44, s44, 0x100
	s_addc_u32 s45, s45, 0
	s_add_u32 s27, s27, 0x100
	s_addc_u32 s29, s29, 0
	s_cmp_gt_u32 s59, 13
	s_cbranch_scc0 .LBB0_978
	s_and_b64 vcc, exec, s[24:25]
	s_cbranch_vccz .LBB0_981
	s_barrier

.LBB0_985:
	s_setprio 0
	s_waitcnt vmcnt(0)
	s_barrier
	s_and_saveexec_b64 s[0:1], s[80:81]
	s_cbranch_execz .LBB0_1037
	v_readlane_b32 s98, v248, 1
	v_readlane_b32 s99, v248, 2
	v_mov_b32_e32 v0, 0x20ff0
	ds_read2_b32 v[2:3], v0 offset1:1
	v_mov_b32_e32 v1, 1
	v_mov_b32_e32 v4, s97
	v_lshlrev_b32_e32 v4, 8, v4
	s_add_u32 s98, s98, 0x1000
	s_addc_u32 s99, s99, 0
	s_nop 2
	global_atomic_add v5, v4, v1, s[98:99] offset:1024 sc0
	s_waitcnt vmcnt(0) lgkmcnt(0)
	v_mul_u32_u24_e32 v2, 9, v2
	v_mul_u32_u24_e32 v3, 9, v3
	v_add_u32_e32 v5, 1, v5
	v_cmp_ne_u32_e32 vcc, v5, v2
	v_mov_b32_e32 v6, 0x2400
	s_cbranch_vccnz .Lxb8_poll
	buffer_wbl2 sc1
	s_waitcnt vmcnt(0)
	global_atomic_add v6, v1, s[98:99]

.LBB0_1092:
	s_or_b64 exec, exec, s[0:1]
	v_mov_b32_e32 v10, v193
	s_waitcnt lgkmcnt(0)
	s_barrier
	s_cmpk_gt_i32 s6, 0xaff
	v_readfirstlane_b32 s0, v10
	s_cbranch_scc1 .LBB0_1108
	v_lshlrev_b32_e32 v0, 4, v10
	v_add_u32_e32 v1, 0x2000, v0
	v_ashrrev_i32_e32 v2, 31, v1
	v_lshrrev_b32_e32 v2, 22, v2
	v_add_u32_e32 v2, v1, v2
	v_ashrrev_i32_e32 v8, 10, v2
	v_mul_i32_i24_e32 v2, 0x400, v8
	v_sub_u32_e32 v1, v1, v2
	v_lshrrev_b32_e32 v2, 4, v1
	v_bitop3_b32 v1, v2, v1, 32 bitop3:0x6c
	v_ashrrev_i32_e32 v2, 31, v1
	v_lshrrev_b32_e32 v2, 26, v2
	v_add_u32_e32 v2, v1, v2
	v_lshlrev_b32_e32 v3, 3, v8
	v_ashrrev_i32_e32 v9, 6, v2
	v_and_b32_e32 v3, -16, v3
	v_add_u32_e32 v3, v9, v3
	v_and_b32_e32 v4, 3, v9
	s_mov_b32 s3, 0x1fffe0
	v_lshrrev_b32_e32 v5, 2, v3
	v_lshlrev_b32_e32 v6, 1, v3
	v_and_b32_e32 v2, 0xc0, v2
	v_and_or_b32 v4, v3, s3, v4
	v_and_b32_e32 v5, 4, v5
	v_and_b32_e32 v6, 24, v6
	v_sub_u32_e32 v1, v1, v2
	v_mov_b32_e32 v2, 1
	v_or3_b32 v4, v4, v5, v6
	v_lshlrev_b32_e32 v5, 5, v8
	v_ashrrev_i16_sdwa v1, v2, sext(v1) dst_sel:DWORD dst_unused:UNUSED_PAD src0_sel:DWORD src1_sel:BYTE_0
	v_and_b32_e32 v5, 32, v5
	v_bfe_i32 v11, v1, 0, 16
	v_add_lshl_u32 v1, v5, v11, 1
	v_lshl_add_u32 v128, v4, 11, v1
	v_lshl_add_u32 v130, v3, 11, v1
	v_bfe_i32 v1, v10, 27, 1
	v_lshrrev_b32_e32 v1, 22, v1
	v_add_u32_e32 v1, v0, v1
	v_and_b32_e32 v1, 0xfffffc00, v1
	v_sub_u32_e32 v0, v0, v1
	v_lshrrev_b32_e32 v1, 4, v0
	v_ashrrev_i32_e32 v3, 31, v10
	v_bitop3_b32 v0, v1, v0, 32 bitop3:0x6c
	v_lshrrev_b32_e32 v3, 26, v3
	v_ashrrev_i32_e32 v1, 31, v0
	v_add_u32_e32 v3, v10, v3
	v_lshrrev_b32_e32 v1, 26, v1
	v_ashrrev_i32_e32 v13, 6, v3
	v_add_u32_e32 v1, v0, v1
	v_lshlrev_b32_e32 v3, 3, v13
	v_ashrrev_i32_e32 v12, 6, v1
	v_and_b32_e32 v3, -16, v3
	v_add_u32_e32 v3, v12, v3
	v_and_b32_e32 v4, 3, v12
	v_and_or_b32 v4, v3, s3, v4
	s_ashr_i32 s3, s6, 31
	s_lshr_b32 s7, s3, 29
	s_add_i32 s7, s6, s7
	s_ashr_i32 s12, s0, 6
	s_ashr_i32 s8, s7, 3
	s_and_b32 s7, s7, -8
	s_ashr_i32 s1, s0, 8
	s_lshl_b32 s2, s12, 10
	s_sub_i32 s9, s6, s7
	s_cmp_lt_i32 s9, 0
	s_movk_i32 s7, 0x161
	s_cselect_b32 s13, s7, 0x160
	s_mul_i32 s9, s9, s13
	s_add_i32 s9, s9, s8
	s_mul_hi_i32 s8, s9, 0x2e8ba2e9
	s_lshr_b32 s13, s8, 31
	s_ashr_i32 s8, s8, 5
	s_add_i32 s8, s8, s13
	s_mul_i32 s13, s8, 0xb0
	s_sub_i32 s9, s9, s13
	s_sext_i32_i16 s13, s9
	s_bfe_u32 s13, s13, 0x3001c
	s_add_i32 s13, s9, s13
	s_sext_i32_i16 s24, s13
	s_and_b32 s13, s13, 0xfff8
	s_sub_i32 s9, s9, s13
	s_sext_i32_i16 s9, s9
	s_lshl_b32 s8, s8, 11
	s_lshl_b32 s9, s9, 8
	s_add_i32 s38, s9, s8
	s_lshl_b32 s8, s24, 5
	s_ashr_i32 s39, s38, 31
	s_and_b32 s40, s8, 0xffffff00
	s_lshl_b64 s[8:9], s[38:39], 11
	v_lshrrev_b32_e32 v5, 2, v3
	v_lshlrev_b32_e32 v6, 1, v3
	v_and_b32_e32 v1, 0xc0, v1
	s_add_u32 s42, s18, s8
	v_and_b32_e32 v5, 4, v5
	v_and_b32_e32 v6, 24, v6
	v_sub_u32_e32 v0, v0, v1
	s_addc_u32 s43, s19, s9
	s_ashr_i32 s41, s40, 31
	v_or3_b32 v4, v4, v5, v6
	v_lshlrev_b32_e32 v5, 5, v13
	v_ashrrev_i16_sdwa v0, v2, sext(v0) dst_sel:DWORD dst_unused:UNUSED_PAD src0_sel:DWORD src1_sel:BYTE_0
	s_lshl_b64 s[8:9], s[40:41], 11
	v_and_b32_e32 v5, 32, v5
	v_bfe_i32 v14, v0, 0, 16
	s_add_u32 s44, s16, s8
	v_add_lshl_u32 v0, v5, v14, 1
	s_addc_u32 s45, s17, s9
	s_add_i32 s33, s2, 0
	v_lshl_add_u32 v132, v4, 11, v0
	s_add_i32 m0, s33, 0x10000
	v_lshl_add_u32 v134, v3, 11, v0
	global_load_lds_dwordx4 v132, s[44:45]
	s_add_i32 m0, s33, 0x12000
	s_add_u32 s8, s44, 0x40000
	global_load_lds_dwordx4 v128, s[44:45]
	s_addc_u32 s9, s45, 0
	s_add_i32 m0, s33, 0x14000
	s_add_i32 s34, s33, 0x2000
	global_load_lds_dwordx4 v132, s[8:9]
	s_add_i32 m0, s33, 0x16000
	v_mov_b32_e32 v137, 0
	global_load_lds_dwordx4 v128, s[8:9]
	s_mov_b32 m0, s33
	s_add_u32 s8, s42, 0x40000
	global_load_lds_dwordx4 v134, s[42:43]
	s_mov_b32 m0, s34
	s_addc_u32 s9, s43, 0
	s_add_i32 s35, s33, 0x4000
	global_load_lds_dwordx4 v130, s[42:43]
	s_mov_b32 m0, s35
	s_add_i32 s39, s33, 0x6000
	global_load_lds_dwordx4 v134, s[8:9]
	s_mov_b32 m0, s39
	v_mov_b32_e32 v133, v137
	global_load_lds_dwordx4 v130, s[8:9]
	v_mov_b32_e32 v129, v137
	v_mov_b32_e32 v135, v137
	v_mov_b32_e32 v131, v137
	s_cmp_eq_u32 s1, 1
	s_mov_b32 s41, 0
	v_lshl_add_u64 v[6:7], s[44:45], 0, v[132:133]
	v_lshl_add_u64 v[4:5], s[44:45], 0, v[128:129]
	v_lshl_add_u64 v[0:1], s[42:43], 0, v[134:135]
	s_cselect_b64 s[8:9], -1, 0
	s_cmp_lg_u32 s1, 1
	v_lshl_add_u64 v[2:3], s[42:43], 0, v[130:131]
	s_cbranch_scc1 .LBB0_1095
	s_setprio 1
	s_barrier

.LBB0_1101:
	ds_read_b128 v[156:159], v153
	ds_read_b128 v[160:163], v153 offset:1024
	ds_read_b128 v[164:167], v153 offset:2048
	ds_read_b128 v[168:171], v153 offset:3072
	ds_read_b128 v[172:175], v154
	ds_read_b128 v[176:179], v154 offset:1024
	ds_read_b128 v[180:183], v154 offset:2048
	ds_read_b128 v[184:187], v154 offset:3072
	s_add_u32 s44, s42, 0xfffc0080
	s_addc_u32 s45, s43, -1
	s_cmp_eq_u32 s55, 12
	s_cselect_b32 s47, s31, s45
	s_cselect_b32 s46, s30, s44
	s_cselect_b32 s45, s37, s29
	s_cselect_b32 s44, s36, s27
	v_lshl_add_u64 v[148:149], s[42:43], 0, v[138:139]
	s_add_i32 m0, s33, 0xc000
	ds_read_b128 v[188:191], v155
	ds_read_b128 v[194:197], v155 offset:1024
	ds_read_b128 v[198:201], v155 offset:2048
	ds_read_b128 v[202:205], v155 offset:3072
	ds_read_b128 v[206:209], v155 offset:4096
	ds_read_b128 v[210:213], v155 offset:5120
	ds_read_b128 v[214:217], v155 offset:6144
	ds_read_b128 v[218:221], v155 offset:7168
	global_load_lds_dwordx4 v[148:149], off
	v_lshl_add_u64 v[148:149], s[42:43], 0, v[140:141]
	s_add_i32 m0, s33, 0xe000
	s_nop 0
	global_load_lds_dwordx4 v[148:149], off
	s_waitcnt vmcnt(8)
	s_waitcnt lgkmcnt(0)
	s_barrier
	s_waitcnt lgkmcnt(0)
	v_mfma_f32_16x16x32_bf16 v[124:127], v[156:159], v[188:191], v[124:127]
	v_mfma_f32_16x16x32_bf16 v[120:123], v[164:167], v[188:191], v[120:123]
	v_mfma_f32_16x16x32_bf16 v[108:111], v[156:159], v[198:201], v[108:111]
	v_mfma_f32_16x16x32_bf16 v[104:107], v[164:167], v[198:201], v[104:107]
	v_mfma_f32_16x16x32_bf16 v[92:95], v[156:159], v[206:209], v[92:95]
	v_mfma_f32_16x16x32_bf16 v[88:91], v[164:167], v[206:209], v[88:91]
	v_mfma_f32_16x16x32_bf16 v[76:79], v[156:159], v[214:217], v[76:79]
	v_mfma_f32_16x16x32_bf16 v[72:75], v[164:167], v[214:217], v[72:75]
	v_mfma_f32_16x16x32_bf16 v[124:127], v[160:163], v[194:197], v[124:127]
	v_mfma_f32_16x16x32_bf16 v[120:123], v[168:171], v[194:197], v[120:123]
	v_mfma_f32_16x16x32_bf16 v[108:111], v[160:163], v[202:205], v[108:111]
	v_mfma_f32_16x16x32_bf16 v[104:107], v[168:171], v[202:205], v[104:107]
	v_mfma_f32_16x16x32_bf16 v[92:95], v[160:163], v[210:213], v[92:95]
	v_mfma_f32_16x16x32_bf16 v[88:91], v[168:171], v[210:213], v[88:91]
	v_mfma_f32_16x16x32_bf16 v[76:79], v[160:163], v[218:221], v[76:79]
	v_mfma_f32_16x16x32_bf16 v[72:75], v[168:171], v[218:221], v[72:75]
	v_mfma_f32_16x16x32_bf16 v[116:119], v[172:175], v[188:191], v[116:119]
	v_mfma_f32_16x16x32_bf16 v[112:115], v[180:183], v[188:191], v[112:115]
	v_mfma_f32_16x16x32_bf16 v[100:103], v[172:175], v[198:201], v[100:103]
	v_mfma_f32_16x16x32_bf16 v[96:99], v[180:183], v[198:201], v[96:99]
	v_mfma_f32_16x16x32_bf16 v[84:87], v[172:175], v[206:209], v[84:87]
	v_mfma_f32_16x16x32_bf16 v[80:83], v[180:183], v[206:209], v[80:83]
	v_mfma_f32_16x16x32_bf16 v[68:71], v[172:175], v[214:217], v[68:71]
	v_mfma_f32_16x16x32_bf16 v[64:67], v[180:183], v[214:217], v[64:67]
	v_mfma_f32_16x16x32_bf16 v[116:119], v[176:179], v[194:197], v[116:119]
	v_mfma_f32_16x16x32_bf16 v[112:115], v[184:187], v[194:197], v[112:115]
	v_mfma_f32_16x16x32_bf16 v[100:103], v[176:179], v[202:205], v[100:103]
	v_mfma_f32_16x16x32_bf16 v[96:99], v[184:187], v[202:205], v[96:99]
	v_mfma_f32_16x16x32_bf16 v[84:87], v[176:179], v[210:213], v[84:87]
	v_mfma_f32_16x16x32_bf16 v[80:83], v[184:187], v[210:213], v[80:83]
	v_mfma_f32_16x16x32_bf16 v[68:71], v[176:179], v[218:221], v[68:71]
	v_mfma_f32_16x16x32_bf16 v[64:67], v[184:187], v[218:221], v[64:67]
	s_barrier
	s_add_i32 s56, s52, s2
	v_lshl_add_u64 v[148:149], s[44:45], 0, v[132:133]
	s_mov_b32 m0, s56
	ds_read_b128 v[188:191], v155 offset:16384
	ds_read_b128 v[194:197], v155 offset:17408
	ds_read_b128 v[198:201], v155 offset:18432
	ds_read_b128 v[202:205], v155 offset:19456
	ds_read_b128 v[206:209], v155 offset:20480
	ds_read_b128 v[210:213], v155 offset:21504
	ds_read_b128 v[214:217], v155 offset:22528
	ds_read_b128 v[218:221], v155 offset:23552
	global_load_lds_dwordx4 v[148:149], off
	s_add_i32 m0, s56, 0x2000
	s_add_u32 s56, s44, 0x40000
	v_lshl_add_u64 v[222:223], s[44:45], 0, v[128:129]
	s_addc_u32 s57, s45, 0
	s_add_i32 s58, s53, s2
	global_load_lds_dwordx4 v[222:223], off
	v_lshl_add_u64 v[224:225], s[56:57], 0, v[132:133]
	s_mov_b32 m0, s58
	v_lshl_add_u64 v[228:229], s[46:47], 0, v[130:131]
	global_load_lds_dwordx4 v[224:225], off
	v_lshl_add_u64 v[224:225], s[56:57], 0, v[128:129]
	s_add_i32 m0, s58, 0x2000
	s_nop 0
	global_load_lds_dwordx4 v[224:225], off
	v_lshl_add_u64 v[224:225], s[46:47], 0, v[134:135]
	s_mov_b32 m0, s33
	s_nop 0
	global_load_lds_dwordx4 v[224:225], off
	s_mov_b32 m0, s34
	s_nop 0
	global_load_lds_dwordx4 v[228:229], off
	s_waitcnt vmcnt(8)
	s_waitcnt lgkmcnt(0)
	s_barrier
	s_waitcnt lgkmcnt(0)
	v_mfma_f32_16x16x32_bf16 v[60:63], v[156:159], v[188:191], v[60:63]
	v_mfma_f32_16x16x32_bf16 v[56:59], v[164:167], v[188:191], v[56:59]
	v_mfma_f32_16x16x32_bf16 v[44:47], v[156:159], v[198:201], v[44:47]
	v_mfma_f32_16x16x32_bf16 v[40:43], v[164:167], v[198:201], v[40:43]
	v_mfma_f32_16x16x32_bf16 v[28:31], v[156:159], v[206:209], v[28:31]
	v_mfma_f32_16x16x32_bf16 v[24:27], v[164:167], v[206:209], v[24:27]
	v_mfma_f32_16x16x32_bf16 v[12:15], v[156:159], v[214:217], v[12:15]
	v_mfma_f32_16x16x32_bf16 v[8:11], v[164:167], v[214:217], v[8:11]
	v_mfma_f32_16x16x32_bf16 v[60:63], v[160:163], v[194:197], v[60:63]
	v_mfma_f32_16x16x32_bf16 v[56:59], v[168:171], v[194:197], v[56:59]
	v_mfma_f32_16x16x32_bf16 v[44:47], v[160:163], v[202:205], v[44:47]
	v_mfma_f32_16x16x32_bf16 v[40:43], v[168:171], v[202:205], v[40:43]
	v_mfma_f32_16x16x32_bf16 v[28:31], v[160:163], v[210:213], v[28:31]
	v_mfma_f32_16x16x32_bf16 v[24:27], v[168:171], v[210:213], v[24:27]
	v_mfma_f32_16x16x32_bf16 v[12:15], v[160:163], v[218:221], v[12:15]
	v_mfma_f32_16x16x32_bf16 v[8:11], v[168:171], v[218:221], v[8:11]
	v_mfma_f32_16x16x32_bf16 v[52:55], v[172:175], v[188:191], v[52:55]
	v_mfma_f32_16x16x32_bf16 v[48:51], v[180:183], v[188:191], v[48:51]
	v_mfma_f32_16x16x32_bf16 v[36:39], v[172:175], v[198:201], v[36:39]
	v_mfma_f32_16x16x32_bf16 v[32:35], v[180:183], v[198:201], v[32:35]
	v_mfma_f32_16x16x32_bf16 v[20:23], v[172:175], v[206:209], v[20:23]
	v_mfma_f32_16x16x32_bf16 v[16:19], v[180:183], v[206:209], v[16:19]
	v_mfma_f32_16x16x32_bf16 v[4:7], v[172:175], v[214:217], v[4:7]
	v_mfma_f32_16x16x32_bf16 v[0:3], v[180:183], v[214:217], v[0:3]
	v_mfma_f32_16x16x32_bf16 v[52:55], v[176:179], v[194:197], v[52:55]
	v_mfma_f32_16x16x32_bf16 v[48:51], v[184:187], v[194:197], v[48:51]
	v_mfma_f32_16x16x32_bf16 v[36:39], v[176:179], v[202:205], v[36:39]
	v_mfma_f32_16x16x32_bf16 v[32:35], v[184:187], v[202:205], v[32:35]
	v_mfma_f32_16x16x32_bf16 v[20:23], v[176:179], v[210:213], v[20:23]
	v_mfma_f32_16x16x32_bf16 v[16:19], v[184:187], v[210:213], v[16:19]
	v_mfma_f32_16x16x32_bf16 v[4:7], v[176:179], v[218:221], v[4:7]
	v_mfma_f32_16x16x32_bf16 v[0:3], v[184:187], v[218:221], v[0:3]
	s_barrier
	s_add_i32 s56, 0, 0x18000
	v_add_u32_e32 v136, s56, v151
	s_add_i32 s57, 0, 0x1c000
	ds_read_b128 v[156:159], v136
	ds_read_b128 v[160:163], v136 offset:1024
	ds_read_b128 v[164:167], v136 offset:2048
	ds_read_b128 v[168:171], v136 offset:3072
	v_add_u32_e32 v136, s57, v151
	ds_read_b128 v[172:175], v136
	ds_read_b128 v[176:179], v136 offset:1024
	ds_read_b128 v[180:183], v136 offset:2048
	ds_read_b128 v[184:187], v136 offset:3072
	s_add_u32 s46, s46, 0x40000
	s_addc_u32 s47, s47, 0
	s_mov_b32 m0, s35
	v_lshl_add_u64 v[230:231], s[46:47], 0, v[134:135]
	ds_read_b128 v[188:191], v155 offset:32768
	ds_read_b128 v[194:197], v155 offset:33792
	ds_read_b128 v[198:201], v155 offset:34816
	ds_read_b128 v[202:205], v155 offset:35840
	ds_read_b128 v[206:209], v155 offset:36864
	ds_read_b128 v[210:213], v155 offset:37888
	ds_read_b128 v[214:217], v155 offset:38912
	ds_read_b128 v[218:221], v155 offset:39936
	global_load_lds_dwordx4 v[230:231], off
	v_lshl_add_u64 v[230:231], s[46:47], 0, v[130:131]
	s_mov_b32 m0, s39
	s_nop 0
	global_load_lds_dwordx4 v[230:231], off
	s_waitcnt vmcnt(8)
	s_waitcnt lgkmcnt(0)
	s_barrier
	s_waitcnt lgkmcnt(0)
	v_mfma_f32_16x16x32_bf16 v[124:127], v[156:159], v[188:191], v[124:127]
	v_mfma_f32_16x16x32_bf16 v[120:123], v[164:167], v[188:191], v[120:123]
	v_mfma_f32_16x16x32_bf16 v[108:111], v[156:159], v[198:201], v[108:111]
	v_mfma_f32_16x16x32_bf16 v[104:107], v[164:167], v[198:201], v[104:107]
	v_mfma_f32_16x16x32_bf16 v[92:95], v[156:159], v[206:209], v[92:95]
	v_mfma_f32_16x16x32_bf16 v[88:91], v[164:167], v[206:209], v[88:91]
	v_mfma_f32_16x16x32_bf16 v[76:79], v[156:159], v[214:217], v[76:79]
	v_mfma_f32_16x16x32_bf16 v[72:75], v[164:167], v[214:217], v[72:75]
	v_mfma_f32_16x16x32_bf16 v[124:127], v[160:163], v[194:197], v[124:127]
	v_mfma_f32_16x16x32_bf16 v[120:123], v[168:171], v[194:197], v[120:123]
	v_mfma_f32_16x16x32_bf16 v[108:111], v[160:163], v[202:205], v[108:111]
	v_mfma_f32_16x16x32_bf16 v[104:107], v[168:171], v[202:205], v[104:107]
	v_mfma_f32_16x16x32_bf16 v[92:95], v[160:163], v[210:213], v[92:95]
	v_mfma_f32_16x16x32_bf16 v[88:91], v[168:171], v[210:213], v[88:91]
	v_mfma_f32_16x16x32_bf16 v[76:79], v[160:163], v[218:221], v[76:79]
	v_mfma_f32_16x16x32_bf16 v[72:75], v[168:171], v[218:221], v[72:75]
	v_mfma_f32_16x16x32_bf16 v[116:119], v[172:175], v[188:191], v[116:119]
	v_mfma_f32_16x16x32_bf16 v[112:115], v[180:183], v[188:191], v[112:115]
	v_mfma_f32_16x16x32_bf16 v[100:103], v[172:175], v[198:201], v[100:103]
	v_mfma_f32_16x16x32_bf16 v[96:99], v[180:183], v[198:201], v[96:99]
	v_mfma_f32_16x16x32_bf16 v[84:87], v[172:175], v[206:209], v[84:87]
	v_mfma_f32_16x16x32_bf16 v[80:83], v[180:183], v[206:209], v[80:83]
	v_mfma_f32_16x16x32_bf16 v[68:71], v[172:175], v[214:217], v[68:71]
	v_mfma_f32_16x16x32_bf16 v[64:67], v[180:183], v[214:217], v[64:67]
	v_mfma_f32_16x16x32_bf16 v[116:119], v[176:179], v[194:197], v[116:119]
	v_mfma_f32_16x16x32_bf16 v[112:115], v[184:187], v[194:197], v[112:115]
	v_mfma_f32_16x16x32_bf16 v[100:103], v[176:179], v[202:205], v[100:103]
	v_mfma_f32_16x16x32_bf16 v[96:99], v[184:187], v[202:205], v[96:99]
	v_mfma_f32_16x16x32_bf16 v[84:87], v[176:179], v[210:213], v[84:87]
	v_mfma_f32_16x16x32_bf16 v[80:83], v[184:187], v[210:213], v[80:83]
	v_mfma_f32_16x16x32_bf16 v[68:71], v[176:179], v[218:221], v[68:71]
	v_mfma_f32_16x16x32_bf16 v[64:67], v[184:187], v[218:221], v[64:67]
	s_barrier
	s_add_i32 s46, s56, s2
	v_lshl_add_u64 v[148:149], v[148:149], 0, s[12:13]
	s_mov_b32 m0, s46
	ds_read_b128 v[188:191], v155 offset:49152
	ds_read_b128 v[194:197], v155 offset:50176
	ds_read_b128 v[198:201], v155 offset:51200
	ds_read_b128 v[202:205], v155 offset:52224
	ds_read_b128 v[206:209], v155 offset:53248
	ds_read_b128 v[210:213], v155 offset:54272
	ds_read_b128 v[214:217], v155 offset:55296
	ds_read_b128 v[218:221], v155 offset:56320
	global_load_lds_dwordx4 v[148:149], off
	s_add_i32 m0, s46, 0x2000
	s_add_u32 s44, s44, 0x40080
	v_lshl_add_u64 v[148:149], v[222:223], 0, s[12:13]
	s_addc_u32 s45, s45, 0
	s_add_i32 s46, s57, s2
	global_load_lds_dwordx4 v[148:149], off
	v_lshl_add_u64 v[148:149], s[44:45], 0, v[132:133]
	s_mov_b32 m0, s46
	s_nop 0
	global_load_lds_dwordx4 v[148:149], off
	v_lshl_add_u64 v[148:149], s[44:45], 0, v[128:129]
	s_add_i32 m0, s46, 0x2000
	s_nop 0
	global_load_lds_dwordx4 v[148:149], off
	v_lshl_add_u64 v[148:149], v[224:225], 0, s[12:13]
	s_mov_b32 m0, s48
	s_nop 0
	global_load_lds_dwordx4 v[148:149], off
	v_lshl_add_u64 v[148:149], v[228:229], 0, s[12:13]
	s_mov_b32 m0, s49
	s_nop 0
	global_load_lds_dwordx4 v[148:149], off
	s_waitcnt vmcnt(8)
	s_waitcnt lgkmcnt(0)
	s_barrier
	s_waitcnt lgkmcnt(0)
	v_mfma_f32_16x16x32_bf16 v[60:63], v[156:159], v[188:191], v[60:63]
	v_mfma_f32_16x16x32_bf16 v[56:59], v[164:167], v[188:191], v[56:59]
	v_mfma_f32_16x16x32_bf16 v[44:47], v[156:159], v[198:201], v[44:47]
	v_mfma_f32_16x16x32_bf16 v[40:43], v[164:167], v[198:201], v[40:43]
	v_mfma_f32_16x16x32_bf16 v[28:31], v[156:159], v[206:209], v[28:31]
	v_mfma_f32_16x16x32_bf16 v[24:27], v[164:167], v[206:209], v[24:27]
	v_mfma_f32_16x16x32_bf16 v[12:15], v[156:159], v[214:217], v[12:15]
	v_mfma_f32_16x16x32_bf16 v[8:11], v[164:167], v[214:217], v[8:11]
	v_mfma_f32_16x16x32_bf16 v[60:63], v[160:163], v[194:197], v[60:63]
	v_mfma_f32_16x16x32_bf16 v[56:59], v[168:171], v[194:197], v[56:59]
	v_mfma_f32_16x16x32_bf16 v[44:47], v[160:163], v[202:205], v[44:47]
	v_mfma_f32_16x16x32_bf16 v[40:43], v[168:171], v[202:205], v[40:43]
	v_mfma_f32_16x16x32_bf16 v[28:31], v[160:163], v[210:213], v[28:31]
	v_mfma_f32_16x16x32_bf16 v[24:27], v[168:171], v[210:213], v[24:27]
	v_mfma_f32_16x16x32_bf16 v[12:15], v[160:163], v[218:221], v[12:15]
	v_mfma_f32_16x16x32_bf16 v[8:11], v[168:171], v[218:221], v[8:11]
	v_mfma_f32_16x16x32_bf16 v[52:55], v[172:175], v[188:191], v[52:55]
	v_mfma_f32_16x16x32_bf16 v[48:51], v[180:183], v[188:191], v[48:51]
	v_mfma_f32_16x16x32_bf16 v[36:39], v[172:175], v[198:201], v[36:39]
	v_mfma_f32_16x16x32_bf16 v[32:35], v[180:183], v[198:201], v[32:35]
	v_mfma_f32_16x16x32_bf16 v[20:23], v[172:175], v[206:209], v[20:23]
	v_mfma_f32_16x16x32_bf16 v[16:19], v[180:183], v[206:209], v[16:19]
	v_mfma_f32_16x16x32_bf16 v[4:7], v[172:175], v[214:217], v[4:7]
	v_mfma_f32_16x16x32_bf16 v[0:3], v[180:183], v[214:217], v[0:3]
	v_mfma_f32_16x16x32_bf16 v[52:55], v[176:179], v[194:197], v[52:55]
	v_mfma_f32_16x16x32_bf16 v[48:51], v[184:187], v[194:197], v[48:51]
	v_mfma_f32_16x16x32_bf16 v[36:39], v[176:179], v[202:205], v[36:39]
	v_mfma_f32_16x16x32_bf16 v[32:35], v[184:187], v[202:205], v[32:35]
	v_mfma_f32_16x16x32_bf16 v[20:23], v[176:179], v[210:213], v[20:23]
	v_mfma_f32_16x16x32_bf16 v[16:19], v[184:187], v[210:213], v[16:19]
	v_mfma_f32_16x16x32_bf16 v[4:7], v[176:179], v[218:221], v[4:7]
	v_mfma_f32_16x16x32_bf16 v[0:3], v[184:187], v[218:221], v[0:3]
	s_barrier
	s_add_i32 s55, s55, 2
	s_add_u32 s42, s42, 0x100
	s_addc_u32 s43, s43, 0
	s_add_u32 s27, s27, 0x100
	s_addc_u32 s29, s29, 0
	s_cmp_gt_u32 s55, 13
	s_cbranch_scc0 .LBB0_1101
	s_and_b64 vcc, exec, s[24:25]
	s_cbranch_vccz .LBB0_1104
	s_barrier

.LBB0_1108:
	s_setprio 0
	s_waitcnt vmcnt(0)
	s_waitcnt vmcnt(0)
	s_barrier
	s_and_saveexec_b64 s[0:1], s[80:81]
	s_cbranch_execz .LBB0_1160
	v_readlane_b32 s98, v248, 1
	v_readlane_b32 s99, v248, 2
	v_mov_b32_e32 v0, 0x20ff0
	ds_read2_b32 v[2:3], v0 offset1:1
	v_mov_b32_e32 v1, 1
	v_mov_b32_e32 v4, s97
	v_lshlrev_b32_e32 v4, 8, v4
	s_add_u32 s98, s98, 0x1000
	s_addc_u32 s99, s99, 0
	s_nop 2
	global_atomic_add v5, v4, v1, s[98:99] offset:1024 sc0
	s_waitcnt vmcnt(0) lgkmcnt(0)
	v_mul_u32_u24_e32 v2, 11, v2
	v_mul_u32_u24_e32 v3, 11, v3
	v_add_u32_e32 v5, 1, v5
	v_cmp_ne_u32_e32 vcc, v5, v2
	v_mov_b32_e32 v6, 0x2400
	s_cbranch_vccnz .Lxb10_poll
	buffer_wbl2 sc1
	s_waitcnt vmcnt(0)
	global_atomic_add v6, v1, s[98:99]

.LBB0_1165:
	v_ashrrev_i32_e32 v1, 31, v193
	v_lshrrev_b32_e32 v1, 26, v1
	v_add_u32_e32 v1, v193, v1
	v_ashrrev_i32_e32 v8, 6, v1
	v_bfe_i32 v1, v193, 27, 1
	v_lshlrev_b32_e32 v0, 4, v193
	v_lshrrev_b32_e32 v1, 22, v1
	v_add_u32_e32 v1, v0, v1
	v_and_b32_e32 v1, 0xfffffc00, v1
	v_sub_u32_e32 v1, v0, v1
	v_lshrrev_b32_e32 v2, 4, v1
	v_bitop3_b32 v1, v2, v1, 32 bitop3:0x6c
	v_ashrrev_i32_e32 v3, 31, v1
	v_lshrrev_b32_e32 v3, 26, v3
	v_lshlrev_b32_e32 v2, 3, v8
	v_add_u32_e32 v3, v1, v3
	v_and_b32_e32 v2, -16, v2
	v_ashrrev_i32_e32 v10, 6, v3
	v_and_b32_e32 v3, 0xc0, v3
	v_add_u32_e32 v2, v10, v2
	v_lshlrev_b32_e32 v4, 5, v8
	v_sub_u32_e32 v1, v1, v3
	v_mov_b32_e32 v3, 1
	v_and_b32_e32 v9, 32, v4
	v_ashrrev_i16_sdwa v1, v3, sext(v1) dst_sel:DWORD dst_unused:UNUSED_PAD src0_sel:DWORD src1_sel:BYTE_0
	v_lshlrev_b32_e32 v4, 1, v2
	v_lshrrev_b32_e32 v5, 2, v2
	v_and_b32_e32 v6, 3, v10
	s_mov_b32 s3, 0xffffe0
	v_bfe_i32 v11, v1, 0, 16
	v_and_b32_e32 v4, 24, v4
	v_and_b32_e32 v5, 4, v5
	v_and_or_b32 v6, v2, s3, v6
	s_movk_i32 s1, 0xb00
	v_add_u32_e32 v1, v9, v11
	v_or3_b32 v4, v6, v5, v4
	v_mul_lo_u32 v2, v2, s1
	v_add_lshl_u32 v146, v1, v2, 1
	v_mul_u32_u24_e32 v2, 0xb00, v4
	v_add_u32_e32 v0, 0x2000, v0
	s_add_i32 s7, s7, s8
	v_add_lshl_u32 v148, v2, v1, 1
	v_ashrrev_i32_e32 v1, 31, v0
	s_ashr_i32 s8, s7, 31
	v_lshrrev_b32_e32 v1, 22, v1
	s_lshr_b32 s8, s8, 27
	v_add_u32_e32 v1, v0, v1
	s_add_i32 s8, s7, s8
	v_ashrrev_i32_e32 v12, 10, v1
	s_and_b32 s9, s8, 0xffe0
	v_mul_i32_i24_e32 v1, 0x400, v12
	s_sub_i32 s7, s7, s9
	v_sub_u32_e32 v0, v0, v1
	s_bfe_i32 s9, s7, 0x80000
	v_lshrrev_b32_e32 v1, 4, v0
	s_bfe_u32 s9, s9, 0x3000c
	v_bitop3_b32 v0, v1, v0, 32 bitop3:0x6c
	s_add_i32 s9, s7, s9
	v_ashrrev_i32_e32 v2, 31, v0
	s_bfe_i32 s11, s9, 0x80000
	s_and_b32 s9, s9, 0xf8
	v_lshrrev_b32_e32 v2, 26, v2
	s_sub_i32 s7, s7, s9
	v_lshlrev_b32_e32 v1, 3, v12
	v_add_u32_e32 v2, v0, v2
	s_sext_i32_i8 s7, s7
	s_lshl_b32 s8, s8, 6
	v_and_b32_e32 v1, -16, v1
	v_ashrrev_i32_e32 v13, 6, v2
	v_lshlrev_b32_e32 v4, 5, v12
	s_and_b32 s8, s8, 0xfffff800
	s_lshl_b32 s7, s7, 8
	v_add_u32_e32 v1, v13, v1
	v_and_b32_e32 v14, 32, v4
	v_and_b32_e32 v4, 3, v13
	s_ashr_i32 s10, s12, 6
	s_sext_i32_i16 s11, s11
	s_add_i32 s49, s7, s8
	s_ashr_i32 s0, s12, 8
	v_and_or_b32 v4, v1, s3, v4
	s_lshl_b32 s3, s10, 10
	s_ashr_i32 s11, s11, 3
	s_mul_i32 s8, s49, 0x1600
	s_mul_hi_i32 s7, s49, 0x1600
	s_add_u32 s26, s20, s8
	v_and_b32_e32 v2, 0xc0, v2
	s_addc_u32 s27, s21, s7
	s_mul_i32 s7, s11, 0x160000
	v_sub_u32_e32 v0, v0, v2
	s_ashr_i32 s8, s7, 31
	v_ashrrev_i16_sdwa v0, v3, sext(v0) dst_sel:DWORD dst_unused:UNUSED_PAD src0_sel:DWORD src1_sel:BYTE_0
	v_lshlrev_b32_e32 v2, 1, v1
	v_lshrrev_b32_e32 v3, 2, v1
	s_add_u32 s28, s14, s7
	v_bfe_i32 v15, v0, 0, 16
	v_and_b32_e32 v2, 24, v2
	v_and_b32_e32 v3, 4, v3
	s_addc_u32 s29, s15, s8
	s_add_i32 s7, s3, 0
	v_add_u32_e32 v0, v14, v15
	v_or3_b32 v2, v4, v3, v2
	v_mul_lo_u32 v1, v1, s1
	s_add_i32 m0, s7, 0x10000
	v_add_lshl_u32 v150, v0, v1, 1
	v_mul_u32_u24_e32 v1, 0xb00, v2
	global_load_lds_dwordx4 v148, s[28:29]
	s_add_i32 m0, s7, 0x12000
	v_add_lshl_u32 v152, v1, v0, 1
	s_add_u32 s8, s28, 0xb0000
	global_load_lds_dwordx4 v152, s[28:29]
	s_addc_u32 s9, s29, 0
	s_add_i32 m0, s7, 0x14000
	s_add_i32 s33, s7, 0x2000
	global_load_lds_dwordx4 v148, s[8:9]
	s_add_i32 m0, s7, 0x16000
	v_mov_b32_e32 v149, 0
	global_load_lds_dwordx4 v152, s[8:9]
	s_mov_b32 m0, s7
	s_add_u32 s8, s26, 0xb0000
	global_load_lds_dwordx4 v146, s[26:27]
	s_mov_b32 m0, s33
	s_addc_u32 s9, s27, 0
	s_add_i32 s34, s7, 0x4000
	global_load_lds_dwordx4 v150, s[26:27]
	s_mov_b32 m0, s34
	s_add_i32 s35, s7, 0x6000
	global_load_lds_dwordx4 v146, s[8:9]
	s_mov_b32 m0, s35
	v_mov_b32_e32 v153, v149
	global_load_lds_dwordx4 v150, s[8:9]
	v_mov_b32_e32 v147, v149
	v_mov_b32_e32 v151, v149
	s_cmp_eq_u32 s0, 1
	s_mov_b32 s38, 0
	v_lshl_add_u64 v[6:7], s[28:29], 0, v[148:149]
	v_lshl_add_u64 v[4:5], s[28:29], 0, v[152:153]
	v_lshl_add_u64 v[0:1], s[26:27], 0, v[146:147]
	s_cselect_b64 s[8:9], -1, 0
	s_cmp_lg_u32 s0, 1
	v_lshl_add_u64 v[2:3], s[26:27], 0, v[150:151]
	s_cbranch_scc1 .LBB0_1167
	s_setprio 1
	s_barrier

.LBB0_1177:
	ds_read_b128 v[128:131], v171
	ds_read_b128 v[132:135], v171 offset:1024
	ds_read_b128 v[136:139], v171 offset:2048
	ds_read_b128 v[140:143], v171 offset:3072
	ds_read_b128 v[162:165], v172
	ds_read_b128 v[174:177], v172 offset:1024
	ds_read_b128 v[178:181], v172 offset:2048
	ds_read_b128 v[182:185], v172 offset:3072
	s_add_u32 s28, s26, 0x100
	s_addc_u32 s29, s27, 0
	s_cmp_eq_u32 s53, 40
	s_cselect_b32 s37, s17, s29
	s_cselect_b32 s36, s16, s28
	s_cselect_b32 s31, s25, s52
	s_cselect_b32 s30, s24, s51
	v_lshl_add_u64 v[166:167], s[26:27], 0, v[154:155]
	s_add_i32 m0, s7, 0xc000
	ds_read_b128 v[186:189], v173
	ds_read_b128 v[194:197], v173 offset:1024
	ds_read_b128 v[198:201], v173 offset:2048
	ds_read_b128 v[202:205], v173 offset:3072
	ds_read_b128 v[206:209], v173 offset:4096
	ds_read_b128 v[210:213], v173 offset:5120
	ds_read_b128 v[214:217], v173 offset:6144
	ds_read_b128 v[218:221], v173 offset:7168
	global_load_lds_dwordx4 v[166:167], off
	v_lshl_add_u64 v[166:167], s[26:27], 0, v[156:157]
	s_add_i32 m0, s7, 0xe000
	s_nop 0
	global_load_lds_dwordx4 v[166:167], off
	s_waitcnt vmcnt(8)
	s_waitcnt lgkmcnt(0)
	s_barrier
	s_waitcnt lgkmcnt(0)
	v_mfma_f32_16x16x32_bf16 v[124:127], v[128:131], v[186:189], v[124:127]
	v_mfma_f32_16x16x32_bf16 v[120:123], v[136:139], v[186:189], v[120:123]
	v_mfma_f32_16x16x32_bf16 v[112:115], v[128:131], v[198:201], v[112:115]
	v_mfma_f32_16x16x32_bf16 v[104:107], v[136:139], v[198:201], v[104:107]
	v_mfma_f32_16x16x32_bf16 v[96:99], v[128:131], v[206:209], v[96:99]
	v_mfma_f32_16x16x32_bf16 v[88:91], v[136:139], v[206:209], v[88:91]
	v_mfma_f32_16x16x32_bf16 v[80:83], v[128:131], v[214:217], v[80:83]
	v_mfma_f32_16x16x32_bf16 v[72:75], v[136:139], v[214:217], v[72:75]
	v_mfma_f32_16x16x32_bf16 v[124:127], v[132:135], v[194:197], v[124:127]
	v_mfma_f32_16x16x32_bf16 v[120:123], v[140:143], v[194:197], v[120:123]
	v_mfma_f32_16x16x32_bf16 v[112:115], v[132:135], v[202:205], v[112:115]
	v_mfma_f32_16x16x32_bf16 v[104:107], v[140:143], v[202:205], v[104:107]
	v_mfma_f32_16x16x32_bf16 v[96:99], v[132:135], v[210:213], v[96:99]
	v_mfma_f32_16x16x32_bf16 v[88:91], v[140:143], v[210:213], v[88:91]
	v_mfma_f32_16x16x32_bf16 v[80:83], v[132:135], v[218:221], v[80:83]
	v_mfma_f32_16x16x32_bf16 v[72:75], v[140:143], v[218:221], v[72:75]
	v_mfma_f32_16x16x32_bf16 v[116:119], v[162:165], v[186:189], v[116:119]
	v_mfma_f32_16x16x32_bf16 v[108:111], v[178:181], v[186:189], v[108:111]
	v_mfma_f32_16x16x32_bf16 v[100:103], v[162:165], v[198:201], v[100:103]
	v_mfma_f32_16x16x32_bf16 v[92:95], v[178:181], v[198:201], v[92:95]
	v_mfma_f32_16x16x32_bf16 v[84:87], v[162:165], v[206:209], v[84:87]
	v_mfma_f32_16x16x32_bf16 v[76:79], v[178:181], v[206:209], v[76:79]
	v_mfma_f32_16x16x32_bf16 v[68:71], v[162:165], v[214:217], v[68:71]
	v_mfma_f32_16x16x32_bf16 v[64:67], v[178:181], v[214:217], v[64:67]
	v_mfma_f32_16x16x32_bf16 v[116:119], v[174:177], v[194:197], v[116:119]
	v_mfma_f32_16x16x32_bf16 v[108:111], v[182:185], v[194:197], v[108:111]
	v_mfma_f32_16x16x32_bf16 v[100:103], v[174:177], v[202:205], v[100:103]
	v_mfma_f32_16x16x32_bf16 v[92:95], v[182:185], v[202:205], v[92:95]
	v_mfma_f32_16x16x32_bf16 v[84:87], v[174:177], v[210:213], v[84:87]
	v_mfma_f32_16x16x32_bf16 v[76:79], v[182:185], v[210:213], v[76:79]
	v_mfma_f32_16x16x32_bf16 v[68:71], v[174:177], v[218:221], v[68:71]
	v_mfma_f32_16x16x32_bf16 v[64:67], v[182:185], v[218:221], v[64:67]
	s_barrier
	s_add_i32 s26, s45, s3
	v_lshl_add_u64 v[166:167], s[30:31], 0, v[148:149]
	s_mov_b32 m0, s26
	ds_read_b128 v[186:189], v173 offset:16384
	ds_read_b128 v[194:197], v173 offset:17408
	ds_read_b128 v[198:201], v173 offset:18432
	ds_read_b128 v[202:205], v173 offset:19456
	ds_read_b128 v[206:209], v173 offset:20480
	ds_read_b128 v[210:213], v173 offset:21504
	ds_read_b128 v[214:217], v173 offset:22528
	ds_read_b128 v[218:221], v173 offset:23552
	global_load_lds_dwordx4 v[166:167], off
	s_add_i32 m0, s26, 0x2000
	s_add_u32 s26, s30, 0xb0000
	v_lshl_add_u64 v[190:191], s[30:31], 0, v[152:153]
	s_addc_u32 s27, s31, 0
	s_add_i32 s54, s46, s3
	global_load_lds_dwordx4 v[190:191], off
	v_lshl_add_u64 v[222:223], s[26:27], 0, v[148:149]
	s_mov_b32 m0, s54
	v_lshl_add_u64 v[224:225], s[36:37], 0, v[150:151]
	global_load_lds_dwordx4 v[222:223], off
	v_lshl_add_u64 v[222:223], s[26:27], 0, v[152:153]
	s_add_i32 m0, s54, 0x2000
	s_nop 0
	global_load_lds_dwordx4 v[222:223], off
	v_lshl_add_u64 v[222:223], s[36:37], 0, v[146:147]
	s_mov_b32 m0, s7
	s_nop 0
	global_load_lds_dwordx4 v[222:223], off
	s_mov_b32 m0, s33
	s_nop 0
	global_load_lds_dwordx4 v[224:225], off
	s_waitcnt vmcnt(8)
	s_waitcnt lgkmcnt(0)
	s_barrier
	s_waitcnt lgkmcnt(0)
	v_mfma_f32_16x16x32_bf16 v[60:63], v[128:131], v[186:189], v[60:63]
	v_mfma_f32_16x16x32_bf16 v[56:59], v[136:139], v[186:189], v[56:59]
	v_mfma_f32_16x16x32_bf16 v[48:51], v[128:131], v[198:201], v[48:51]
	v_mfma_f32_16x16x32_bf16 v[32:35], v[136:139], v[198:201], v[32:35]
	v_mfma_f32_16x16x32_bf16 v[16:19], v[128:131], v[206:209], v[16:19]
	v_mfma_f32_16x16x32_bf16 v[12:15], v[136:139], v[206:209], v[12:15]
	v_mfma_f32_16x16x32_bf16 v[4:7], v[128:131], v[214:217], v[4:7]
	v_mfma_f32_16x16x32_bf16 v[0:3], v[136:139], v[214:217], v[0:3]
	v_mfma_f32_16x16x32_bf16 v[60:63], v[132:135], v[194:197], v[60:63]
	v_mfma_f32_16x16x32_bf16 v[56:59], v[140:143], v[194:197], v[56:59]
	v_mfma_f32_16x16x32_bf16 v[48:51], v[132:135], v[202:205], v[48:51]
	v_mfma_f32_16x16x32_bf16 v[32:35], v[140:143], v[202:205], v[32:35]
	v_mfma_f32_16x16x32_bf16 v[16:19], v[132:135], v[210:213], v[16:19]
	v_mfma_f32_16x16x32_bf16 v[12:15], v[140:143], v[210:213], v[12:15]
	v_mfma_f32_16x16x32_bf16 v[4:7], v[132:135], v[218:221], v[4:7]
	v_mfma_f32_16x16x32_bf16 v[0:3], v[140:143], v[218:221], v[0:3]
	v_mfma_f32_16x16x32_bf16 v[52:55], v[162:165], v[186:189], v[52:55]
	v_mfma_f32_16x16x32_bf16 v[36:39], v[178:181], v[186:189], v[36:39]
	v_mfma_f32_16x16x32_bf16 v[20:23], v[162:165], v[198:201], v[20:23]
	v_mfma_f32_16x16x32_bf16 v[8:11], v[178:181], v[198:201], v[8:11]
	v_mfma_f32_16x16x32_bf16 v[44:47], v[162:165], v[206:209], v[44:47]
	v_mfma_f32_16x16x32_bf16 v[40:43], v[178:181], v[206:209], v[40:43]
	v_mfma_f32_16x16x32_bf16 v[28:31], v[162:165], v[214:217], v[28:31]
	v_mfma_f32_16x16x32_bf16 v[24:27], v[178:181], v[214:217], v[24:27]
	v_mfma_f32_16x16x32_bf16 v[52:55], v[174:177], v[194:197], v[52:55]
	v_mfma_f32_16x16x32_bf16 v[36:39], v[182:185], v[194:197], v[36:39]
	v_mfma_f32_16x16x32_bf16 v[20:23], v[174:177], v[202:205], v[20:23]
	v_mfma_f32_16x16x32_bf16 v[8:11], v[182:185], v[202:205], v[8:11]
	v_mfma_f32_16x16x32_bf16 v[44:47], v[174:177], v[210:213], v[44:47]
	v_mfma_f32_16x16x32_bf16 v[40:43], v[182:185], v[210:213], v[40:43]
	v_mfma_f32_16x16x32_bf16 v[28:31], v[174:177], v[218:221], v[28:31]
	v_mfma_f32_16x16x32_bf16 v[24:27], v[182:185], v[218:221], v[24:27]
	s_barrier
	s_add_i32 s54, 0, 0x18000
	s_add_i32 s55, 0, 0x1c000
	v_add_u32_e32 v140, s54, v169
	v_add_u32_e32 v182, s55, v169
	ds_read_b128 v[128:131], v140
	ds_read_b128 v[132:135], v140 offset:1024
	ds_read_b128 v[136:139], v140 offset:2048
	ds_read_b128 v[140:143], v140 offset:3072
	ds_read_b128 v[162:165], v182
	ds_read_b128 v[174:177], v182 offset:1024
	ds_read_b128 v[178:181], v182 offset:2048
	ds_read_b128 v[182:185], v182 offset:3072
	s_add_u32 s26, s36, 0xb0000
	s_addc_u32 s27, s37, 0
	s_mov_b32 m0, s34
	v_lshl_add_u64 v[228:229], s[26:27], 0, v[146:147]
	ds_read_b128 v[186:189], v173 offset:32768
	ds_read_b128 v[194:197], v173 offset:33792
	ds_read_b128 v[198:201], v173 offset:34816
	ds_read_b128 v[202:205], v173 offset:35840
	ds_read_b128 v[206:209], v173 offset:36864
	ds_read_b128 v[210:213], v173 offset:37888
	ds_read_b128 v[214:217], v173 offset:38912
	ds_read_b128 v[218:221], v173 offset:39936
	global_load_lds_dwordx4 v[228:229], off
	v_lshl_add_u64 v[228:229], s[26:27], 0, v[150:151]
	s_mov_b32 m0, s35
	s_nop 0
	global_load_lds_dwordx4 v[228:229], off
	s_waitcnt vmcnt(8)
	s_waitcnt lgkmcnt(0)
	s_barrier
	s_waitcnt lgkmcnt(0)
	v_mfma_f32_16x16x32_bf16 v[124:127], v[128:131], v[186:189], v[124:127]
	v_mfma_f32_16x16x32_bf16 v[120:123], v[136:139], v[186:189], v[120:123]
	v_mfma_f32_16x16x32_bf16 v[112:115], v[128:131], v[198:201], v[112:115]
	v_mfma_f32_16x16x32_bf16 v[104:107], v[136:139], v[198:201], v[104:107]
	v_mfma_f32_16x16x32_bf16 v[96:99], v[128:131], v[206:209], v[96:99]
	v_mfma_f32_16x16x32_bf16 v[88:91], v[136:139], v[206:209], v[88:91]
	v_mfma_f32_16x16x32_bf16 v[80:83], v[128:131], v[214:217], v[80:83]
	v_mfma_f32_16x16x32_bf16 v[72:75], v[136:139], v[214:217], v[72:75]
	v_mfma_f32_16x16x32_bf16 v[124:127], v[132:135], v[194:197], v[124:127]
	v_mfma_f32_16x16x32_bf16 v[120:123], v[140:143], v[194:197], v[120:123]
	v_mfma_f32_16x16x32_bf16 v[112:115], v[132:135], v[202:205], v[112:115]
	v_mfma_f32_16x16x32_bf16 v[104:107], v[140:143], v[202:205], v[104:107]
	v_mfma_f32_16x16x32_bf16 v[96:99], v[132:135], v[210:213], v[96:99]
	v_mfma_f32_16x16x32_bf16 v[88:91], v[140:143], v[210:213], v[88:91]
	v_mfma_f32_16x16x32_bf16 v[80:83], v[132:135], v[218:221], v[80:83]
	v_mfma_f32_16x16x32_bf16 v[72:75], v[140:143], v[218:221], v[72:75]
	v_mfma_f32_16x16x32_bf16 v[116:119], v[162:165], v[186:189], v[116:119]
	v_mfma_f32_16x16x32_bf16 v[108:111], v[178:181], v[186:189], v[108:111]
	v_mfma_f32_16x16x32_bf16 v[100:103], v[162:165], v[198:201], v[100:103]
	v_mfma_f32_16x16x32_bf16 v[92:95], v[178:181], v[198:201], v[92:95]
	v_mfma_f32_16x16x32_bf16 v[84:87], v[162:165], v[206:209], v[84:87]
	v_mfma_f32_16x16x32_bf16 v[76:79], v[178:181], v[206:209], v[76:79]
	v_mfma_f32_16x16x32_bf16 v[68:71], v[162:165], v[214:217], v[68:71]
	v_mfma_f32_16x16x32_bf16 v[64:67], v[178:181], v[214:217], v[64:67]
	v_mfma_f32_16x16x32_bf16 v[116:119], v[174:177], v[194:197], v[116:119]
	v_mfma_f32_16x16x32_bf16 v[108:111], v[182:185], v[194:197], v[108:111]
	v_mfma_f32_16x16x32_bf16 v[100:103], v[174:177], v[202:205], v[100:103]
	v_mfma_f32_16x16x32_bf16 v[92:95], v[182:185], v[202:205], v[92:95]
	v_mfma_f32_16x16x32_bf16 v[84:87], v[174:177], v[210:213], v[84:87]
	v_mfma_f32_16x16x32_bf16 v[76:79], v[182:185], v[210:213], v[76:79]
	v_mfma_f32_16x16x32_bf16 v[68:71], v[174:177], v[218:221], v[68:71]
	v_mfma_f32_16x16x32_bf16 v[64:67], v[182:185], v[218:221], v[64:67]
	s_barrier
	s_add_i32 s26, s54, s3
	v_lshl_add_u64 v[166:167], v[166:167], 0, s[10:11]
	s_mov_b32 m0, s26
	ds_read_b128 v[186:189], v173 offset:49152
	ds_read_b128 v[194:197], v173 offset:50176
	ds_read_b128 v[198:201], v173 offset:51200
	ds_read_b128 v[202:205], v173 offset:52224
	ds_read_b128 v[206:209], v173 offset:53248
	ds_read_b128 v[210:213], v173 offset:54272
	ds_read_b128 v[214:217], v173 offset:55296
	ds_read_b128 v[218:221], v173 offset:56320
	global_load_lds_dwordx4 v[166:167], off
	s_add_i32 m0, s26, 0x2000
	s_add_u32 s26, s30, 0xb0080
	v_lshl_add_u64 v[166:167], v[190:191], 0, s[10:11]
	s_addc_u32 s27, s31, 0
	s_add_i32 s30, s55, s3
	global_load_lds_dwordx4 v[166:167], off
	v_lshl_add_u64 v[166:167], s[26:27], 0, v[148:149]
	s_mov_b32 m0, s30
	s_nop 0
	global_load_lds_dwordx4 v[166:167], off
	v_lshl_add_u64 v[166:167], s[26:27], 0, v[152:153]
	s_add_i32 m0, s30, 0x2000
	s_nop 0
	global_load_lds_dwordx4 v[166:167], off
	v_lshl_add_u64 v[166:167], v[222:223], 0, s[10:11]
	s_mov_b32 m0, s41
	s_nop 0
	global_load_lds_dwordx4 v[166:167], off
	v_lshl_add_u64 v[166:167], v[224:225], 0, s[10:11]
	s_mov_b32 m0, s42
	s_nop 0
	global_load_lds_dwordx4 v[166:167], off
	s_waitcnt vmcnt(8)
	s_waitcnt lgkmcnt(0)
	s_barrier
	s_waitcnt lgkmcnt(0)
	v_mfma_f32_16x16x32_bf16 v[60:63], v[128:131], v[186:189], v[60:63]
	v_mfma_f32_16x16x32_bf16 v[56:59], v[136:139], v[186:189], v[56:59]
	v_mfma_f32_16x16x32_bf16 v[48:51], v[128:131], v[198:201], v[48:51]
	v_mfma_f32_16x16x32_bf16 v[32:35], v[136:139], v[198:201], v[32:35]
	v_mfma_f32_16x16x32_bf16 v[16:19], v[128:131], v[206:209], v[16:19]
	v_mfma_f32_16x16x32_bf16 v[12:15], v[136:139], v[206:209], v[12:15]
	v_mfma_f32_16x16x32_bf16 v[4:7], v[128:131], v[214:217], v[4:7]
	v_mfma_f32_16x16x32_bf16 v[0:3], v[136:139], v[214:217], v[0:3]
	v_mfma_f32_16x16x32_bf16 v[60:63], v[132:135], v[194:197], v[60:63]
	v_mfma_f32_16x16x32_bf16 v[56:59], v[140:143], v[194:197], v[56:59]
	v_mfma_f32_16x16x32_bf16 v[48:51], v[132:135], v[202:205], v[48:51]
	v_mfma_f32_16x16x32_bf16 v[32:35], v[140:143], v[202:205], v[32:35]
	v_mfma_f32_16x16x32_bf16 v[16:19], v[132:135], v[210:213], v[16:19]
	v_mfma_f32_16x16x32_bf16 v[12:15], v[140:143], v[210:213], v[12:15]
	v_mfma_f32_16x16x32_bf16 v[4:7], v[132:135], v[218:221], v[4:7]
	v_mfma_f32_16x16x32_bf16 v[0:3], v[140:143], v[218:221], v[0:3]
	v_mfma_f32_16x16x32_bf16 v[52:55], v[162:165], v[186:189], v[52:55]
	v_mfma_f32_16x16x32_bf16 v[36:39], v[178:181], v[186:189], v[36:39]
	v_mfma_f32_16x16x32_bf16 v[20:23], v[162:165], v[198:201], v[20:23]
	v_mfma_f32_16x16x32_bf16 v[8:11], v[178:181], v[198:201], v[8:11]
	v_mfma_f32_16x16x32_bf16 v[44:47], v[162:165], v[206:209], v[44:47]
	v_mfma_f32_16x16x32_bf16 v[40:43], v[178:181], v[206:209], v[40:43]
	v_mfma_f32_16x16x32_bf16 v[28:31], v[162:165], v[214:217], v[28:31]
	v_mfma_f32_16x16x32_bf16 v[24:27], v[178:181], v[214:217], v[24:27]
	v_mfma_f32_16x16x32_bf16 v[52:55], v[174:177], v[194:197], v[52:55]
	v_mfma_f32_16x16x32_bf16 v[36:39], v[182:185], v[194:197], v[36:39]
	v_mfma_f32_16x16x32_bf16 v[20:23], v[174:177], v[202:205], v[20:23]
	v_mfma_f32_16x16x32_bf16 v[8:11], v[182:185], v[202:205], v[8:11]
	v_mfma_f32_16x16x32_bf16 v[44:47], v[174:177], v[210:213], v[44:47]
	v_mfma_f32_16x16x32_bf16 v[40:43], v[182:185], v[210:213], v[40:43]
	v_mfma_f32_16x16x32_bf16 v[28:31], v[174:177], v[218:221], v[28:31]
	v_mfma_f32_16x16x32_bf16 v[24:27], v[182:185], v[218:221], v[24:27]
	s_barrier
	s_add_i32 s53, s53, 2
	s_add_u32 s51, s51, 0x100
	s_addc_u32 s52, s52, 0
	s_cmp_gt_u32 s53, 41
	s_mov_b64 s[26:27], s[28:29]
	s_cbranch_scc0 .LBB0_1177
	s_and_b64 vcc, exec, s[12:13]
	s_cbranch_vccz .LBB0_1180
	s_barrier

.LBB0_1184:
	s_setprio 0
	s_waitcnt vmcnt(0)
	s_barrier
	s_and_saveexec_b64 s[0:1], s[80:81]
	s_cbranch_execz .LBB0_1236
	v_readlane_b32 s98, v248, 1
	v_readlane_b32 s99, v248, 2
	v_mov_b32_e32 v0, 0x20ff0
	ds_read2_b32 v[2:3], v0 offset1:1
	v_mov_b32_e32 v1, 1
	v_mov_b32_e32 v4, s97
	v_lshlrev_b32_e32 v4, 8, v4
	s_add_u32 s98, s98, 0x1000
	s_addc_u32 s99, s99, 0
	s_nop 2
	global_atomic_add v5, v4, v1, s[98:99] offset:1024 sc0
	s_waitcnt vmcnt(0) lgkmcnt(0)
	v_mul_u32_u24_e32 v2, 12, v2
	v_mul_u32_u24_e32 v3, 12, v3
	v_add_u32_e32 v5, 1, v5
	v_cmp_ne_u32_e32 vcc, v5, v2
	v_mov_b32_e32 v6, 0x2400
	s_cbranch_vccnz .Lxb11_poll
	buffer_wbl2 sc1
	s_waitcnt vmcnt(0)
	global_atomic_add v6, v1, s[98:99]
